# gate/up transposition items of layers 1-3 (73472 of them) moved under the grid barriers: waves 1-7 load one item before each barrier and finish it after; prologue skips them; g3-tail slot dropped
# speedup vs baseline: 1.0207x; 1.0036x over previous
; #define LAS __attribute__((address_space(3)))
; #define GAS __attribute__((address_space(1)))
; DEV int readfirstlane_i(int v) { return __builtin_amdgcn_readfirstlane(v); }
; __global__ void __launch_bounds__(NTHREADS, 2) mega_fwd(Args args) {
;     ...
;     Frame F;
;     F.in = args.in; F.out = (GAS float*)args.out; F.ws = (GAS unsigned char*)args.ws; F.lds = lds;
;     F.tid = threadIdx.x; F.lane = F.tid & 63; F.wave = readfirstlane_i(F.tid >> 6); F.G = gridDim.x; F.bid = blockIdx.x;
;     F.gw = F.bid * NWAVES + F.wave; F.NGW = F.G * NWAVES;
;     for (int u = F.tid; u < (LDS_BYTES - LDS_MISC) / 4; u += NTHREADS) ((LAS unsigned*)(lds + LDS_MISC))[u] = 0u;
;     __syncthreads();
;     XcdBarrier bar = xcd_barrier_post((unsigned*)(F.ws + WS_CTL), (volatile LAS unsigned*)(lds + LDS_MISC), F.wave);
_Z8mega_fwd4Args:
	s_mov_b32 s100, 0
	v_writelane_b32 v255, s100, 59
	v_writelane_b32 v255, s100, 60
	s_nop 0
	s_load_dwordx2 s[100:101], s[0:1], 0x68
	s_waitcnt lgkmcnt(0)
	v_writelane_b32 v255, s100, 49
	v_writelane_b32 v255, s101, 50
	s_load_dwordx2 s[100:101], s[0:1], 0x128
	s_waitcnt lgkmcnt(0)
	v_writelane_b32 v255, s100, 53
	v_writelane_b32 v255, s101, 54
	s_load_dwordx2 s[100:101], s[0:1], 0x58
	s_waitcnt lgkmcnt(0)
	v_writelane_b32 v255, s100, 55
	v_writelane_b32 v255, s101, 56
	s_load_dwordx2 s[100:101], s[0:1], 0x60
	s_waitcnt lgkmcnt(0)
	v_writelane_b32 v255, s100, 57
	v_writelane_b32 v255, s101, 58
	s_load_dword s100, s[0:1], 0x130
	s_waitcnt lgkmcnt(0)
	v_writelane_b32 v255, s100, 51
	v_writelane_b32 v255, s2, 48
	s_mov_b32 s100, 0
	v_writelane_b32 v255, s100, 52
	s_nop 0
	s_load_dwordx4 s[4:7], s[0:1], 0x120
	s_load_dwordx8 s[8:15], s[0:1], 0x100
	s_mov_b32 s24, s2
	s_movk_i32 s2, 0x80
	v_cmp_gt_u32_e32 vcc, s2, v0
	s_waitcnt lgkmcnt(0)
	v_writelane_b32 v251, s4, 0
	s_nop 1
	v_writelane_b32 v251, s5, 1
	v_writelane_b32 v251, s6, 2
	v_writelane_b32 v251, s7, 3
	v_readfirstlane_b32 s6, v0
	s_and_saveexec_b64 s[2:3], vcc
	v_lshl_add_u32 v0, v0, 2, 0
	v_add_u32_e32 v0, 0x27e00, v0
	v_mov_b32_e32 v1, 0
	ds_write_b32 v0, v1
	v_writelane_b32 v251, s8, 4
	s_nop 1
	v_writelane_b32 v251, s9, 5
	v_writelane_b32 v251, s10, 6
	v_writelane_b32 v251, s11, 7
	v_writelane_b32 v251, s12, 8
	v_writelane_b32 v251, s13, 9
	v_writelane_b32 v251, s14, 10
	v_writelane_b32 v251, s15, 11
	s_or_b64 exec, exec, s[2:3]
	s_load_dword s96, s[0:1], 0x130
	s_load_dwordx16 s[44:59], s[0:1], 0x40
	s_load_dwordx16 s[8:23], s[0:1], 0x80
	s_waitcnt lgkmcnt(0)
	s_barrier
	s_getreg_b32 s2, hwreg(HW_REG_XCC_ID, 0, 4)
	v_writelane_b32 v251, s8, 12
	s_and_b32 s2, s2, 15
	s_cmp_gt_u32 s6, 63
	v_writelane_b32 v251, s9, 13
	v_writelane_b32 v251, s10, 14
	v_writelane_b32 v251, s11, 15
	v_writelane_b32 v251, s12, 16
	v_writelane_b32 v251, s13, 17
	v_writelane_b32 v251, s14, 18
	v_writelane_b32 v251, s15, 19
	v_writelane_b32 v251, s16, 20
	v_writelane_b32 v251, s17, 21
	v_writelane_b32 v251, s18, 22
	v_writelane_b32 v251, s19, 23
	v_writelane_b32 v251, s20, 24
	v_writelane_b32 v251, s21, 25
	v_writelane_b32 v251, s22, 26
	v_writelane_b32 v251, s23, 27
	v_writelane_b32 v251, s2, 28
	v_mbcnt_lo_u32_b32 v0, -1, 0
	s_cbranch_scc1 .LBB0_7
	v_mbcnt_hi_u32_b32 v1, -1, v0
	v_cmp_eq_u32_e32 vcc, 0, v1
	s_and_saveexec_b64 s[2:3], vcc
	s_cbranch_execz .LBB0_6
	s_mov_b64 s[4:5], exec
	v_mbcnt_lo_u32_b32 v1, s4, 0
	v_mbcnt_hi_u32_b32 v1, s5, v1
	v_cmp_eq_u32_e32 vcc, 0, v1
	s_and_b64 s[8:9], exec, vcc
	s_mov_b64 exec, s[8:9]
	s_cbranch_execz .LBB0_6
	s_load_dwordx4 s[8:11], s[0:1], 0x120
	v_readlane_b32 s7, v251, 28
	s_lshl_b32 s7, s7, 8
	s_bcnt1_i32_b64 s4, s[4:5]
	v_mov_b32_e32 v1, s7
	v_mov_b32_e32 v2, s4
	s_waitcnt lgkmcnt(0)
	global_atomic_add v1, v2, s[10:11] offset:1024

; DEV void phase_prologue_a(const Frame& F0) {
;     ...
;         constexpr int GU_NB = 2 * FF / 32, GU_ITEMS = 16 * GU_NB;
;         for (int it = F.gw; it < NE * GU_ITEMS; it += F.NGW) { const int e = it / GU_ITEMS, r = it % GU_ITEMS, kb = r / GU_NB, nb = r % GU_NB; const int d0 = 32 * nb, j = d0 >> 8, w = d0 & 255;
;             const float* src = (w < 128 ? GIN(I_WGATE) : GIN(I_WUP)) + ((size_t)l * NE + e) * 1024 * FF;
;             tr_item(src, FF, 128 * j + (w & 127), 64 * kb, (bf16_t*)(F.ws + WS_WGU) + ((size_t)l * NE + e) * 2 * FF * 1024, 1024, d0, scr, F.lane); }
.LBB0_24:
	s_andn2_b64 vcc, exec, s[10:11]
	s_cbranch_vccnz .LBB0_29
	s_lshl_b64 s[20:21], s[2:3], 27
	s_mov_b32 s28, s31
	s_cmp_eq_u32 s14, 0
	s_cbranch_scc1 .Lpro_gu_all
	v_readlane_b32 s100, v255, 51
	s_cmp_lg_u32 s100, 0x100
	s_cbranch_scc1 .Lpro_gu_all
	s_cmp_eq_u32 s14, 1
	s_cbranch_scc1 .LBB0_29
	s_mov_b32 s100, 0x4d00
	s_cmp_eq_u32 s14, 2
	s_cbranch_scc0 .Lpro_gu_p3
	s_mov_b32 s100, 0x5200
.Lpro_gu_p3:
	s_add_i32 s28, s28, s100

; #define WAIT_VM(n) do {} while (0)
; #define WAIT_ALL() do {} while (0)
; #define LAUNDER_S(x) do {} while (0)
; #define LAS __attribute__((address_space(3)))
; #define WAIT_VM(n) asm volatile("s_waitcnt vmcnt(" #n ")" ::: "memory")
; #define WAIT_ALL() asm volatile("s_waitcnt vmcnt(0) lgkmcnt(0)" ::: "memory")
; #define NT_LOAD(p) __builtin_nontemporal_load(p)
; #define LAUNDER_S(x) asm volatile("" : "+s"(x))
; DEV int lane_id() { return (int)__builtin_amdgcn_mbcnt_hi(~0u, __builtin_amdgcn_mbcnt_lo(~0u, 0u)); }
; DEV void xcd_barrier(const XcdBarrier& b) {
;     WAIT_VM(0);
;     __syncthreads();
;     int bw = b.wave; LAUNDER_S(bw);
;     if (bw == 0 && lane_id() == 0) {
;         unsigned* bar = b.bar; LAUNDER_S(bar);
;         unsigned bx = b.x; LAUNDER_S(bx);
;         WAIT_ALL();
;         unsigned nloc = b.st[0], nx = b.st[1];
; DEV void tr_item(const float* W, int ldw, int col0, int k0, bf16_t* WT, int K, int row0, LAS float* scr, int lane) {
; #pragma unroll 8
;     for (int i = 0; i < 32; ++i) { const int kk = 2 * i + (lane >> 5); scr[kk * 33 + (lane & 31)] = NT_LOAD(&W[(size_t)(k0 + kk) * ldw + col0 + (lane & 31)]); }
.LBB0_71:
	s_waitcnt vmcnt(0)
	v_readlane_b32 s0, v251, 29
	s_cselect_b32 s38, 1, 0
	v_writelane_b32 v255, s38, 61
	v_readlane_b32 s38, v255, 59
	s_add_i32 s39, s38, 1
	v_writelane_b32 v255, s39, 59
	s_mov_b32 s41, 0
	v_readlane_b32 s39, v251, 29
	s_cmp_eq_u32 s39, 0
	s_cbranch_scc1 .Lbw0_none
	v_readlane_b32 s40, v255, 51
	s_cmp_lg_u32 s40, 0x100
	s_cbranch_scc1 .Lbw0_none
	v_readlane_b32 s40, v255, 48
	s_mul_i32 s40, s40, 7
	s_mul_i32 s38, s38, 0x700
	s_add_i32 s40, s40, s38
	s_add_i32 s40, s40, s39
	s_add_i32 s40, s40, -1
	s_cmp_lt_u32 s40, 0x11f00
	s_cbranch_scc0 .Lbw0_none
	s_mov_b32 s41, 1
	s_cmp_lt_u32 s40, 0x8000
	s_cbranch_scc1 .Lbw0_have
	s_mov_b32 s41, 2
	s_sub_i32 s40, s40, 0x8000
	s_cmp_lt_u32 s40, 0x5200
	s_cbranch_scc1 .Lbw0_have
	s_mov_b32 s41, 3
	s_sub_i32 s40, s40, 0x5200
.Lbw0_have:
	s_and_b32 s38, s40, 0x7ff
	s_lshr_b32 s39, s38, 7
	s_and_b32 s38, s38, 0x7f
	s_lshl_b32 s42, s39, 19
	s_lshr_b32 s43, s38, 3
	s_lshl_b32 s43, s43, 9
	s_add_i32 s42, s42, s43
	s_and_b32 s43, s38, 3
	s_lshl_b32 s43, s43, 7
	s_add_i32 s42, s42, s43
	s_lshr_b32 s39, s40, 11
	s_lshl_b32 s39, s39, 23
	s_add_i32 s42, s42, s39
	s_lshl_b32 s39, s41, 27
	s_add_u32 s42, s42, s39
	v_readlane_b32 s100, v255, 55
	v_readlane_b32 s101, v255, 56
	s_bitcmp0_b32 s38, 2
	s_cbranch_scc1 .Lbw0_gate
	v_readlane_b32 s100, v255, 57
	v_readlane_b32 s101, v255, 58
.Lbw0_gate:
	s_add_u32 s42, s100, s42
	s_addc_u32 s43, s101, 0
	s_lshl_b32 s39, s41, 16
	s_or_b32 s41, s39, s40
	v_lshrrev_b32_e32 v173, 5, v200
	v_and_b32_e32 v174, 31, v200
	v_lshlrev_b32_e32 v174, 2, v174
	v_lshl_add_u32 v80, v173, 13, v174
	v_mov_b32_e32 v81, 0
	s_mov_b64 s[100:101], 0x4000
	v_lshl_add_u64 v[64:65], s[42:43], 0, v[80:81]
	v_lshl_add_u64 v[66:67], v[64:65], 0, s[100:101]
	v_lshl_add_u64 v[68:69], v[66:67], 0, s[100:101]
	v_lshl_add_u64 v[70:71], v[68:69], 0, s[100:101]
	v_lshl_add_u64 v[72:73], v[70:71], 0, s[100:101]
	v_lshl_add_u64 v[74:75], v[72:73], 0, s[100:101]
	v_lshl_add_u64 v[76:77], v[74:75], 0, s[100:101]
	v_lshl_add_u64 v[78:79], v[76:77], 0, s[100:101]
	s_mov_b64 s[100:101], 0x20000
	global_load_dword v82, v[64:65], off nt
	global_load_dword v83, v[66:67], off nt
	global_load_dword v84, v[68:69], off nt
	global_load_dword v85, v[70:71], off nt
	global_load_dword v86, v[72:73], off nt
	global_load_dword v87, v[74:75], off nt
	global_load_dword v88, v[76:77], off nt
	global_load_dword v89, v[78:79], off nt
	v_lshl_add_u64 v[64:65], v[64:65], 0, s[100:101]
	v_lshl_add_u64 v[66:67], v[66:67], 0, s[100:101]
	v_lshl_add_u64 v[68:69], v[68:69], 0, s[100:101]
	v_lshl_add_u64 v[70:71], v[70:71], 0, s[100:101]
	v_lshl_add_u64 v[72:73], v[72:73], 0, s[100:101]
	v_lshl_add_u64 v[74:75], v[74:75], 0, s[100:101]
	v_lshl_add_u64 v[76:77], v[76:77], 0, s[100:101]
	v_lshl_add_u64 v[78:79], v[78:79], 0, s[100:101]
	global_load_dword v90, v[64:65], off nt
	global_load_dword v91, v[66:67], off nt
	global_load_dword v92, v[68:69], off nt
	global_load_dword v93, v[70:71], off nt
	global_load_dword v94, v[72:73], off nt
	global_load_dword v95, v[74:75], off nt
	global_load_dword v96, v[76:77], off nt
	global_load_dword v97, v[78:79], off nt
	v_lshl_add_u64 v[64:65], v[64:65], 0, s[100:101]
	v_lshl_add_u64 v[66:67], v[66:67], 0, s[100:101]
	v_lshl_add_u64 v[68:69], v[68:69], 0, s[100:101]
	v_lshl_add_u64 v[70:71], v[70:71], 0, s[100:101]
	v_lshl_add_u64 v[72:73], v[72:73], 0, s[100:101]
	v_lshl_add_u64 v[74:75], v[74:75], 0, s[100:101]
	v_lshl_add_u64 v[76:77], v[76:77], 0, s[100:101]
	v_lshl_add_u64 v[78:79], v[78:79], 0, s[100:101]
	global_load_dword v98, v[64:65], off nt
	global_load_dword v99, v[66:67], off nt
	global_load_dword v100, v[68:69], off nt
	global_load_dword v101, v[70:71], off nt
	global_load_dword v102, v[72:73], off nt
	global_load_dword v103, v[74:75], off nt
	global_load_dword v104, v[76:77], off nt
	global_load_dword v105, v[78:79], off nt
	v_lshl_add_u64 v[64:65], v[64:65], 0, s[100:101]
	v_lshl_add_u64 v[66:67], v[66:67], 0, s[100:101]
	v_lshl_add_u64 v[68:69], v[68:69], 0, s[100:101]
	v_lshl_add_u64 v[70:71], v[70:71], 0, s[100:101]
	v_lshl_add_u64 v[72:73], v[72:73], 0, s[100:101]
	v_lshl_add_u64 v[74:75], v[74:75], 0, s[100:101]
	v_lshl_add_u64 v[76:77], v[76:77], 0, s[100:101]
	v_lshl_add_u64 v[78:79], v[78:79], 0, s[100:101]
	global_load_dword v106, v[64:65], off nt
	global_load_dword v107, v[66:67], off nt
	global_load_dword v108, v[68:69], off nt
	global_load_dword v109, v[70:71], off nt
	global_load_dword v110, v[72:73], off nt
	global_load_dword v111, v[74:75], off nt
	global_load_dword v112, v[76:77], off nt
	global_load_dword v113, v[78:79], off nt
.Lbw0_none:
	v_writelane_b32 v255, s41, 60
	s_nop 0
	v_readlane_b32 s38, v255, 61
	s_cmp_lg_u32 s38, 0
	s_barrier
	s_nop 0
	v_or_b32_e32 v0, s0, v200
	v_cmp_eq_u32_e32 vcc, 0, v0
	s_and_saveexec_b64 s[30:31], vcc
	s_cbranch_execz .LBB0_115
	v_readlane_b32 s0, v251, 0
	v_readlane_b32 s2, v251, 2
	v_readlane_b32 s3, v251, 3
	s_mov_b64 s[34:35], s[2:3]
	v_readlane_b32 s33, v251, 28
	s_add_i32 s0, 0, 0x27e00
	s_waitcnt vmcnt(0) lgkmcnt(0)
	v_mov_b32_e32 v0, s0
	ds_read_b32 v2, v0
	s_add_i32 s0, 0, 0x27e04
	v_mov_b32_e32 v0, s0
	ds_read_b32 v0, v0
	v_readlane_b32 s1, v251, 1
	s_waitcnt lgkmcnt(1)
	v_cmp_ne_u32_e32 vcc, 0, v2
	s_cbranch_vccnz .LBB0_86
	s_add_u32 s2, s34, 0x1000
	s_addc_u32 s3, s35, 0
	s_add_u32 s4, s34, 0x1100
	s_addc_u32 s5, s35, 0
	s_add_u32 s6, s34, 0x1200
	s_addc_u32 s7, s35, 0
	s_add_u32 s8, s34, 0x1300
	s_addc_u32 s9, s35, 0
	s_mov_b32 s18, 1
	s_mov_b64 s[0:1], 0
	s_waitcnt lgkmcnt(0)
	v_mov_b64_e32 v[0:1], s[34:35]
	v_mov_b64_e32 v[2:3], s[2:3]
	v_mov_b64_e32 v[4:5], s[4:5]
	v_mov_b64_e32 v[6:7], s[6:7]
	v_mov_b64_e32 v[8:9], s[8:9]
	s_branch .LBB0_76

; #define WAVE_LDS_SYNC() do { int _z = 0; (void)emu::wave_xchg(&_z, 4); } while (0)
; #define LAS __attribute__((address_space(3)))
; #define WAVE_LDS_SYNC() asm volatile("s_waitcnt lgkmcnt(0)" ::: "memory")
; #define NT_LOAD(p) __builtin_nontemporal_load(p)
; #define NT_STORE(v, p) __builtin_nontemporal_store((v), (p))
; DEV unsigned pk2(float lo, float hi) { return f2bf(lo) | (f2bf(hi) << 16); }
; DEV unsigned pk2(float lo, float hi) { const f32x2n_t v = {lo, hi}; return __builtin_bit_cast(unsigned, __builtin_convertvector(v, bf16x2n_t)); }
; DEV void tr_item(const float* W, int ldw, int col0, int k0, bf16_t* WT, int K, int row0, LAS float* scr, int lane) {
; #pragma unroll 8
;     for (int i = 0; i < 32; ++i) { const int kk = 2 * i + (lane >> 5); scr[kk * 33 + (lane & 31)] = NT_LOAD(&W[(size_t)(k0 + kk) * ldw + col0 + (lane & 31)]); }
;     WAVE_LDS_SYNC();
;     const int c = lane & 7;
; #pragma unroll
;     for (int j = 0; j < 4; ++j) { const int n = (lane >> 3) + 8 * j; const LAS float* s = scr + (8 * c) * 33 + n;
;         u32x4 o; o.x = pk2(s[0 * 33], s[1 * 33]); o.y = pk2(s[2 * 33], s[3 * 33]); o.z = pk2(s[4 * 33], s[5 * 33]); o.w = pk2(s[6 * 33], s[7 * 33]);
;         NT_STORE(o, (u32x4*)(WT + (size_t)(row0 + n) * K + k0 + 8 * c)); }
;     WAVE_LDS_SYNC();
.LBB0_115:
	s_or_b64 exec, exec, s[30:31]
	s_lshl_b32 s82, s96, 5
	s_abs_i32 s4, s82
	v_cvt_f32_u32_e32 v0, s4
	v_readlane_b32 s0, v251, 0
	v_readlane_b32 s1, v251, 1
	v_readlane_b32 s2, v251, 2
	v_rcp_iflag_f32_e32 v0, v0
	v_readlane_b32 s3, v251, 3
	s_mov_b64 s[0:1], s[2:3]
	s_sub_i32 s2, 0, s4
	v_mul_f32_e32 v0, 0x4f7ffffe, v0
	v_cvt_u32_f32_e32 v0, v0
	v_readlane_b32 s10, v251, 29
	s_waitcnt lgkmcnt(0)
	s_barrier
	s_cselect_b32 s38, 1, 0
	v_writelane_b32 v255, s38, 61
	s_nop 0
	v_readlane_b32 s40, v255, 60
	s_cmp_eq_u32 s40, 0
	s_cbranch_scc1 .Lbw0_skip
	s_lshr_b32 s41, s40, 16
	s_and_b32 s40, s40, 0xffff
	s_and_b32 s38, s40, 0x7ff
	s_lshr_b32 s39, s38, 7
	s_and_b32 s38, s38, 0x7f
	s_lshl_b32 s42, s38, 16
	s_lshl_b32 s39, s39, 7
	s_add_i32 s42, s42, s39
	s_lshr_b32 s39, s40, 11
	s_lshl_b32 s39, s39, 23
	s_add_i32 s42, s42, s39
	s_lshl_b32 s39, s41, 27
	s_add_u32 s42, s42, s39
	s_add_u32 s42, s42, 0x2bc8000
	v_readlane_b32 s100, v255, 53
	v_readlane_b32 s101, v255, 54
	s_add_u32 s42, s100, s42
	s_addc_u32 s43, s101, 0
	v_readlane_b32 s39, v251, 29
	s_lshl_b32 s39, s39, 14
	v_and_b32_e32 v173, 31, v200
	v_lshrrev_b32_e32 v174, 5, v200
	v_mul_u32_u24_e32 v174, 33, v174
	v_add_u32_e32 v174, v174, v173
	v_lshl_add_u32 v147, v174, 2, s39
	v_add_u32_e32 v148, 0x400, v147
	v_add_u32_e32 v166, 0x840, v147
	v_add_u32_e32 v167, 0xc40, v147
	v_add_u32_e32 v168, 0x1080, v147
	v_add_u32_e32 v169, 0x1480, v147
	v_add_u32_e32 v170, 0x18c0, v147
	v_add_u32_e32 v171, 0x1cc0, v147
	v_and_b32_e32 v173, 7, v200
	v_lshrrev_b32_e32 v174, 3, v200
	v_mul_u32_u24_e32 v175, 0x108, v173
	v_add_u32_e32 v175, v175, v174
	v_lshl_add_u32 v172, v175, 2, s39
	v_lshlrev_b32_e32 v173, 4, v173
	v_lshl_add_u32 v80, v174, 11, v173
	v_mov_b32_e32 v81, 0
	s_mov_b64 s[100:101], 0x4000
	v_lshl_add_u64 v[64:65], s[42:43], 0, v[80:81]
	v_lshl_add_u64 v[66:67], v[64:65], 0, s[100:101]
	v_lshl_add_u64 v[68:69], v[66:67], 0, s[100:101]
	v_lshl_add_u64 v[70:71], v[68:69], 0, s[100:101]
	s_waitcnt vmcnt(0)
	ds_write2_b32 v147, v82, v83 offset1:66
	ds_write2_b32 v147, v84, v85 offset0:132 offset1:198
	ds_write2_b32 v148, v86, v87 offset0:8 offset1:74
	ds_write2_b32 v148, v88, v89 offset0:140 offset1:206
	ds_write2_b32 v166, v90, v91 offset1:66
	ds_write2_b32 v166, v92, v93 offset0:132 offset1:198
	ds_write2_b32 v167, v94, v95 offset0:8 offset1:74
	ds_write2_b32 v167, v96, v97 offset0:140 offset1:206
	ds_write2_b32 v168, v98, v99 offset1:66
	ds_write2_b32 v168, v100, v101 offset0:132 offset1:198
	ds_write2_b32 v169, v102, v103 offset0:8 offset1:74
	ds_write2_b32 v169, v104, v105 offset0:140 offset1:206
	ds_write2_b32 v170, v106, v107 offset1:66
	ds_write2_b32 v170, v108, v109 offset0:132 offset1:198
	ds_write2_b32 v171, v110, v111 offset0:8 offset1:74
	ds_write2_b32 v171, v112, v113 offset0:140 offset1:206
	ds_read2_b32 v[114:115], v172 offset1:8
	ds_read2_b32 v[116:117], v172 offset0:33 offset1:41
	ds_read2_b32 v[118:119], v172 offset0:66 offset1:74
	ds_read2_b32 v[120:121], v172 offset0:99 offset1:107
	ds_read2_b32 v[122:123], v172 offset0:132 offset1:140
	ds_read2_b32 v[124:125], v172 offset0:165 offset1:173
	ds_read2_b32 v[126:127], v172 offset0:198 offset1:206
	ds_read2_b32 v[128:129], v172 offset0:231 offset1:239
	ds_read2_b32 v[130:131], v172 offset0:16 offset1:24
	ds_read2_b32 v[132:133], v172 offset0:49 offset1:57
	ds_read2_b32 v[134:135], v172 offset0:82 offset1:90
	ds_read2_b32 v[136:137], v172 offset0:115 offset1:123
	s_waitcnt lgkmcnt(4)
	v_cvt_pk_bf16_f32 v150, v114, v116
	v_cvt_pk_bf16_f32 v151, v118, v120
	v_cvt_pk_bf16_f32 v152, v122, v124
	v_cvt_pk_bf16_f32 v153, v126, v128
	v_cvt_pk_bf16_f32 v154, v115, v117
	v_cvt_pk_bf16_f32 v155, v119, v121
	v_cvt_pk_bf16_f32 v156, v123, v125
	v_cvt_pk_bf16_f32 v157, v127, v129
	ds_read2_b32 v[138:139], v172 offset0:148 offset1:156
	ds_read2_b32 v[140:141], v172 offset0:181 offset1:189
	ds_read2_b32 v[142:143], v172 offset0:214 offset1:222
	ds_read2_b32 v[144:145], v172 offset0:247 offset1:255
	global_store_dwordx4 v[64:65], v[150:153], off nt
	global_store_dwordx4 v[66:67], v[154:157], off nt
	s_waitcnt lgkmcnt(0)
	v_cvt_pk_bf16_f32 v158, v130, v132
	v_cvt_pk_bf16_f32 v159, v134, v136
	v_cvt_pk_bf16_f32 v160, v138, v140
	v_cvt_pk_bf16_f32 v161, v142, v144
	v_cvt_pk_bf16_f32 v162, v131, v133
	v_cvt_pk_bf16_f32 v163, v135, v137
	v_cvt_pk_bf16_f32 v164, v139, v141
	v_cvt_pk_bf16_f32 v165, v143, v145
	global_store_dwordx4 v[68:69], v[158:161], off nt
	global_store_dwordx4 v[70:71], v[162:165], off nt
.Lbw0_skip:
	s_waitcnt lgkmcnt(0)
	s_barrier
	v_readlane_b32 s38, v255, 61
	s_cmp_lg_u32 s38, 0
	v_readfirstlane_b32 s3, v0
	s_mul_i32 s2, s2, s3
	s_mul_hi_u32 s2, s3, s2
	s_add_i32 s2, s3, s2
	v_writelane_b32 v252, s2, 2
	s_mul_hi_u32 s2, s2, 0x4400
	s_mul_i32 s2, s2, s4
	s_sub_i32 s2, 0x4400, s2
	s_sub_i32 s3, s2, s4
	s_cmp_ge_u32 s2, s4
	s_cselect_b32 s2, s3, s2
	s_sub_i32 s3, s2, s4
	s_cmp_ge_u32 s2, s4
	s_cselect_b32 s2, s3, s2
	v_writelane_b32 v252, s4, 3
	s_sub_i32 s3, 0x4400, s2
	s_lshl_b32 s4, s95, 5
	s_lshl_b32 s2, s10, 2
	v_mov_b32_e32 v64, v200
	v_writelane_b32 v252, s4, 4
	s_add_i32 s2, s2, s4
	v_writelane_b32 v252, s3, 5
	s_cmp_ge_i32 s2, s3
	v_ashrrev_i32_e32 v65, 31, v64
	s_cbranch_scc1 .LBB0_120
	s_add_u32 s11, s0, 0x10000
	s_addc_u32 s12, s1, 0
	s_ashr_i32 s3, s2, 31
	s_add_u32 s13, s2, 3
	s_addc_u32 s14, s3, 0
	s_ashr_i32 s83, s82, 31
	s_lshl_b64 s[4:5], s[2:3], 11
	s_add_u32 s4, s0, s4
	s_addc_u32 s5, s1, s5
	v_lshl_add_u64 v[0:1], v[64:65], 3, s[4:5]
	s_mov_b64 s[4:5], 0x37099e00
	v_lshl_add_u64 v[66:67], v[0:1], 0, s[4:5]
	s_lshl_b64 s[4:5], s[82:83], 11
	v_lshlrev_b64 v[68:69], 4, v[64:65]
	s_mov_b64 s[6:7], 0x1000
	s_movk_i32 s3, 0xf000
	s_branch .LBB0_118

; #define WAIT_VM(n) do {} while (0)
; #define WAIT_ALL() do {} while (0)
; #define LAUNDER_S(x) do {} while (0)
; #define LAS __attribute__((address_space(3)))
; #define WAIT_VM(n) asm volatile("s_waitcnt vmcnt(" #n ")" ::: "memory")
; #define WAIT_ALL() asm volatile("s_waitcnt vmcnt(0) lgkmcnt(0)" ::: "memory")
; #define NT_LOAD(p) __builtin_nontemporal_load(p)
; #define LAUNDER_S(x) asm volatile("" : "+s"(x))
; DEV int lane_id() { return (int)__builtin_amdgcn_mbcnt_hi(~0u, __builtin_amdgcn_mbcnt_lo(~0u, 0u)); }
; DEV void xcd_barrier(const XcdBarrier& b) {
;     WAIT_VM(0);
;     __syncthreads();
;     int bw = b.wave; LAUNDER_S(bw);
;     if (bw == 0 && lane_id() == 0) {
;         unsigned* bar = b.bar; LAUNDER_S(bar);
;         unsigned bx = b.x; LAUNDER_S(bx);
;         WAIT_ALL();
;         unsigned nloc = b.st[0], nx = b.st[1];
;         if (nloc == 0u) { xcd_barrier_complete(bar, bx, nloc, nx); b.st[0] = nloc; b.st[1] = nx; }
; DEV void tr_item(const float* W, int ldw, int col0, int k0, bf16_t* WT, int K, int row0, LAS float* scr, int lane) {
; #pragma unroll 8
;     for (int i = 0; i < 32; ++i) { const int kk = 2 * i + (lane >> 5); scr[kk * 33 + (lane & 31)] = NT_LOAD(&W[(size_t)(k0 + kk) * ldw + col0 + (lane & 31)]); }
.Lbw1_gate:
	s_add_u32 s42, s100, s42
	s_addc_u32 s43, s101, 0
	s_lshl_b32 s39, s41, 16
	s_or_b32 s41, s39, s40
	v_lshrrev_b32_e32 v134, 5, v200
	v_and_b32_e32 v135, 31, v200
	v_lshlrev_b32_e32 v135, 2, v135
	v_lshl_add_u32 v44, v134, 13, v135
	v_mov_b32_e32 v45, 0
	s_mov_b64 s[100:101], 0x4000
	v_lshl_add_u64 v[28:29], s[42:43], 0, v[44:45]
	v_lshl_add_u64 v[30:31], v[28:29], 0, s[100:101]
	v_lshl_add_u64 v[32:33], v[30:31], 0, s[100:101]
	v_lshl_add_u64 v[34:35], v[32:33], 0, s[100:101]
	v_lshl_add_u64 v[36:37], v[34:35], 0, s[100:101]
	v_lshl_add_u64 v[38:39], v[36:37], 0, s[100:101]
	v_lshl_add_u64 v[40:41], v[38:39], 0, s[100:101]
	v_lshl_add_u64 v[42:43], v[40:41], 0, s[100:101]
	s_mov_b64 s[100:101], 0x20000
	global_load_dword v27, v[28:29], off nt
	global_load_dword v46, v[30:31], off nt
	global_load_dword v47, v[32:33], off nt
	global_load_dword v48, v[34:35], off nt
	global_load_dword v49, v[36:37], off nt
	global_load_dword v50, v[38:39], off nt
	global_load_dword v51, v[40:41], off nt
	global_load_dword v52, v[42:43], off nt
	v_lshl_add_u64 v[28:29], v[28:29], 0, s[100:101]
	v_lshl_add_u64 v[30:31], v[30:31], 0, s[100:101]
	v_lshl_add_u64 v[32:33], v[32:33], 0, s[100:101]
	v_lshl_add_u64 v[34:35], v[34:35], 0, s[100:101]
	v_lshl_add_u64 v[36:37], v[36:37], 0, s[100:101]
	v_lshl_add_u64 v[38:39], v[38:39], 0, s[100:101]
	v_lshl_add_u64 v[40:41], v[40:41], 0, s[100:101]
	v_lshl_add_u64 v[42:43], v[42:43], 0, s[100:101]
	global_load_dword v53, v[28:29], off nt
	global_load_dword v54, v[30:31], off nt
	global_load_dword v55, v[32:33], off nt
	global_load_dword v56, v[34:35], off nt
	global_load_dword v57, v[36:37], off nt
	global_load_dword v58, v[38:39], off nt
	global_load_dword v59, v[40:41], off nt
	global_load_dword v60, v[42:43], off nt
	v_lshl_add_u64 v[28:29], v[28:29], 0, s[100:101]
	v_lshl_add_u64 v[30:31], v[30:31], 0, s[100:101]
	v_lshl_add_u64 v[32:33], v[32:33], 0, s[100:101]
	v_lshl_add_u64 v[34:35], v[34:35], 0, s[100:101]
	v_lshl_add_u64 v[36:37], v[36:37], 0, s[100:101]
	v_lshl_add_u64 v[38:39], v[38:39], 0, s[100:101]
	v_lshl_add_u64 v[40:41], v[40:41], 0, s[100:101]
	v_lshl_add_u64 v[42:43], v[42:43], 0, s[100:101]
	global_load_dword v61, v[28:29], off nt
	global_load_dword v62, v[30:31], off nt
	global_load_dword v63, v[32:33], off nt
	global_load_dword v64, v[34:35], off nt
	global_load_dword v65, v[36:37], off nt
	global_load_dword v66, v[38:39], off nt
	global_load_dword v67, v[40:41], off nt
	global_load_dword v68, v[42:43], off nt
	v_lshl_add_u64 v[28:29], v[28:29], 0, s[100:101]
	v_lshl_add_u64 v[30:31], v[30:31], 0, s[100:101]
	v_lshl_add_u64 v[32:33], v[32:33], 0, s[100:101]
	v_lshl_add_u64 v[34:35], v[34:35], 0, s[100:101]
	v_lshl_add_u64 v[36:37], v[36:37], 0, s[100:101]
	v_lshl_add_u64 v[38:39], v[38:39], 0, s[100:101]
	v_lshl_add_u64 v[40:41], v[40:41], 0, s[100:101]
	v_lshl_add_u64 v[42:43], v[42:43], 0, s[100:101]
	global_load_dword v69, v[28:29], off nt
	global_load_dword v70, v[30:31], off nt
	global_load_dword v71, v[32:33], off nt
	global_load_dword v72, v[34:35], off nt
	global_load_dword v73, v[36:37], off nt
	global_load_dword v74, v[38:39], off nt
	global_load_dword v75, v[40:41], off nt
	global_load_dword v76, v[42:43], off nt
.Lbw1_none:
	v_writelane_b32 v255, s41, 60
	s_nop 0
	v_readlane_b32 s38, v255, 61
	s_cmp_lg_u32 s38, 0
	s_barrier
	s_nop 0
	v_or_b32_e32 v0, s0, v200
	v_cmp_eq_u32_e32 vcc, 0, v0
	s_and_saveexec_b64 s[30:31], vcc
	s_cbranch_execz .LBB0_169
	v_readlane_b32 s0, v251, 0
	v_readlane_b32 s2, v251, 2
	v_readlane_b32 s3, v251, 3
	s_mov_b64 s[34:35], s[2:3]
	v_readlane_b32 s33, v251, 28
	s_add_i32 s0, 0, 0x27e00
	s_waitcnt vmcnt(0) lgkmcnt(0)
	v_mov_b32_e32 v0, s0
	ds_read_b32 v2, v0
	s_add_i32 s0, 0, 0x27e04
	v_mov_b32_e32 v0, s0
	ds_read_b32 v0, v0
	v_readlane_b32 s1, v251, 1
	s_waitcnt lgkmcnt(0)
	v_cmp_ne_u32_e32 vcc, 0, v2
	s_cbranch_vccnz .LBB0_140
	s_add_u32 s2, s34, 0x1000
	s_addc_u32 s3, s35, 0
	s_add_u32 s4, s34, 0x1100
	s_addc_u32 s5, s35, 0
	s_add_u32 s6, s34, 0x1200
	s_addc_u32 s7, s35, 0
	s_add_u32 s8, s34, 0x1300
	s_addc_u32 s9, s35, 0
	s_mov_b32 s18, 1
	s_mov_b64 s[0:1], 0
	v_mov_b64_e32 v[0:1], s[34:35]
	v_mov_b64_e32 v[2:3], s[2:3]
	v_mov_b64_e32 v[4:5], s[4:5]
	v_mov_b64_e32 v[6:7], s[6:7]
	v_mov_b64_e32 v[8:9], s[8:9]
	s_branch .LBB0_130

; #define GRID_BAR() xcd_barrier(bar)
; #define PT(k) do { if (TIMING_PROBE == (k)) pt_t0 = rt_now(); } while (0)
; #define PTE(k) do { if (TIMING_PROBE == (k)) pt_acc += rt_now() - pt_t0; } while (0)
; #define PH(k) if ((PHASE_MASK >> (k)) & 1)
; __global__ void __launch_bounds__(NTHREADS, 2) mega_fwd(Args args) {
;     ...
;     PT(1); PH(1) phase_xg0(F);
;     GRID_BAR(); PTE(1);
;     for (int l = 0; l < DEPTH; ++l) {
;         const int odd = l & 1;
;         PT(2); PH(2) gemm_g1(F, l, F.bid);
.LBB0_169:
	s_or_b64 exec, exec, s[30:31]
	s_ashr_i32 s81, s95, 31
	s_lshr_b32 s0, s81, 29
	s_add_i32 s0, s95, s0
	s_ashr_i32 s6, s0, 3
	s_and_b32 s0, s0, -8
	s_sub_i32 s7, s95, s0
	s_cmp_gt_i32 s7, 3
	s_cselect_b64 s[0:1], -1, 0
	v_writelane_b32 v252, s0, 6
	s_ashr_i32 s83, s96, 31
	s_movk_i32 s88, 0x1600
	v_writelane_b32 v252, s1, 7
	s_add_i32 s0, s7, -4
	v_writelane_b32 v252, s0, 8
	s_movk_i32 s84, 0x10ff
	v_readlane_b32 s0, v252, 5
	s_add_i32 s0, s0, s95
	s_cmpk_gt_i32 s95, 0xff
	v_writelane_b32 v252, s0, 9
	s_cselect_b64 s[0:1], -1, 0
	v_writelane_b32 v252, s0, 10
	v_mov_b32_e32 v1, 0
	v_mov_b32_e32 v202, 1
	v_writelane_b32 v252, s1, 11
	s_mul_hi_i32 s0, s95, 0x78787879
	s_ashr_i32 s1, s0, 6
	s_lshr_b32 s2, s0, 31
	s_ashr_i32 s0, s0, 5
	s_add_i32 s0, s0, s2
	s_and_b32 s8, s0, 1
	s_mulk_i32 s0, 0x44
	s_sub_i32 s0, s95, s0
	s_add_i32 s4, s1, s2
	s_lshl_b32 s9, s0, 6
	s_cmp_lt_i32 s0, 4
	s_cselect_b64 s[0:1], -1, 0
	s_add_i32 s2, s9, 0xffffff00
	s_sub_i32 s3, 0x10ff, s9
	s_sub_i32 s5, 0xff, s9
	v_writelane_b32 v252, s0, 12
	s_cmp_eq_u32 s8, 0
	v_mov_b32_e32 v203, 0x260
	v_writelane_b32 v252, s1, 13
	s_cselect_b64 s[0:1], -1, 0
	v_writelane_b32 v252, s0, 14
	v_mov_b32_e32 v204, 0x3ecc95a3
	v_mov_b32_e32 v205, 0x2000
	v_writelane_b32 v252, s1, 15
	s_and_b64 s[0:1], s[0:1], exec
	s_cselect_b32 s0, s2, s3
	v_writelane_b32 v252, s0, 16
	s_cselect_b32 s0, s9, s5
	v_writelane_b32 v252, s9, 17
	s_addk_i32 s0, 0x4000
	v_writelane_b32 v252, s0, 18
	s_ashr_i32 s1, s96, 3
	v_writelane_b32 v252, s8, 19
	s_lshl_b32 s0, s8, 2
	s_mul_i32 s1, s1, s7
	v_writelane_b32 v252, s0, 20
	s_and_b32 s0, s96, 7
	s_add_i32 s1, s1, s6
	s_add_i32 s2, s96, 0xffffff80
	v_writelane_b32 v252, s6, 21
	s_cmp_lt_i32 s7, 0
	v_writelane_b32 v252, s2, 22
	s_cselect_b64 s[2:3], -1, 0
	s_cmp_eq_u32 s0, 0
	v_writelane_b32 v252, s7, 23
	s_cselect_b32 s9, s1, s95
	v_writelane_b32 v252, s2, 24
	s_cmpk_gt_i32 s9, 0x7f
	s_cselect_b64 s[0:1], -1, 0
	v_writelane_b32 v252, s3, 25
	v_writelane_b32 v252, s0, 26
	s_ashr_i32 s2, s9, 2
	s_add_i32 s10, s9, 0xffffff80
	v_writelane_b32 v252, s1, 27
	s_ashr_i32 s0, s9, 3
	s_lshr_b32 s1, s0, 30
	s_add_i32 s1, s0, s1
	s_and_b32 s1, s1, 0x1fffffc
	s_sub_i32 s0, s0, s1
	s_lshr_b32 s1, s2, 29
	s_add_i32 s1, s2, s1
	s_lshl_b32 s0, s0, 7
	s_and_b32 s5, s9, 3
	s_bfe_i32 s3, s2, 0x10000
	s_and_b32 s6, s2, 1
	s_ashr_i32 s7, s1, 3
	s_ashr_i32 s1, s0, 31
	s_cmp_eq_u32 s6, 0
	s_mul_i32 s12, s2, 0x44
	s_cselect_b64 s[14:15], -1, 0
	s_lshl_b32 s2, s7, 8
	s_add_i32 s8, s2, 0x4000
	s_and_b32 s2, s3, 0xff
	v_writelane_b32 v252, s8, 28
	s_or_b32 s8, s8, s2
	s_and_b64 s[2:3], s[14:15], exec
	s_cselect_b32 s2, s88, 0xffffea00
	v_writelane_b32 v252, s2, 29
	s_mul_hi_i32 s2, s8, 0x1600
	v_writelane_b32 v252, s2, 30
	s_mul_i32 s2, s8, 0x1600
	s_cselect_b32 s11, 0, -1
	v_writelane_b32 v252, s2, 31
	s_lshl_b32 s2, s5, 6
	s_ashr_i32 s13, s12, 31
	v_writelane_b32 v252, s2, 32
	s_lshl_b64 s[2:3], s[12:13], 11
	v_writelane_b32 v252, s2, 33
	v_writelane_b32 v253, s10, 0
	v_mov_b32_e32 v206, 0x3727c5ac
	v_writelane_b32 v252, s3, 34
	s_lshl_b64 s[2:3], s[12:13], 13
	v_writelane_b32 v252, s2, 35
	v_mov_b32_e32 v207, 0x4400
	v_mov_b32_e32 v208, 0x3db504f3
	v_writelane_b32 v252, s3, 36
	s_mov_b32 s2, s12
	v_writelane_b32 v252, s2, 37
	v_mov_b32_e32 v209, 0x7f800000
	v_mov_b32_e32 v146, 0x3f317218
	v_writelane_b32 v252, s3, 38
	s_lshl_b64 s[2:3], s[12:13], 14
	v_writelane_b32 v252, s2, 39
	s_mov_b32 s13, s11
	v_mov_b32_e32 v210, 0x10ff
	v_writelane_b32 v252, s3, 40
	s_lshl_b32 s2, s7, 12
	v_writelane_b32 v252, s2, 41
	s_movk_i32 s7, 0x800
	v_writelane_b32 v252, s14, 42
	s_and_b64 s[2:3], s[14:15], exec
	s_cselect_b32 s12, s7, 0xfffff800
	s_abs_i32 s3, s54
	v_cvt_f32_u32_e32 v0, s3
	v_writelane_b32 v252, s15, 43
	v_writelane_b32 v252, s11, 44
	s_mul_i32 s2, s6, 0x4400
	v_writelane_b32 v252, s2, 45
	s_lshl_b32 s2, s5, 5
	s_or_b32 s2, s0, s2
	v_rcp_iflag_f32_e32 v0, v0
	v_writelane_b32 v252, s2, 46
	s_ashr_i32 s2, s4, 31
	v_writelane_b32 v252, s2, 47
	s_abs_i32 s2, s4
	v_writelane_b32 v252, s2, 48
	s_abs_i32 s2, s95
	v_writelane_b32 v252, s2, 49
	v_mul_f32_e32 v0, 0x4f7ffffe, v0
	s_mul_hi_i32 s5, s12, 5
	v_cvt_u32_f32_e32 v0, v0
	v_writelane_b32 v252, s12, 50
	s_mul_i32 s4, s12, 5
	s_sub_i32 s2, 0, s3
	v_writelane_b32 v252, s13, 51
	v_writelane_b32 v252, s4, 52
	s_ashr_i32 s55, s54, 31
	v_mov_b32_e32 v211, 0xff
	v_writelane_b32 v252, s5, 53
	v_writelane_b32 v252, s3, 54
	v_readfirstlane_b32 s3, v0
	s_mul_i32 s2, s2, s3
	s_mul_hi_u32 s2, s3, s2
	s_add_i32 s2, s3, s2
	v_writelane_b32 v252, s2, 55
	s_lshl_b64 s[2:3], s[54:55], 2
	v_writelane_b32 v252, s2, 56
	s_mul_i32 s4, s96, 0x8800
	v_mov_b32_e32 v201, 0x1000
	v_writelane_b32 v252, s3, 57
	s_mul_i32 s3, s95, 0x8800
	s_mul_hi_i32 s2, s95, 0x8800
	s_add_u32 s3, s3, 0x40d54c00
	v_writelane_b32 v252, s3, 58
	s_addc_u32 s2, s2, 0
	v_writelane_b32 v252, s2, 59
	s_mul_hi_i32 s2, s96, 0x8800
	v_writelane_b32 v252, s2, 60
	s_mul_i32 s3, s9, 0x8800
	s_mul_hi_i32 s2, s9, 0x8800
	v_writelane_b32 v252, s9, 61
	s_add_u32 s5, s3, 0x40d54c00
	v_writelane_b32 v252, s5, 62
	s_addc_u32 s2, s2, 0
	s_add_i32 s3, s3, 0xffbc0000
	v_writelane_b32 v252, s2, 63
	s_mul_hi_i32 s2, s10, 0x8800
	s_add_u32 s3, s3, 0x40d54c00
	v_writelane_b32 v253, s3, 1
	s_addc_u32 s2, s2, 0
	v_writelane_b32 v253, s2, 2
	v_writelane_b32 v253, s4, 3
	s_add_i32 s2, s4, 0xffbc0000
	v_writelane_b32 v253, s2, 4
	s_lshl_b64 s[0:1], s[0:1], 1
	v_writelane_b32 v253, s0, 5
	s_add_i32 s86, 0, 0x20200
	v_mov_b32_e32 v250, 0x2200
	v_writelane_b32 v253, s1, 6
	s_add_i32 s0, 0, 0x27e00
	v_writelane_b32 v253, s0, 7
	s_add_i32 s0, 0, 0x27e04
	v_writelane_b32 v253, s0, 8
	s_add_i32 s0, 0, 0x15000
; #define WAVE_LDS_SYNC() do { int _z = 0; (void)emu::wave_xchg(&_z, 4); } while (0)
; #define LAS __attribute__((address_space(3)))
; #define WAVE_LDS_SYNC() asm volatile("s_waitcnt lgkmcnt(0)" ::: "memory")
; #define NT_LOAD(p) __builtin_nontemporal_load(p)
; #define NT_STORE(v, p) __builtin_nontemporal_store((v), (p))
; DEV unsigned pk2(float lo, float hi) { return f2bf(lo) | (f2bf(hi) << 16); }
; DEV unsigned pk2(float lo, float hi) { const f32x2n_t v = {lo, hi}; return __builtin_bit_cast(unsigned, __builtin_convertvector(v, bf16x2n_t)); }
; DEV void xcd_barrier(const XcdBarrier& b) {
;     ...
;     __syncthreads();
; }
; DEV void tr_item(const float* W, int ldw, int col0, int k0, bf16_t* WT, int K, int row0, LAS float* scr, int lane) {
; #pragma unroll 8
;     for (int i = 0; i < 32; ++i) { const int kk = 2 * i + (lane >> 5); scr[kk * 33 + (lane & 31)] = NT_LOAD(&W[(size_t)(k0 + kk) * ldw + col0 + (lane & 31)]); }
;     WAVE_LDS_SYNC();
;     const int c = lane & 7;
; #pragma unroll
;     for (int j = 0; j < 4; ++j) { const int n = (lane >> 3) + 8 * j; const LAS float* s = scr + (8 * c) * 33 + n;
;         u32x4 o; o.x = pk2(s[0 * 33], s[1 * 33]); o.y = pk2(s[2 * 33], s[3 * 33]); o.z = pk2(s[4 * 33], s[5 * 33]); o.w = pk2(s[6 * 33], s[7 * 33]);
;         NT_STORE(o, (u32x4*)(WT + (size_t)(row0 + n) * K + k0 + 8 * c)); }
;     WAVE_LDS_SYNC();
	v_writelane_b32 v253, s0, 9
	s_add_i32 s0, 0, 0x24400
	v_writelane_b32 v253, s0, 10
	s_add_i32 s0, 0, 0x23200
	v_writelane_b32 v253, s0, 11
	s_add_i32 s0, 0, 0x21000
	v_writelane_b32 v253, s0, 12
	s_add_i32 s0, 0, 0x24600
	v_writelane_b32 v253, s0, 13
	s_add_i32 s0, 0, 0xe400
	v_writelane_b32 v253, s0, 14
	s_add_i32 s0, 0, 0xe800
	v_writelane_b32 v253, s0, 15
	s_add_i32 s0, 0, 0xec00
	v_writelane_b32 v253, s0, 16
	s_add_i32 s0, 0, 0x10400
	v_writelane_b32 v253, s0, 17
	s_add_i32 s0, 0, 0xc400
	v_writelane_b32 v253, s0, 18
	s_add_i32 s0, 0, 0xc800
	v_writelane_b32 v253, s0, 19
	s_add_i32 s0, 0, 0xcc00
	v_writelane_b32 v253, s0, 20
	s_add_i32 s0, 0, 0xd000
	v_writelane_b32 v253, s0, 21
	s_add_i32 s0, 0, 0xd400
	v_writelane_b32 v253, s0, 22
	s_add_i32 s0, 0, 0xdc00
	v_writelane_b32 v253, s0, 23
	s_mov_b32 s1, 0
	v_writelane_b32 v253, s95, 24
	s_mov_b32 s52, s1
	v_writelane_b32 v253, s96, 25
	v_writelane_b32 v253, s44, 26
	s_mov_b32 s0, s82
	v_mov_b32_e32 v220, 0xba800000
	v_writelane_b32 v253, s45, 27
	v_writelane_b32 v253, s46, 28
	v_writelane_b32 v253, s47, 29
	v_writelane_b32 v253, s48, 30
	v_writelane_b32 v253, s49, 31
	v_writelane_b32 v253, s50, 32
	v_writelane_b32 v253, s51, 33
	v_writelane_b32 v253, s52, 34
	v_writelane_b32 v253, s53, 35
	v_writelane_b32 v253, s54, 36
	v_writelane_b32 v253, s55, 37
	v_writelane_b32 v253, s56, 38
	v_writelane_b32 v253, s57, 39
	v_writelane_b32 v253, s58, 40
	v_writelane_b32 v253, s59, 41
	v_writelane_b32 v253, s54, 42
	v_mov_b32_e32 v221, 0x3a800000
	v_mov_b32_e32 v222, 0x900
	v_writelane_b32 v253, s55, 43
	v_writelane_b32 v253, s0, 44
	v_mov_b32_e32 v149, 0x10000
	s_mov_b32 s94, 0xf800000
	v_writelane_b32 v253, s1, 45
	v_writelane_b32 v253, s81, 46
	v_writelane_b32 v253, s83, 47
	s_mov_b32 s97, 0x3fb8aa3b
	s_mov_b32 s80, 0xc2ce8ed0
	s_mov_b32 s85, 0x42b17218
	s_movk_i32 s89, 0x1fff
	s_mov_b64 s[90:91], 0x80
	s_mov_b32 s92, 0x3fd744fd
	v_writelane_b32 v253, s86, 48
	s_waitcnt lgkmcnt(0)
	s_barrier
	s_cselect_b32 s38, 1, 0
	v_writelane_b32 v255, s38, 61
	s_nop 0
	v_readlane_b32 s40, v255, 60
	s_cmp_eq_u32 s40, 0
	s_cbranch_scc1 .Lbw1_skip
	s_lshr_b32 s41, s40, 16
	s_and_b32 s40, s40, 0xffff
	s_and_b32 s38, s40, 0x7ff
	s_lshr_b32 s39, s38, 7
	s_and_b32 s38, s38, 0x7f
	s_lshl_b32 s42, s38, 16
	s_lshl_b32 s39, s39, 7
	s_add_i32 s42, s42, s39
	s_lshr_b32 s39, s40, 11
	s_lshl_b32 s39, s39, 23
	s_add_i32 s42, s42, s39
	s_lshl_b32 s39, s41, 27
	s_add_u32 s42, s42, s39
	s_add_u32 s42, s42, 0x2bc8000
	v_readlane_b32 s100, v255, 53
	v_readlane_b32 s101, v255, 54
	s_add_u32 s42, s100, s42
	s_addc_u32 s43, s101, 0
	v_readlane_b32 s39, v251, 29
	s_lshl_b32 s39, s39, 14
	v_and_b32_e32 v134, 31, v200
	v_lshrrev_b32_e32 v135, 5, v200
	v_mul_u32_u24_e32 v135, 33, v135
	v_add_u32_e32 v135, v135, v134
	v_lshl_add_u32 v77, v135, 2, s39
	v_add_u32_e32 v126, 0x400, v77
	v_add_u32_e32 v127, 0x840, v77
	v_add_u32_e32 v128, 0xc40, v77
	v_add_u32_e32 v129, 0x1080, v77
	v_add_u32_e32 v130, 0x1480, v77
	v_add_u32_e32 v131, 0x18c0, v77
	v_add_u32_e32 v132, 0x1cc0, v77
	v_and_b32_e32 v134, 7, v200
	v_lshrrev_b32_e32 v135, 3, v200
	v_mul_u32_u24_e32 v136, 0x108, v134
	v_add_u32_e32 v136, v136, v135
	v_lshl_add_u32 v133, v136, 2, s39
	v_lshlrev_b32_e32 v134, 4, v134
	v_lshl_add_u32 v44, v135, 11, v134
	v_mov_b32_e32 v45, 0
	s_mov_b64 s[100:101], 0x4000
	v_lshl_add_u64 v[28:29], s[42:43], 0, v[44:45]
	v_lshl_add_u64 v[30:31], v[28:29], 0, s[100:101]
	v_lshl_add_u64 v[32:33], v[30:31], 0, s[100:101]
	v_lshl_add_u64 v[34:35], v[32:33], 0, s[100:101]
	s_waitcnt vmcnt(0)
	ds_write2_b32 v77, v27, v46 offset1:66
	ds_write2_b32 v77, v47, v48 offset0:132 offset1:198
	ds_write2_b32 v126, v49, v50 offset0:8 offset1:74
	ds_write2_b32 v126, v51, v52 offset0:140 offset1:206
	ds_write2_b32 v127, v53, v54 offset1:66
	ds_write2_b32 v127, v55, v56 offset0:132 offset1:198
	ds_write2_b32 v128, v57, v58 offset0:8 offset1:74
	ds_write2_b32 v128, v59, v60 offset0:140 offset1:206
	ds_write2_b32 v129, v61, v62 offset1:66
	ds_write2_b32 v129, v63, v64 offset0:132 offset1:198
	ds_write2_b32 v130, v65, v66 offset0:8 offset1:74
	ds_write2_b32 v130, v67, v68 offset0:140 offset1:206
	ds_write2_b32 v131, v69, v70 offset1:66
	ds_write2_b32 v131, v71, v72 offset0:132 offset1:198
	ds_write2_b32 v132, v73, v74 offset0:8 offset1:74
	ds_write2_b32 v132, v75, v76 offset0:140 offset1:206
	ds_read2_b32 v[78:79], v133 offset1:8
	ds_read2_b32 v[80:81], v133 offset0:33 offset1:41
	ds_read2_b32 v[82:83], v133 offset0:66 offset1:74
	ds_read2_b32 v[84:85], v133 offset0:99 offset1:107
	ds_read2_b32 v[86:87], v133 offset0:132 offset1:140
	ds_read2_b32 v[88:89], v133 offset0:165 offset1:173
	ds_read2_b32 v[90:91], v133 offset0:198 offset1:206
	ds_read2_b32 v[92:93], v133 offset0:231 offset1:239
	ds_read2_b32 v[94:95], v133 offset0:16 offset1:24
	ds_read2_b32 v[96:97], v133 offset0:49 offset1:57
	ds_read2_b32 v[98:99], v133 offset0:82 offset1:90
	ds_read2_b32 v[100:101], v133 offset0:115 offset1:123
	s_waitcnt lgkmcnt(4)
	v_cvt_pk_bf16_f32 v110, v78, v80
	v_cvt_pk_bf16_f32 v111, v82, v84
	v_cvt_pk_bf16_f32 v112, v86, v88
	v_cvt_pk_bf16_f32 v113, v90, v92
	v_cvt_pk_bf16_f32 v114, v79, v81
	v_cvt_pk_bf16_f32 v115, v83, v85
	v_cvt_pk_bf16_f32 v116, v87, v89
	v_cvt_pk_bf16_f32 v117, v91, v93
	ds_read2_b32 v[102:103], v133 offset0:148 offset1:156
	ds_read2_b32 v[104:105], v133 offset0:181 offset1:189
	ds_read2_b32 v[106:107], v133 offset0:214 offset1:222
	ds_read2_b32 v[108:109], v133 offset0:247 offset1:255
	global_store_dwordx4 v[28:29], v[110:113], off nt
	global_store_dwordx4 v[30:31], v[114:117], off nt
	s_waitcnt lgkmcnt(0)
	v_cvt_pk_bf16_f32 v118, v94, v96
	v_cvt_pk_bf16_f32 v119, v98, v100
	v_cvt_pk_bf16_f32 v120, v102, v104
	v_cvt_pk_bf16_f32 v121, v106, v108
	v_cvt_pk_bf16_f32 v122, v95, v97
	v_cvt_pk_bf16_f32 v123, v99, v101
	v_cvt_pk_bf16_f32 v124, v103, v105
	v_cvt_pk_bf16_f32 v125, v107, v109
	global_store_dwordx4 v[32:33], v[118:121], off nt
	global_store_dwordx4 v[34:35], v[122:125], off nt
.Lbw1_skip:
	s_waitcnt lgkmcnt(0)
	s_barrier
	v_readlane_b32 s38, v255, 61
	s_cmp_lg_u32 s38, 0
	s_branch .LBB0_173

; #define WAIT_VM(n) do {} while (0)
; #define WAIT_ALL() do {} while (0)
; #define LAUNDER_S(x) do {} while (0)
; #define WAIT_VM(n) asm volatile("s_waitcnt vmcnt(" #n ")" ::: "memory")
; #define WAIT_ALL() asm volatile("s_waitcnt vmcnt(0) lgkmcnt(0)" ::: "memory")
; #define LAUNDER_S(x) asm volatile("" : "+s"(x))
; DEV int lane_id() { return (int)__builtin_amdgcn_mbcnt_hi(~0u, __builtin_amdgcn_mbcnt_lo(~0u, 0u)); }
; DEV void xcd_barrier(const XcdBarrier& b) {
;     WAIT_VM(0);
;     __syncthreads();
;     int bw = b.wave; LAUNDER_S(bw);
;     if (bw == 0 && lane_id() == 0) {
;         unsigned* bar = b.bar; LAUNDER_S(bar);
;         unsigned bx = b.x; LAUNDER_S(bx);
;         WAIT_ALL();
;         unsigned nloc = b.st[0], nx = b.st[1];
.LBB0_197:
	s_waitcnt vmcnt(0)
	v_readlane_b32 s0, v251, 29
	s_waitcnt vmcnt(0)
	s_cselect_b32 s38, 1, 0
	v_writelane_b32 v255, s38, 61
	v_readlane_b32 s38, v255, 59
	s_add_i32 s39, s38, 1
	v_writelane_b32 v255, s39, 59
	s_mov_b32 s41, 0
	v_readlane_b32 s39, v251, 29
	s_cmp_eq_u32 s39, 0
	s_cbranch_scc1 .Lbw2_none
	v_readlane_b32 s40, v255, 51
	s_cmp_lg_u32 s40, 0x100
	s_cbranch_scc1 .Lbw2_none
	v_readlane_b32 s40, v255, 48
	s_mul_i32 s40, s40, 7
	s_mul_i32 s38, s38, 0x700
	s_add_i32 s40, s40, s38
	s_add_i32 s40, s40, s39
	s_add_i32 s40, s40, -1
	s_cmp_lt_u32 s40, 0x11f00
	s_cbranch_scc0 .Lbw2_none
	s_mov_b32 s41, 1
	s_cmp_lt_u32 s40, 0x8000
	s_cbranch_scc1 .Lbw2_have
	s_mov_b32 s41, 2
	s_sub_i32 s40, s40, 0x8000
	s_cmp_lt_u32 s40, 0x5200
	s_cbranch_scc1 .Lbw2_have
	s_mov_b32 s41, 3
	s_sub_i32 s40, s40, 0x5200

; #define WAIT_VM(n) do {} while (0)
; #define WAIT_ALL() do {} while (0)
; #define LAUNDER_S(x) do {} while (0)
; #define LAS __attribute__((address_space(3)))
; #define WAIT_VM(n) asm volatile("s_waitcnt vmcnt(" #n ")" ::: "memory")
; #define WAIT_ALL() asm volatile("s_waitcnt vmcnt(0) lgkmcnt(0)" ::: "memory")
; #define NT_LOAD(p) __builtin_nontemporal_load(p)
; #define LAUNDER_S(x) asm volatile("" : "+s"(x))
; DEV int lane_id() { return (int)__builtin_amdgcn_mbcnt_hi(~0u, __builtin_amdgcn_mbcnt_lo(~0u, 0u)); }
; DEV void xcd_barrier(const XcdBarrier& b) {
;     WAIT_VM(0);
;     __syncthreads();
;     int bw = b.wave; LAUNDER_S(bw);
;     if (bw == 0 && lane_id() == 0) {
;         unsigned* bar = b.bar; LAUNDER_S(bar);
;         unsigned bx = b.x; LAUNDER_S(bx);
;         WAIT_ALL();
;         unsigned nloc = b.st[0], nx = b.st[1];
;         if (nloc == 0u) { xcd_barrier_complete(bar, bx, nloc, nx); b.st[0] = nloc; b.st[1] = nx; }
; DEV void tr_item(const float* W, int ldw, int col0, int k0, bf16_t* WT, int K, int row0, LAS float* scr, int lane) {
; #pragma unroll 8
;     for (int i = 0; i < 32; ++i) { const int kk = 2 * i + (lane >> 5); scr[kk * 33 + (lane & 31)] = NT_LOAD(&W[(size_t)(k0 + kk) * ldw + col0 + (lane & 31)]); }
.Lbw2_gate:
	s_add_u32 s42, s100, s42
	s_addc_u32 s43, s101, 0
	s_lshl_b32 s39, s41, 16
	s_or_b32 s41, s39, s40
	v_lshrrev_b32_e32 v129, 5, v200
	v_and_b32_e32 v130, 31, v200
	v_lshlrev_b32_e32 v130, 2, v130
	v_lshl_add_u32 v36, v129, 13, v130
	v_mov_b32_e32 v37, 0
	s_mov_b64 s[100:101], 0x4000
	v_lshl_add_u64 v[20:21], s[42:43], 0, v[36:37]
	v_lshl_add_u64 v[22:23], v[20:21], 0, s[100:101]
	v_lshl_add_u64 v[24:25], v[22:23], 0, s[100:101]
	v_lshl_add_u64 v[26:27], v[24:25], 0, s[100:101]
	v_lshl_add_u64 v[28:29], v[26:27], 0, s[100:101]
	v_lshl_add_u64 v[30:31], v[28:29], 0, s[100:101]
	v_lshl_add_u64 v[32:33], v[30:31], 0, s[100:101]
	v_lshl_add_u64 v[34:35], v[32:33], 0, s[100:101]
	s_mov_b64 s[100:101], 0x20000
	global_load_dword v38, v[20:21], off nt
	global_load_dword v39, v[22:23], off nt
	global_load_dword v40, v[24:25], off nt
	global_load_dword v41, v[26:27], off nt
	global_load_dword v42, v[28:29], off nt
	global_load_dword v43, v[30:31], off nt
	global_load_dword v44, v[32:33], off nt
	global_load_dword v45, v[34:35], off nt
	v_lshl_add_u64 v[20:21], v[20:21], 0, s[100:101]
	v_lshl_add_u64 v[22:23], v[22:23], 0, s[100:101]
	v_lshl_add_u64 v[24:25], v[24:25], 0, s[100:101]
	v_lshl_add_u64 v[26:27], v[26:27], 0, s[100:101]
	v_lshl_add_u64 v[28:29], v[28:29], 0, s[100:101]
	v_lshl_add_u64 v[30:31], v[30:31], 0, s[100:101]
	v_lshl_add_u64 v[32:33], v[32:33], 0, s[100:101]
	v_lshl_add_u64 v[34:35], v[34:35], 0, s[100:101]
	global_load_dword v46, v[20:21], off nt
	global_load_dword v47, v[22:23], off nt
	global_load_dword v48, v[24:25], off nt
	global_load_dword v49, v[26:27], off nt
	global_load_dword v50, v[28:29], off nt
	global_load_dword v51, v[30:31], off nt
	global_load_dword v52, v[32:33], off nt
	global_load_dword v53, v[34:35], off nt
	v_lshl_add_u64 v[20:21], v[20:21], 0, s[100:101]
	v_lshl_add_u64 v[22:23], v[22:23], 0, s[100:101]
	v_lshl_add_u64 v[24:25], v[24:25], 0, s[100:101]
	v_lshl_add_u64 v[26:27], v[26:27], 0, s[100:101]
	v_lshl_add_u64 v[28:29], v[28:29], 0, s[100:101]
	v_lshl_add_u64 v[30:31], v[30:31], 0, s[100:101]
	v_lshl_add_u64 v[32:33], v[32:33], 0, s[100:101]
	v_lshl_add_u64 v[34:35], v[34:35], 0, s[100:101]
	global_load_dword v54, v[20:21], off nt
	global_load_dword v55, v[22:23], off nt
	global_load_dword v56, v[24:25], off nt
	global_load_dword v57, v[26:27], off nt
	global_load_dword v58, v[28:29], off nt
	global_load_dword v59, v[30:31], off nt
	global_load_dword v60, v[32:33], off nt
	global_load_dword v61, v[34:35], off nt
	v_lshl_add_u64 v[20:21], v[20:21], 0, s[100:101]
	v_lshl_add_u64 v[22:23], v[22:23], 0, s[100:101]
	v_lshl_add_u64 v[24:25], v[24:25], 0, s[100:101]
	v_lshl_add_u64 v[26:27], v[26:27], 0, s[100:101]
	v_lshl_add_u64 v[28:29], v[28:29], 0, s[100:101]
	v_lshl_add_u64 v[30:31], v[30:31], 0, s[100:101]
	v_lshl_add_u64 v[32:33], v[32:33], 0, s[100:101]
	v_lshl_add_u64 v[34:35], v[34:35], 0, s[100:101]
	global_load_dword v62, v[20:21], off nt
	global_load_dword v63, v[22:23], off nt
	global_load_dword v64, v[24:25], off nt
	global_load_dword v65, v[26:27], off nt
	global_load_dword v66, v[28:29], off nt
	global_load_dword v67, v[30:31], off nt
	global_load_dword v68, v[32:33], off nt
	global_load_dword v69, v[34:35], off nt
.Lbw2_none:
	v_writelane_b32 v255, s41, 60
	s_nop 0
	v_readlane_b32 s38, v255, 61
	s_cmp_lg_u32 s38, 0
	s_barrier
	s_nop 0
	v_or_b32_e32 v0, s0, v200
	v_cmp_eq_u32_e32 vcc, 0, v0
	s_and_saveexec_b64 s[34:35], vcc
	s_cbranch_execz .LBB0_241
	v_readlane_b32 s4, v251, 0
	v_readlane_b32 s6, v251, 2
	v_readlane_b32 s7, v251, 3
	s_mov_b64 s[36:37], s[6:7]
	v_readlane_b32 s0, v251, 28
	v_readlane_b32 s2, v253, 7
	s_waitcnt vmcnt(0) lgkmcnt(0)
	v_readlane_b32 s5, v251, 1
	s_nop 0
	v_mov_b32_e32 v0, s2
	ds_read_b32 v2, v0
	v_readlane_b32 s2, v253, 8
	s_waitcnt lgkmcnt(0)
	v_cmp_ne_u32_e32 vcc, 0, v2
	v_mov_b32_e32 v0, s2
	ds_read_b32 v0, v0
	s_cbranch_vccnz .LBB0_212
	s_add_u32 s2, s36, 0x1000
	s_addc_u32 s3, s37, 0
	s_add_u32 s4, s36, 0x1100
	s_addc_u32 s5, s37, 0
	s_add_u32 s6, s36, 0x1200
	s_addc_u32 s7, s37, 0
	s_add_u32 s8, s36, 0x1300
	s_addc_u32 s9, s37, 0
	s_mov_b32 s28, 1
	s_mov_b64 s[10:11], 0
	s_branch .LBB0_202

; #define WAVE_LDS_SYNC() do { int _z = 0; (void)emu::wave_xchg(&_z, 4); } while (0)
; #define LAS __attribute__((address_space(3)))
; #define WAVE_LDS_SYNC() asm volatile("s_waitcnt lgkmcnt(0)" ::: "memory")
; #define NT_LOAD(p) __builtin_nontemporal_load(p)
; #define NT_STORE(v, p) __builtin_nontemporal_store((v), (p))
; DEV unsigned pk2(float lo, float hi) { return f2bf(lo) | (f2bf(hi) << 16); }
; DEV unsigned pk2(float lo, float hi) { const f32x2n_t v = {lo, hi}; return __builtin_bit_cast(unsigned, __builtin_convertvector(v, bf16x2n_t)); }
; DEV void xcd_barrier(const XcdBarrier& b) {
;     ...
;     __syncthreads();
; DEV void tr_item(const float* W, int ldw, int col0, int k0, bf16_t* WT, int K, int row0, LAS float* scr, int lane) {
; #pragma unroll 8
;     for (int i = 0; i < 32; ++i) { const int kk = 2 * i + (lane >> 5); scr[kk * 33 + (lane & 31)] = NT_LOAD(&W[(size_t)(k0 + kk) * ldw + col0 + (lane & 31)]); }
;     WAVE_LDS_SYNC();
;     const int c = lane & 7;
; #pragma unroll
;     for (int j = 0; j < 4; ++j) { const int n = (lane >> 3) + 8 * j; const LAS float* s = scr + (8 * c) * 33 + n;
;         u32x4 o; o.x = pk2(s[0 * 33], s[1 * 33]); o.y = pk2(s[2 * 33], s[3 * 33]); o.z = pk2(s[4 * 33], s[5 * 33]); o.w = pk2(s[6 * 33], s[7 * 33]);
;         NT_STORE(o, (u32x4*)(WT + (size_t)(row0 + n) * K + k0 + 8 * c)); }
;     WAVE_LDS_SYNC();
.LBB0_241:
	v_writelane_b32 v253, s58, 51
	s_nop 1
	v_writelane_b32 v253, s59, 52
	v_writelane_b32 v253, s56, 53
	s_nop 1
	v_writelane_b32 v253, s57, 54
	s_or_b64 exec, exec, s[34:35]
	s_mov_b64 s[74:75], s[54:55]
	v_readlane_b32 s4, v251, 0
	v_readlane_b32 s2, v251, 29
	v_readlane_b32 s0, v251, 30
	v_readlane_b32 s5, v251, 1
	v_readlane_b32 s6, v251, 2
	v_readlane_b32 s7, v251, 3
	v_writelane_b32 v251, s64, 47
	v_mov_b32_e32 v223, v200
	s_mov_b64 s[4:5], s[6:7]
	v_writelane_b32 v251, s65, 48
	v_writelane_b32 v251, s66, 49
	v_writelane_b32 v251, s67, 50
	v_writelane_b32 v251, s68, 51
	v_writelane_b32 v251, s69, 52
	v_writelane_b32 v251, s70, 53
	v_writelane_b32 v251, s71, 54
	s_waitcnt lgkmcnt(0)
	s_barrier
	s_cselect_b32 s38, 1, 0
	v_writelane_b32 v255, s38, 61
	s_nop 0
	v_readlane_b32 s40, v255, 60
	s_cmp_eq_u32 s40, 0
	s_cbranch_scc1 .Lbw2_skip
	s_lshr_b32 s41, s40, 16
	s_and_b32 s40, s40, 0xffff
	s_and_b32 s38, s40, 0x7ff
	s_lshr_b32 s39, s38, 7
	s_and_b32 s38, s38, 0x7f
	s_lshl_b32 s42, s38, 16
	s_lshl_b32 s39, s39, 7
	s_add_i32 s42, s42, s39
	s_lshr_b32 s39, s40, 11
	s_lshl_b32 s39, s39, 23
	s_add_i32 s42, s42, s39
	s_lshl_b32 s39, s41, 27
	s_add_u32 s42, s42, s39
	s_add_u32 s42, s42, 0x2bc8000
	v_readlane_b32 s100, v255, 53
	v_readlane_b32 s101, v255, 54
	s_add_u32 s42, s100, s42
	s_addc_u32 s43, s101, 0
	v_readlane_b32 s39, v251, 29
	s_lshl_b32 s39, s39, 14
	v_and_b32_e32 v129, 31, v200
	v_lshrrev_b32_e32 v130, 5, v200
	v_mul_u32_u24_e32 v130, 33, v130
	v_add_u32_e32 v130, v130, v129
	v_lshl_add_u32 v120, v130, 2, s39
	v_add_u32_e32 v121, 0x400, v120
	v_add_u32_e32 v122, 0x840, v120
	v_add_u32_e32 v123, 0xc40, v120
	v_add_u32_e32 v124, 0x1080, v120
	v_add_u32_e32 v125, 0x1480, v120
	v_add_u32_e32 v126, 0x18c0, v120
	v_add_u32_e32 v127, 0x1cc0, v120
	v_and_b32_e32 v129, 7, v200
	v_lshrrev_b32_e32 v130, 3, v200
	v_mul_u32_u24_e32 v131, 0x108, v129
	v_add_u32_e32 v131, v131, v130
	v_lshl_add_u32 v128, v131, 2, s39
	v_lshlrev_b32_e32 v129, 4, v129
	v_lshl_add_u32 v36, v130, 11, v129
	v_mov_b32_e32 v37, 0
	s_mov_b64 s[100:101], 0x4000
	v_lshl_add_u64 v[20:21], s[42:43], 0, v[36:37]
	v_lshl_add_u64 v[22:23], v[20:21], 0, s[100:101]
	v_lshl_add_u64 v[24:25], v[22:23], 0, s[100:101]
	v_lshl_add_u64 v[26:27], v[24:25], 0, s[100:101]
	s_waitcnt vmcnt(0)
	ds_write2_b32 v120, v38, v39 offset1:66
	ds_write2_b32 v120, v40, v41 offset0:132 offset1:198
	ds_write2_b32 v121, v42, v43 offset0:8 offset1:74
	ds_write2_b32 v121, v44, v45 offset0:140 offset1:206
	ds_write2_b32 v122, v46, v47 offset1:66
	ds_write2_b32 v122, v48, v49 offset0:132 offset1:198
	ds_write2_b32 v123, v50, v51 offset0:8 offset1:74
	ds_write2_b32 v123, v52, v53 offset0:140 offset1:206
	ds_write2_b32 v124, v54, v55 offset1:66
	ds_write2_b32 v124, v56, v57 offset0:132 offset1:198
	ds_write2_b32 v125, v58, v59 offset0:8 offset1:74
	ds_write2_b32 v125, v60, v61 offset0:140 offset1:206
	ds_write2_b32 v126, v62, v63 offset1:66
	ds_write2_b32 v126, v64, v65 offset0:132 offset1:198
	ds_write2_b32 v127, v66, v67 offset0:8 offset1:74
	ds_write2_b32 v127, v68, v69 offset0:140 offset1:206
	ds_read2_b32 v[70:71], v128 offset1:8
	ds_read2_b32 v[72:73], v128 offset0:33 offset1:41
	ds_read2_b32 v[74:75], v128 offset0:66 offset1:74
	ds_read2_b32 v[76:77], v128 offset0:99 offset1:107
	ds_read2_b32 v[78:79], v128 offset0:132 offset1:140
	ds_read2_b32 v[80:81], v128 offset0:165 offset1:173
	ds_read2_b32 v[82:83], v128 offset0:198 offset1:206
	ds_read2_b32 v[84:85], v128 offset0:231 offset1:239
	ds_read2_b32 v[88:89], v128 offset0:16 offset1:24
	ds_read2_b32 v[90:91], v128 offset0:49 offset1:57
	ds_read2_b32 v[92:93], v128 offset0:82 offset1:90
	ds_read2_b32 v[94:95], v128 offset0:115 offset1:123
	s_waitcnt lgkmcnt(4)
	v_cvt_pk_bf16_f32 v104, v70, v72
	v_cvt_pk_bf16_f32 v105, v74, v76
	v_cvt_pk_bf16_f32 v106, v78, v80
	v_cvt_pk_bf16_f32 v107, v82, v84
	v_cvt_pk_bf16_f32 v108, v71, v73
	v_cvt_pk_bf16_f32 v109, v75, v77
	v_cvt_pk_bf16_f32 v110, v79, v81
	v_cvt_pk_bf16_f32 v111, v83, v85
	ds_read2_b32 v[96:97], v128 offset0:148 offset1:156
	ds_read2_b32 v[98:99], v128 offset0:181 offset1:189
	ds_read2_b32 v[100:101], v128 offset0:214 offset1:222
	ds_read2_b32 v[102:103], v128 offset0:247 offset1:255
	global_store_dwordx4 v[20:21], v[104:107], off nt
	global_store_dwordx4 v[22:23], v[108:111], off nt
	s_waitcnt lgkmcnt(0)
	v_cvt_pk_bf16_f32 v112, v88, v90
	v_cvt_pk_bf16_f32 v113, v92, v94
	v_cvt_pk_bf16_f32 v114, v96, v98
	v_cvt_pk_bf16_f32 v115, v100, v102
	v_cvt_pk_bf16_f32 v116, v89, v91
	v_cvt_pk_bf16_f32 v117, v93, v95
	v_cvt_pk_bf16_f32 v118, v97, v99
	v_cvt_pk_bf16_f32 v119, v101, v103
	global_store_dwordx4 v[24:25], v[112:115], off nt
	global_store_dwordx4 v[26:27], v[116:119], off nt
; DEV void row_bs(int r, int& b, int& s) { if (r < LATR) { b = r / SEQ; s = CTX + r % SEQ; } else { const int q = r - LATR; b = q / CTX; s = q % CTX; } }
; #define ROW_GROUPS(nrows, CALL4, CALL2) do { const int _r4 = ((nrows) / (4 * F.NGW)) * (4 * F.NGW); \
;     for (int r = 4 * F.gw; r < _r4; r += 4 * F.NGW) { CALL4; } for (int r = _r4 + (F.wave * F.G + F.bid); r < (nrows); r += F.NGW) { CALL2; } } while (0)
; template <int RG> DEV void prep_group(const Frame& F, int l, int r) {
;     const int odd = l & 1, li = l >> 1; const int nin = odd ? NIN_O : NIN_E, nseg = odd ? 2 : 3, qld = odd ? 1024 : 1536;
;     const bf16_t* P = (const bf16_t*)(F.ws + WS_P); bf16_t* Q = (bf16_t*)(F.ws + WS_QKV);
;     const float* cw = odd ? GIN(I_ODCONV) + (size_t)li * 9 * 1024 : GIN(I_EVCONV) + (size_t)li * 9 * 1536; const int cch = odd ? 1024 : 1536;
;     {
;         int b, s; row_bs(r, b, s); const bool lat = s >= CTX; const int rr = lat ? (s - CTX) >> 6 : 0, cc = lat ? (s - CTX) & 63 : s;
;         const int ncol = lat ? 64 : CTX;
;         for (int seg = 0; seg < nseg; ++seg) {
;             const int ch0 = seg * 512 + F.lane * 8; float a[RG][8];
; DEV void phase_prep(const Frame& F0, int l) {
;     const Frame F = refresh(F0);
;     const int odd = l & 1;
;     ROW_GROUPS(MROWS, prep_group<4>(F, l, r), prep_group<1>(F, l, r));
.Lbw2_skip:
	s_waitcnt lgkmcnt(0)
	s_barrier
	v_readlane_b32 s38, v255, 61
	s_cmp_lg_u32 s38, 0
	v_writelane_b32 v251, s72, 55
	v_writelane_b32 v253, s2, 55
	s_add_i32 s2, s2, s0
	v_writelane_b32 v253, s4, 56
	v_writelane_b32 v251, s73, 56
	s_mov_b32 s0, s2
	v_writelane_b32 v253, s5, 57
	v_writelane_b32 v251, s74, 57
	v_writelane_b32 v253, s0, 58
	v_and_b32_e32 v227, 15, v223
	v_writelane_b32 v251, s75, 58
	v_writelane_b32 v253, s1, 59
	s_lshl_b32 s93, s2, 2
	v_cmp_lt_u32_e64 s[2:3], 7, v227
	v_writelane_b32 v251, s76, 59
	v_writelane_b32 v251, s77, 60
	v_writelane_b32 v253, s2, 60
	v_writelane_b32 v251, s78, 61
	v_bfe_u32 v226, v223, 2, 2
	v_writelane_b32 v253, s3, 61
	v_writelane_b32 v253, s52, 62
	v_writelane_b32 v251, s79, 62
	v_readlane_b32 s0, v252, 5
	v_lshrrev_b32_e32 v0, 1, v223
	v_writelane_b32 v253, s53, 63
	v_add_u32_e32 v229, s52, v226
	v_readlane_b32 s52, v251, 31
	s_cmp_ge_i32 s93, s0
	v_lshlrev_b32_e32 v152, 3, v223
	v_ashrrev_i32_e32 v224, 4, v223
	v_and_b32_e32 v225, 3, v223
	v_and_b32_e32 v228, 4, v0
	v_lshlrev_b32_e32 v154, 2, v227
	v_lshlrev_b32_e32 v150, 1, v227
	v_readlane_b32 s53, v251, 32
	v_readlane_b32 s54, v251, 33
	v_readlane_b32 s55, v251, 34
	v_readlane_b32 s56, v251, 35
	v_readlane_b32 s57, v251, 36
	v_readlane_b32 s58, v251, 37
	v_readlane_b32 s59, v251, 38
	v_readlane_b32 s60, v251, 39
	v_readlane_b32 s61, v251, 40
	v_readlane_b32 s62, v251, 41
	v_readlane_b32 s63, v251, 42
	v_readlane_b32 s64, v251, 43
	v_readlane_b32 s65, v251, 44
	v_readlane_b32 s66, v251, 45
	v_readlane_b32 s67, v251, 46
	s_cbranch_scc1 .LBB0_306
	v_readlane_b32 s14, v253, 62
	s_lshr_b32 s0, s14, 1
	v_readlane_b32 s2, v253, 49
	s_cmp_lg_u32 s2, 0
	s_cselect_b64 s[12:13], -1, 0
	s_cmp_eq_u32 s2, 0
	s_cselect_b64 s[2:3], -1, 0
	v_writelane_b32 v254, s2, 0
	v_readlane_b32 s15, v253, 63
	v_readlane_b32 s18, v253, 56
	v_writelane_b32 v254, s3, 1
	s_and_b64 s[2:3], s[12:13], exec
	s_movk_i32 s2, 0x1100
	s_cselect_b32 s16, 0xb00, s2
	s_movk_i32 s2, 0x600
	s_cselect_b32 s15, 0x400, s2
	v_readlane_b32 s19, v253, 57
	s_add_u32 s20, s18, 0x415d4c00
	s_addc_u32 s21, s19, 0
	s_add_u32 s2, s18, 0x4a654c00
	s_addc_u32 s3, s19, 0
	v_writelane_b32 v254, s2, 2
	v_mov_b32_e32 v155, v1
	v_readlane_b32 s36, v251, 12
	v_writelane_b32 v254, s3, 3
	s_and_b64 s[2:3], s[12:13], exec
	s_mov_b32 s2, 0x9000
	s_cselect_b32 s2, s2, 0xd800
	s_mul_hi_u32 s4, s2, s0
	s_mul_i32 s0, s2, s0
	v_cmp_gt_i32_e64 s[2:3], 64, v223
	s_lshl_b32 s5, s15, 1
	s_lshl_b32 s7, s15, 2
	v_writelane_b32 v254, s2, 4
	s_lshl_b32 s11, s15, 3
	v_readlane_b32 s50, v251, 26
	v_writelane_b32 v254, s3, 5
	s_and_b32 s2, s14, 2
	v_and_or_b32 v2, v226, 1, s2
	v_lshlrev_b32_e32 v2, 3, v2
	v_or3_b32 v4, v2, v228, v225
	v_lshl_add_u64 v[2:3], s[18:19], 0, v[154:155]
	s_mov_b64 s[2:3], 0x39298800
	v_lshl_add_u64 v[156:157], v[2:3], 0, s[2:3]
	s_and_b64 s[2:3], s[12:13], exec
	v_readlane_b32 s37, v251, 13
	v_readlane_b32 s51, v251, 27
	s_cselect_b32 s3, s50, s36
	s_cselect_b32 s2, s51, s37
	s_add_u32 s18, s3, s0
	s_addc_u32 s19, s2, s4
	v_writelane_b32 v254, s18, 6
	v_lshl_or_b32 v0, v229, 2, v225
	s_mul_i32 s6, s15, 3
	v_writelane_b32 v254, s19, 7
	v_writelane_b32 v254, s20, 8
	s_mul_i32 s8, s15, 5
	s_mul_i32 s9, s15, 6
	s_mul_i32 s10, s15, 7
	v_readlane_b32 s38, v251, 14
	v_readlane_b32 s39, v251, 15
	v_readlane_b32 s40, v251, 16
	v_readlane_b32 s41, v251, 17
	v_readlane_b32 s42, v251, 18
	v_readlane_b32 s44, v251, 20
	v_readlane_b32 s46, v251, 22
	v_lshlrev_b64 v[2:3], 2, v[0:1]
	v_lshlrev_b32_e32 v0, 2, v4
	v_mov_b32_e32 v151, v1
	v_writelane_b32 v254, s21, 9
	s_mov_b32 s17, s1
	v_lshl_add_u64 v[158:159], s[38:39], 0, v[2:3]
	v_lshl_add_u64 v[160:161], s[40:41], 0, v[2:3]
	v_lshl_add_u64 v[162:163], s[52:53], 0, v[0:1]
	v_lshl_add_u64 v[164:165], s[20:21], 0, v[150:151]
	v_writelane_b32 v254, s15, 10
	s_lshl_b32 s0, s15, 2
	s_lshl_b32 s24, s5, 2
	s_lshl_b32 s26, s6, 2
	s_lshl_b32 s38, s7, 2
	s_lshl_b32 s40, s8, 2
	s_lshl_b32 s42, s9, 2
	s_lshl_b32 s44, s10, 2
	s_lshl_b32 s46, s11, 2
	v_readlane_b32 s43, v251, 19
	v_readlane_b32 s45, v251, 21
	v_readlane_b32 s47, v251, 23
	v_readlane_b32 s48, v251, 24
	v_readlane_b32 s49, v251, 25
	s_branch .LBB0_246

; #define LAS __attribute__((address_space(3)))
; #define NT_LOAD(p) __builtin_nontemporal_load(p)
; DEV void tr_item(const float* W, int ldw, int col0, int k0, bf16_t* WT, int K, int row0, LAS float* scr, int lane) {
; #pragma unroll 8
;     for (int i = 0; i < 32; ++i) { const int kk = 2 * i + (lane >> 5); scr[kk * 33 + (lane & 31)] = NT_LOAD(&W[(size_t)(k0 + kk) * ldw + col0 + (lane & 31)]); }
; DEV void phase_prologue_a(const Frame& F0) {
;     ...
;         constexpr int GU_NB = 2 * FF / 32, GU_ITEMS = 16 * GU_NB;
;         for (int it = F.gw; it < NE * GU_ITEMS; it += F.NGW) { const int e = it / GU_ITEMS, r = it % GU_ITEMS, kb = r / GU_NB, nb = r % GU_NB; const int d0 = 32 * nb, j = d0 >> 8, w = d0 & 255;
;             const float* src = (w < 128 ? GIN(I_WGATE) : GIN(I_WUP)) + ((size_t)l * NE + e) * 1024 * FF;
;             tr_item(src, FF, 128 * j + (w & 127), 64 * kb, (bf16_t*)(F.ws + WS_WGU) + ((size_t)l * NE + e) * 2 * FF * 1024, 1024, d0, scr, F.lane); }
.Lbw3_gate:
	s_add_u32 s42, s100, s42
	s_addc_u32 s43, s101, 0
	s_lshl_b32 s39, s41, 16
	s_or_b32 s41, s39, s40
	v_lshrrev_b32_e32 v144, 5, v200
	v_and_b32_e32 v145, 31, v200
	v_lshlrev_b32_e32 v145, 2, v145
	v_lshl_add_u32 v36, v144, 13, v145
	v_mov_b32_e32 v37, 0
	s_mov_b64 s[100:101], 0x4000
	v_lshl_add_u64 v[20:21], s[42:43], 0, v[36:37]
	v_lshl_add_u64 v[22:23], v[20:21], 0, s[100:101]
	v_lshl_add_u64 v[24:25], v[22:23], 0, s[100:101]
	v_lshl_add_u64 v[26:27], v[24:25], 0, s[100:101]
	v_lshl_add_u64 v[28:29], v[26:27], 0, s[100:101]
	v_lshl_add_u64 v[30:31], v[28:29], 0, s[100:101]
	v_lshl_add_u64 v[32:33], v[30:31], 0, s[100:101]
	v_lshl_add_u64 v[34:35], v[32:33], 0, s[100:101]
	s_mov_b64 s[100:101], 0x20000
	global_load_dword v46, v[20:21], off nt
	global_load_dword v47, v[22:23], off nt
	global_load_dword v48, v[24:25], off nt
	global_load_dword v49, v[26:27], off nt
	global_load_dword v58, v[28:29], off nt
	global_load_dword v59, v[30:31], off nt
	global_load_dword v60, v[32:33], off nt
	global_load_dword v61, v[34:35], off nt
	v_lshl_add_u64 v[20:21], v[20:21], 0, s[100:101]
	v_lshl_add_u64 v[22:23], v[22:23], 0, s[100:101]
	v_lshl_add_u64 v[24:25], v[24:25], 0, s[100:101]
	v_lshl_add_u64 v[26:27], v[26:27], 0, s[100:101]
	v_lshl_add_u64 v[28:29], v[28:29], 0, s[100:101]
	v_lshl_add_u64 v[30:31], v[30:31], 0, s[100:101]
	v_lshl_add_u64 v[32:33], v[32:33], 0, s[100:101]
	v_lshl_add_u64 v[34:35], v[34:35], 0, s[100:101]
	global_load_dword v62, v[20:21], off nt
	global_load_dword v63, v[22:23], off nt
	global_load_dword v64, v[24:25], off nt
	global_load_dword v65, v[26:27], off nt
	global_load_dword v67, v[28:29], off nt
	global_load_dword v68, v[30:31], off nt
	global_load_dword v69, v[32:33], off nt
	global_load_dword v70, v[34:35], off nt
	v_lshl_add_u64 v[20:21], v[20:21], 0, s[100:101]
	v_lshl_add_u64 v[22:23], v[22:23], 0, s[100:101]
	v_lshl_add_u64 v[24:25], v[24:25], 0, s[100:101]
	v_lshl_add_u64 v[26:27], v[26:27], 0, s[100:101]
	v_lshl_add_u64 v[28:29], v[28:29], 0, s[100:101]
	v_lshl_add_u64 v[30:31], v[30:31], 0, s[100:101]
	v_lshl_add_u64 v[32:33], v[32:33], 0, s[100:101]
	v_lshl_add_u64 v[34:35], v[34:35], 0, s[100:101]
	global_load_dword v71, v[20:21], off nt
	global_load_dword v72, v[22:23], off nt
	global_load_dword v73, v[24:25], off nt
	global_load_dword v74, v[26:27], off nt
	global_load_dword v75, v[28:29], off nt
	global_load_dword v76, v[30:31], off nt
	global_load_dword v77, v[32:33], off nt
	global_load_dword v78, v[34:35], off nt
	v_lshl_add_u64 v[20:21], v[20:21], 0, s[100:101]
	v_lshl_add_u64 v[22:23], v[22:23], 0, s[100:101]
	v_lshl_add_u64 v[24:25], v[24:25], 0, s[100:101]
	v_lshl_add_u64 v[26:27], v[26:27], 0, s[100:101]
	v_lshl_add_u64 v[28:29], v[28:29], 0, s[100:101]
	v_lshl_add_u64 v[30:31], v[30:31], 0, s[100:101]
	v_lshl_add_u64 v[32:33], v[32:33], 0, s[100:101]
	v_lshl_add_u64 v[34:35], v[34:35], 0, s[100:101]
	global_load_dword v79, v[20:21], off nt
	global_load_dword v80, v[22:23], off nt
	global_load_dword v81, v[24:25], off nt
	global_load_dword v82, v[26:27], off nt
	global_load_dword v83, v[28:29], off nt
	global_load_dword v84, v[30:31], off nt
	global_load_dword v85, v[32:33], off nt
	global_load_dword v86, v[34:35], off nt

; #define WAVE_LDS_SYNC() do { int _z = 0; (void)emu::wave_xchg(&_z, 4); } while (0)
; #define LAS __attribute__((address_space(3)))
; DEV void tr_item(const float* W, int ldw, int col0, int k0, bf16_t* WT, int K, int row0, LAS float* scr, int lane) {
; #pragma unroll 8
;     for (int i = 0; i < 32; ++i) { const int kk = 2 * i + (lane >> 5); scr[kk * 33 + (lane & 31)] = NT_LOAD(&W[(size_t)(k0 + kk) * ldw + col0 + (lane & 31)]); }
;     WAVE_LDS_SYNC();
;     const int c = lane & 7;
; #pragma unroll
;     for (int j = 0; j < 4; ++j) { const int n = (lane >> 3) + 8 * j; const LAS float* s = scr + (8 * c) * 33 + n;
;         u32x4 o; o.x = pk2(s[0 * 33], s[1 * 33]); o.y = pk2(s[2 * 33], s[3 * 33]); o.z = pk2(s[4 * 33], s[5 * 33]); o.w = pk2(s[6 * 33], s[7 * 33]);
;         NT_STORE(o, (u32x4*)(WT + (size_t)(row0 + n) * K + k0 + 8 * c)); }
;     WAVE_LDS_SYNC();
; DEV void seq_s5_item(const Frame& F, int l, int item, int which) {
;     const int o = l >> 1; const int g = item & 31, d = (item >> 5) & 1, b = item >> 6;
;     LAS float* El = (LAS float*)(F.lds);
;     LAS unsigned char* wl = F.lds + 36864 + F.wave * 14336;
;     LAS float* scr = (LAS float*)wl; LAS bf16_t* hb = (LAS bf16_t*)(wl + 10240);
;     const bf16_t* P = (const bf16_t*)(F.ws + WS_P);
;     const float* Ab = (const float*)(F.ws + WS_S5A) + (size_t)((o * 2 + d) * 32 + g) * 128;
;     const bf16_t* Bb = (const bf16_t*)(F.ws + WS_S5B) + (size_t)((o * 2 + d) * 32 + g) * 128 * 16;
;     const bf16_t* Cm = (const bf16_t*)(F.ws + WS_S5C) + (size_t)(o * 32 + g) * 16 * 128;
;     const int l15 = F.lane & 15, kg = F.lane >> 4;
;     const float ar = Ab[F.lane], ai = Ab[64 + F.lane];
;     bf16x8 bB[8], cB[4]; const bf16x8 zero8 = (bf16x8){0, 0, 0, 0, 0, 0, 0, 0};
; #pragma unroll
;     for (int ct = 0; ct < 8; ++ct) bB[ct] = kg < 2 ? *(const bf16x8*)(Bb + (size_t)(16 * ct + l15) * 16 + 8 * kg) : zero8;
; #pragma unroll
;     for (int s = 0; s < 4; ++s) cB[s] = *(const bf16x8*)(Cm + (size_t)l15 * 128 + 32 * s + 8 * kg);
;     bf16_t* Obase = (bf16_t*)(F.ws + WS_O) + (size_t)d * MROWS * 1024 + 512 + 16 * g;
;     float* SE = (float*)(F.ws + WS_S5E) + (size_t)item * NCH * 128;
;     if (which == 1) { for (int i = F.tid; i < NCH * 128; i += NTHREADS) El[i] = SE[i]; __syncthreads(); }
;     for (int pass = which; pass < which + 1; ++pass) {
;         bf16x8 an[4];
; #pragma unroll
.LBB0_422:
	s_or_b64 exec, exec, s[34:35]
	v_readlane_b32 s2, v252, 10
	v_readlane_b32 s64, v251, 29
	v_mov_b32_e32 v66, v200
	v_readlane_b32 s4, v251, 0
	v_readlane_b32 s3, v252, 11
	s_waitcnt lgkmcnt(0)
	s_barrier
	s_cselect_b32 s38, 1, 0
	v_writelane_b32 v255, s38, 61
	s_nop 0
	v_readlane_b32 s40, v255, 60
	s_cmp_eq_u32 s40, 0
	s_cbranch_scc1 .Lbw3_skip
	s_lshr_b32 s41, s40, 16
	s_and_b32 s40, s40, 0xffff
	s_and_b32 s38, s40, 0x7ff
	s_lshr_b32 s39, s38, 7
	s_and_b32 s38, s38, 0x7f
	s_lshl_b32 s42, s38, 16
	s_lshl_b32 s39, s39, 7
	s_add_i32 s42, s42, s39
	s_lshr_b32 s39, s40, 11
	s_lshl_b32 s39, s39, 23
	s_add_i32 s42, s42, s39
	s_lshl_b32 s39, s41, 27
	s_add_u32 s42, s42, s39
	s_add_u32 s42, s42, 0x2bc8000
	v_readlane_b32 s100, v255, 53
	v_readlane_b32 s101, v255, 54
	s_add_u32 s42, s100, s42
	s_addc_u32 s43, s101, 0
	v_readlane_b32 s39, v251, 29
	s_lshl_b32 s39, s39, 14
	v_and_b32_e32 v144, 31, v200
	v_lshrrev_b32_e32 v145, 5, v200
	v_mul_u32_u24_e32 v145, 33, v145
	v_add_u32_e32 v145, v145, v144
	v_lshl_add_u32 v87, v145, 2, s39
	v_add_u32_e32 v136, 0x400, v87
	v_add_u32_e32 v137, 0x840, v87
	v_add_u32_e32 v138, 0xc40, v87
	v_add_u32_e32 v139, 0x1080, v87
	v_add_u32_e32 v140, 0x1480, v87
	v_add_u32_e32 v141, 0x18c0, v87
	v_add_u32_e32 v142, 0x1cc0, v87
	v_and_b32_e32 v144, 7, v200
	v_lshrrev_b32_e32 v145, 3, v200
	v_mul_u32_u24_e32 v147, 0x108, v144
	v_add_u32_e32 v147, v147, v145
	v_lshl_add_u32 v143, v147, 2, s39
	v_lshlrev_b32_e32 v144, 4, v144
	v_lshl_add_u32 v36, v145, 11, v144
	v_mov_b32_e32 v37, 0
	s_mov_b64 s[100:101], 0x4000
	v_lshl_add_u64 v[20:21], s[42:43], 0, v[36:37]
	v_lshl_add_u64 v[22:23], v[20:21], 0, s[100:101]
	v_lshl_add_u64 v[24:25], v[22:23], 0, s[100:101]
	v_lshl_add_u64 v[26:27], v[24:25], 0, s[100:101]
	s_waitcnt vmcnt(0)
	ds_write2_b32 v87, v46, v47 offset1:66
	ds_write2_b32 v87, v48, v49 offset0:132 offset1:198
	ds_write2_b32 v136, v58, v59 offset0:8 offset1:74
	ds_write2_b32 v136, v60, v61 offset0:140 offset1:206
	ds_write2_b32 v137, v62, v63 offset1:66
	ds_write2_b32 v137, v64, v65 offset0:132 offset1:198
	ds_write2_b32 v138, v67, v68 offset0:8 offset1:74
	ds_write2_b32 v138, v69, v70 offset0:140 offset1:206
	ds_write2_b32 v139, v71, v72 offset1:66
	ds_write2_b32 v139, v73, v74 offset0:132 offset1:198
	ds_write2_b32 v140, v75, v76 offset0:8 offset1:74
	ds_write2_b32 v140, v77, v78 offset0:140 offset1:206
	ds_write2_b32 v141, v79, v80 offset1:66
	ds_write2_b32 v141, v81, v82 offset0:132 offset1:198
	ds_write2_b32 v142, v83, v84 offset0:8 offset1:74
	ds_write2_b32 v142, v85, v86 offset0:140 offset1:206
	ds_read2_b32 v[88:89], v143 offset1:8
	ds_read2_b32 v[90:91], v143 offset0:33 offset1:41
	ds_read2_b32 v[92:93], v143 offset0:66 offset1:74
	ds_read2_b32 v[94:95], v143 offset0:99 offset1:107
	ds_read2_b32 v[96:97], v143 offset0:132 offset1:140
	ds_read2_b32 v[98:99], v143 offset0:165 offset1:173
	ds_read2_b32 v[100:101], v143 offset0:198 offset1:206
	ds_read2_b32 v[102:103], v143 offset0:231 offset1:239
	ds_read2_b32 v[104:105], v143 offset0:16 offset1:24
	ds_read2_b32 v[106:107], v143 offset0:49 offset1:57
	ds_read2_b32 v[108:109], v143 offset0:82 offset1:90
	ds_read2_b32 v[110:111], v143 offset0:115 offset1:123
	s_waitcnt lgkmcnt(4)
	v_cvt_pk_bf16_f32 v120, v88, v90
	v_cvt_pk_bf16_f32 v121, v92, v94
	v_cvt_pk_bf16_f32 v122, v96, v98
	v_cvt_pk_bf16_f32 v123, v100, v102
	v_cvt_pk_bf16_f32 v124, v89, v91
	v_cvt_pk_bf16_f32 v125, v93, v95
	v_cvt_pk_bf16_f32 v126, v97, v99
	v_cvt_pk_bf16_f32 v127, v101, v103
	ds_read2_b32 v[112:113], v143 offset0:148 offset1:156
	ds_read2_b32 v[114:115], v143 offset0:181 offset1:189
	ds_read2_b32 v[116:117], v143 offset0:214 offset1:222
	ds_read2_b32 v[118:119], v143 offset0:247 offset1:255
	global_store_dwordx4 v[20:21], v[120:123], off nt
	global_store_dwordx4 v[22:23], v[124:127], off nt
	s_waitcnt lgkmcnt(0)
	v_cvt_pk_bf16_f32 v128, v104, v106
	v_cvt_pk_bf16_f32 v129, v108, v110
	v_cvt_pk_bf16_f32 v130, v112, v114
	v_cvt_pk_bf16_f32 v131, v116, v118
	v_cvt_pk_bf16_f32 v132, v105, v107
	v_cvt_pk_bf16_f32 v133, v109, v111
	v_cvt_pk_bf16_f32 v134, v113, v115
	v_cvt_pk_bf16_f32 v135, v117, v119
	global_store_dwordx4 v[24:25], v[128:131], off nt
	global_store_dwordx4 v[26:27], v[132:135], off nt
.Lbw3_skip:
	s_waitcnt lgkmcnt(0)
	s_barrier
	v_readlane_b32 s38, v255, 61
	s_cmp_lg_u32 s38, 0
	s_lshl_b32 s65, s64, 6
	v_readlane_b32 s6, v251, 2
	v_readlane_b32 s7, v251, 3
	s_or_b64 s[2:3], s[2:3], s[58:59]
	v_lshlrev_b32_e32 v73, 2, v66
	v_add_u32_e32 v68, s65, v66
	s_mov_b64 s[20:21], s[6:7]
	s_and_b64 vcc, exec, s[2:3]
	v_ashrrev_i32_e32 v67, 31, v66
	v_add_u32_e32 v148, 0, v73
	v_readlane_b32 s5, v251, 1
	s_cbranch_vccnz .LBB0_472
	s_mul_i32 s0, s64, 0x3800
	v_readlane_b32 s2, v253, 62
	s_add_i32 s0, s0, 0
	s_and_b32 s33, s2, 2
	s_add_u32 s22, s20, 0x415d4c00
	s_addc_u32 s23, s21, 0
	s_add_u32 s38, s20, 0x40d54c00
	s_addc_u32 s39, s21, 0
	s_cmpk_lt_i32 s64, 0x44
	s_cselect_b64 s[24:25], -1, 0
	s_cmp_eq_u32 s64, 0
	v_ashrrev_i32_e32 v0, 4, v66
	s_cselect_b64 s[26:27], -1, 0
	v_max_i32_e32 v4, 0x2000, v68
	s_lshl_b32 s18, s64, 9
	v_readlane_b32 s3, v253, 63
	v_lshlrev_b32_e32 v74, 3, v0
	v_sub_u32_e32 v4, v4, v68
	s_add_i32 s18, s18, 0
	v_lshl_add_u64 v[2:3], v[66:67], 2, s[20:21]
	s_mov_b64 s[2:3], 0x32bc8000
	v_ashrrev_i32_e32 v75, 31, v74
	v_add_u32_e32 v4, 0x1ff, v4
	v_add_u32_e32 v97, s18, v73
	s_lshl_b32 s18, s64, 8
	v_and_b32_e32 v78, 15, v66
	v_lshl_add_u64 v[70:71], v[2:3], 0, s[2:3]
	v_lshl_add_u64 v[2:3], v[74:75], 1, s[20:21]
	s_mov_b64 s[4:5], 0x32bd8000
	v_lshrrev_b32_e32 v5, 9, v4
	s_add_i32 s18, s18, 0
	v_lshl_add_u64 v[76:77], v[2:3], 0, s[4:5]
	v_or_b32_e32 v79, s65, v78
	v_mov_b32_e32 v2, s0
	s_movk_i32 s12, 0x50
	v_add_u32_e32 v5, 1, v5
	v_add_u32_e32 v98, s18, v73
	v_readlane_b32 s18, v252, 58
	v_cmp_gt_i32_e64 s[2:3], 2, v0
	v_and_b32_e32 v0, -16, v66
	v_or_b32_e32 v83, 16, v79
	v_or_b32_e32 v87, 32, v79
	v_or_b32_e32 v91, 48, v79
	v_mad_u32_u24 v2, v78, s12, v2
	v_mul_lo_u32 v3, v66, s12
	s_movk_i32 s12, 0x2200
	s_movk_i32 s14, 0x1ff
	v_and_b32_e32 v95, 0xfffffe, v5
	s_add_u32 s28, s20, s18
	v_readlane_b32 s18, v252, 59
	v_lshlrev_b32_e32 v72, 4, v78
	v_cmp_gt_i32_e64 s[4:5], s63, v79
	v_add_u32_e32 v80, 0xffffff00, v79
	v_sub_u32_e32 v81, 0x10ff, v79
	v_sub_u32_e32 v82, 0xff, v79
	v_cmp_gt_i32_e64 s[6:7], s63, v83
	v_add_u32_e32 v84, 0xffffff10, v79
	v_sub_u32_e32 v85, 0x10ff, v83
	v_sub_u32_e32 v86, 0xff, v83
	v_cmp_gt_i32_e64 s[8:9], s63, v87
	v_add_u32_e32 v88, 0xffffff20, v79
	v_sub_u32_e32 v89, 0x10ff, v87
	v_sub_u32_e32 v90, 0xff, v87
	v_cmp_gt_i32_e64 s[10:11], s63, v91
	v_add_u32_e32 v92, 0xffffff30, v79
	v_sub_u32_e32 v93, 0x10ff, v91
	v_sub_u32_e32 v94, 0xff, v91
	v_cmp_gt_i32_e64 s[12:13], s12, v68
	v_cmp_lt_u32_e64 s[14:15], s14, v4
	v_lshl_add_u32 v96, v95, 9, v68
	v_add_u32_e32 v69, 0x200, v68
	v_cmp_ne_u32_e64 s[16:17], v5, v95
	s_addc_u32 s29, s21, s18
	v_add_u32_e32 v99, v2, v0
	v_add_u32_e32 v100, s0, v3
	s_mov_b32 s40, s95
	s_branch .LBB0_425

; #define WAIT_VM(n) do {} while (0)
; #define LAUNDER_S(x) do {} while (0)
; #define WAIT_VM(n) asm volatile("s_waitcnt vmcnt(" #n ")" ::: "memory")
; #define LAUNDER_S(x) asm volatile("" : "+s"(x))
; DEV void xcd_barrier(const XcdBarrier& b) {
;     WAIT_VM(0);
;     __syncthreads();
;     int bw = b.wave; LAUNDER_S(bw);
; DEV void phase_prologue_a(const Frame& F0) {
;     ...
;         constexpr int GU_NB = 2 * FF / 32, GU_ITEMS = 16 * GU_NB;
;         for (int it = F.gw; it < NE * GU_ITEMS; it += F.NGW) { const int e = it / GU_ITEMS, r = it % GU_ITEMS, kb = r / GU_NB, nb = r % GU_NB; const int d0 = 32 * nb, j = d0 >> 8, w = d0 & 255;
;             const float* src = (w < 128 ? GIN(I_WGATE) : GIN(I_WUP)) + ((size_t)l * NE + e) * 1024 * FF;
;             tr_item(src, FF, 128 * j + (w & 127), 64 * kb, (bf16_t*)(F.ws + WS_WGU) + ((size_t)l * NE + e) * 2 * FF * 1024, 1024, d0, scr, F.lane); }
.LBB0_762:
	s_waitcnt vmcnt(0)
	s_waitcnt vmcnt(0) lgkmcnt(0)
	s_barrier
	s_waitcnt vmcnt(0)
	v_readlane_b32 s0, v251, 29
	s_cselect_b32 s38, 1, 0
	v_writelane_b32 v255, s38, 61
	v_readlane_b32 s38, v255, 59
	s_add_i32 s39, s38, 1
	v_writelane_b32 v255, s39, 59
	s_mov_b32 s41, 0
	v_readlane_b32 s39, v251, 29
	s_cmp_eq_u32 s39, 0
	s_cbranch_scc1 .Lbw4_none
	v_readlane_b32 s40, v255, 51
	s_cmp_lg_u32 s40, 0x100
	s_cbranch_scc1 .Lbw4_none
	v_readlane_b32 s40, v255, 48
	s_mul_i32 s40, s40, 7
	s_mul_i32 s38, s38, 0x700
	s_add_i32 s40, s40, s38
	s_add_i32 s40, s40, s39
	s_add_i32 s40, s40, -1
	s_cmp_lt_u32 s40, 0x11f00
	s_cbranch_scc0 .Lbw4_none
	s_mov_b32 s41, 1
	s_cmp_lt_u32 s40, 0x8000
	s_cbranch_scc1 .Lbw4_have
	s_mov_b32 s41, 2
	s_sub_i32 s40, s40, 0x8000
	s_cmp_lt_u32 s40, 0x5200
	s_cbranch_scc1 .Lbw4_have
	s_mov_b32 s41, 3
	s_sub_i32 s40, s40, 0x5200

; #define WAIT_VM(n) do {} while (0)
; #define WAIT_ALL() do {} while (0)
; #define LAUNDER_S(x) do {} while (0)
; #define LAS __attribute__((address_space(3)))
; #define WAIT_VM(n) asm volatile("s_waitcnt vmcnt(" #n ")" ::: "memory")
; #define WAIT_ALL() asm volatile("s_waitcnt vmcnt(0) lgkmcnt(0)" ::: "memory")
; #define NT_LOAD(p) __builtin_nontemporal_load(p)
; #define LAUNDER_S(x) asm volatile("" : "+s"(x))
; DEV int lane_id() { return (int)__builtin_amdgcn_mbcnt_hi(~0u, __builtin_amdgcn_mbcnt_lo(~0u, 0u)); }
; DEV unsigned xb_add(unsigned* p, unsigned v) { return __hip_atomic_fetch_add(p, v, __ATOMIC_RELAXED, __HIP_MEMORY_SCOPE_AGENT); }
; DEV void xcd_barrier(const XcdBarrier& b) {
;     WAIT_VM(0);
;     __syncthreads();
;     int bw = b.wave; LAUNDER_S(bw);
;     if (bw == 0 && lane_id() == 0) {
;         unsigned* bar = b.bar; LAUNDER_S(bar);
;         unsigned bx = b.x; LAUNDER_S(bx);
;         WAIT_ALL();
;         unsigned nloc = b.st[0], nx = b.st[1];
;         if (nloc == 0u) { xcd_barrier_complete(bar, bx, nloc, nx); b.st[0] = nloc; b.st[1] = nx; }
;         const unsigned old = xb_add(&bar[XB_XSUB(bx)], 1u);
; DEV void tr_item(const float* W, int ldw, int col0, int k0, bf16_t* WT, int K, int row0, LAS float* scr, int lane) {
; #pragma unroll 8
;     for (int i = 0; i < 32; ++i) { const int kk = 2 * i + (lane >> 5); scr[kk * 33 + (lane & 31)] = NT_LOAD(&W[(size_t)(k0 + kk) * ldw + col0 + (lane & 31)]); }
.Lbw4_gate:
	s_add_u32 s42, s100, s42
	s_addc_u32 s43, s101, 0
	s_lshl_b32 s39, s41, 16
	s_or_b32 s41, s39, s40
	v_lshrrev_b32_e32 v141, 5, v200
	v_and_b32_e32 v142, 31, v200
	v_lshlrev_b32_e32 v142, 2, v142
	v_lshl_add_u32 v36, v141, 13, v142
	v_mov_b32_e32 v37, 0
	s_mov_b64 s[100:101], 0x4000
	v_lshl_add_u64 v[20:21], s[42:43], 0, v[36:37]
	v_lshl_add_u64 v[22:23], v[20:21], 0, s[100:101]
	v_lshl_add_u64 v[24:25], v[22:23], 0, s[100:101]
	v_lshl_add_u64 v[26:27], v[24:25], 0, s[100:101]
	v_lshl_add_u64 v[28:29], v[26:27], 0, s[100:101]
	v_lshl_add_u64 v[30:31], v[28:29], 0, s[100:101]
	v_lshl_add_u64 v[32:33], v[30:31], 0, s[100:101]
	v_lshl_add_u64 v[34:35], v[32:33], 0, s[100:101]
	s_mov_b64 s[100:101], 0x20000
	global_load_dword v38, v[20:21], off nt
	global_load_dword v39, v[22:23], off nt
	global_load_dword v40, v[24:25], off nt
	global_load_dword v41, v[26:27], off nt
	global_load_dword v42, v[28:29], off nt
	global_load_dword v43, v[30:31], off nt
	global_load_dword v44, v[32:33], off nt
	global_load_dword v45, v[34:35], off nt
	v_lshl_add_u64 v[20:21], v[20:21], 0, s[100:101]
	v_lshl_add_u64 v[22:23], v[22:23], 0, s[100:101]
	v_lshl_add_u64 v[24:25], v[24:25], 0, s[100:101]
	v_lshl_add_u64 v[26:27], v[26:27], 0, s[100:101]
	v_lshl_add_u64 v[28:29], v[28:29], 0, s[100:101]
	v_lshl_add_u64 v[30:31], v[30:31], 0, s[100:101]
	v_lshl_add_u64 v[32:33], v[32:33], 0, s[100:101]
	v_lshl_add_u64 v[34:35], v[34:35], 0, s[100:101]
	global_load_dword v46, v[20:21], off nt
	global_load_dword v47, v[22:23], off nt
	global_load_dword v48, v[24:25], off nt
	global_load_dword v49, v[26:27], off nt
	global_load_dword v50, v[28:29], off nt
	global_load_dword v51, v[30:31], off nt
	global_load_dword v52, v[32:33], off nt
	global_load_dword v53, v[34:35], off nt
	v_lshl_add_u64 v[20:21], v[20:21], 0, s[100:101]
	v_lshl_add_u64 v[22:23], v[22:23], 0, s[100:101]
	v_lshl_add_u64 v[24:25], v[24:25], 0, s[100:101]
	v_lshl_add_u64 v[26:27], v[26:27], 0, s[100:101]
	v_lshl_add_u64 v[28:29], v[28:29], 0, s[100:101]
	v_lshl_add_u64 v[30:31], v[30:31], 0, s[100:101]
	v_lshl_add_u64 v[32:33], v[32:33], 0, s[100:101]
	v_lshl_add_u64 v[34:35], v[34:35], 0, s[100:101]
	global_load_dword v54, v[20:21], off nt
	global_load_dword v55, v[22:23], off nt
	global_load_dword v56, v[24:25], off nt
	global_load_dword v57, v[26:27], off nt
	global_load_dword v70, v[28:29], off nt
	global_load_dword v71, v[30:31], off nt
	global_load_dword v72, v[32:33], off nt
	global_load_dword v73, v[34:35], off nt
	v_lshl_add_u64 v[20:21], v[20:21], 0, s[100:101]
	v_lshl_add_u64 v[22:23], v[22:23], 0, s[100:101]
	v_lshl_add_u64 v[24:25], v[24:25], 0, s[100:101]
	v_lshl_add_u64 v[26:27], v[26:27], 0, s[100:101]
	v_lshl_add_u64 v[28:29], v[28:29], 0, s[100:101]
	v_lshl_add_u64 v[30:31], v[30:31], 0, s[100:101]
	v_lshl_add_u64 v[32:33], v[32:33], 0, s[100:101]
	v_lshl_add_u64 v[34:35], v[34:35], 0, s[100:101]
	global_load_dword v74, v[20:21], off nt
	global_load_dword v75, v[22:23], off nt
	global_load_dword v76, v[24:25], off nt
	global_load_dword v77, v[26:27], off nt
	global_load_dword v78, v[28:29], off nt
	global_load_dword v79, v[30:31], off nt
	global_load_dword v80, v[32:33], off nt
	global_load_dword v81, v[34:35], off nt
.Lbw4_none:
	v_writelane_b32 v255, s41, 60
	s_nop 0
	v_readlane_b32 s38, v255, 61
	s_cmp_lg_u32 s38, 0
	s_barrier
	s_nop 0
	v_or_b32_e32 v0, s0, v200
	v_cmp_eq_u32_e32 vcc, 0, v0
	s_and_saveexec_b64 s[34:35], vcc
	s_mov_b32 s52, 0x10000
	s_cbranch_execz .LBB0_811
	v_readlane_b32 s4, v251, 0
	v_readlane_b32 s6, v251, 2
	v_readlane_b32 s7, v251, 3
	s_mov_b64 s[36:37], s[6:7]
	v_readlane_b32 s0, v251, 28
	v_readlane_b32 s2, v253, 7
	s_waitcnt vmcnt(0) lgkmcnt(0)
	v_readlane_b32 s5, v251, 1
	s_nop 0
	v_mov_b32_e32 v0, s2
	ds_read_b32 v2, v0
	v_readlane_b32 s2, v253, 8
	s_waitcnt lgkmcnt(0)
	v_cmp_ne_u32_e32 vcc, 0, v2
	v_mov_b32_e32 v0, s2
	ds_read_b32 v0, v0
	s_cbranch_vccnz .LBB0_781
	s_add_u32 s2, s36, 0x1000
	s_addc_u32 s3, s37, 0
	s_add_u32 s4, s36, 0x1100
	s_addc_u32 s5, s37, 0
	s_add_u32 s6, s36, 0x1200
	s_addc_u32 s7, s37, 0
	s_add_u32 s8, s36, 0x1300
	s_addc_u32 s9, s37, 0
	s_mov_b32 s28, 1
	s_mov_b64 s[10:11], 0
	s_branch .LBB0_767

; #define WAVE_LDS_SYNC() do { int _z = 0; (void)emu::wave_xchg(&_z, 4); } while (0)
; #define LAS __attribute__((address_space(3)))
; #define WAVE_LDS_SYNC() asm volatile("s_waitcnt lgkmcnt(0)" ::: "memory")
; #define NT_LOAD(p) __builtin_nontemporal_load(p)
; #define NT_STORE(v, p) __builtin_nontemporal_store((v), (p))
; DEV unsigned pk2(float lo, float hi) { return f2bf(lo) | (f2bf(hi) << 16); }
; DEV unsigned pk2(float lo, float hi) { const f32x2n_t v = {lo, hi}; return __builtin_bit_cast(unsigned, __builtin_convertvector(v, bf16x2n_t)); }
; DEV void tr_item(const float* W, int ldw, int col0, int k0, bf16_t* WT, int K, int row0, LAS float* scr, int lane) {
;     ...
;     for (int i = 0; i < 32; ++i) { const int kk = 2 * i + (lane >> 5); scr[kk * 33 + (lane & 31)] = NT_LOAD(&W[(size_t)(k0 + kk) * ldw + col0 + (lane & 31)]); }
;     WAVE_LDS_SYNC();
;     const int c = lane & 7;
; #pragma unroll
;     for (int j = 0; j < 4; ++j) { const int n = (lane >> 3) + 8 * j; const LAS float* s = scr + (8 * c) * 33 + n;
;         u32x4 o; o.x = pk2(s[0 * 33], s[1 * 33]); o.y = pk2(s[2 * 33], s[3 * 33]); o.z = pk2(s[4 * 33], s[5 * 33]); o.w = pk2(s[6 * 33], s[7 * 33]);
;         NT_STORE(o, (u32x4*)(WT + (size_t)(row0 + n) * K + k0 + 8 * c)); }
;     WAVE_LDS_SYNC();
;     const Frame F = refresh(F0);
;     const int odd = l & 1; const int nlin = B_ * (odd ? 4 : 8) * 2 * 4; const int ns5 = odd ? B_ * 2 * 32 : 0;
;     const int vcu = (F.G % 8 == 0) ? (F.bid % 8) * (F.G / 8) + F.bid / 8 : F.bid;
;     if (!odd || F.G <= nlin) {
;         for (int it = vcu; it < nlin + ns5; it += F.G) {
;             if (it < nlin) { if (mode != 2) seq_linear_item(F, l, it, mode >= 10 ? mode - 10 : 0); } else if (mode != 1 && mode < 10) seq_s5_item(F, l, it - nlin, 1);
;             __syncthreads();
;         }
;     } else if (vcu < nlin) { if (mode != 2) seq_linear_item(F, l, vcu, mode >= 10 ? mode - 10 : 0); }
.LBB0_811:
	s_or_b64 exec, exec, s[34:35]
	v_readlane_b32 s62, v251, 29
	v_readlane_b32 s4, v251, 0
	s_waitcnt lgkmcnt(0)
	s_barrier
	s_cselect_b32 s38, 1, 0
	v_writelane_b32 v255, s38, 61
	s_nop 0
	v_readlane_b32 s40, v255, 60
	s_cmp_eq_u32 s40, 0
	s_cbranch_scc1 .Lbw4_skip
	s_lshr_b32 s41, s40, 16
	s_and_b32 s40, s40, 0xffff
	s_and_b32 s38, s40, 0x7ff
	s_lshr_b32 s39, s38, 7
	s_and_b32 s38, s38, 0x7f
	s_lshl_b32 s42, s38, 16
	s_lshl_b32 s39, s39, 7
	s_add_i32 s42, s42, s39
	s_lshr_b32 s39, s40, 11
	s_lshl_b32 s39, s39, 23
	s_add_i32 s42, s42, s39
	s_lshl_b32 s39, s41, 27
	s_add_u32 s42, s42, s39
	s_add_u32 s42, s42, 0x2bc8000
	v_readlane_b32 s100, v255, 53
	v_readlane_b32 s101, v255, 54
	s_add_u32 s42, s100, s42
	s_addc_u32 s43, s101, 0
	v_readlane_b32 s39, v251, 29
	s_lshl_b32 s39, s39, 14
	v_and_b32_e32 v141, 31, v200
	v_lshrrev_b32_e32 v142, 5, v200
	v_mul_u32_u24_e32 v142, 33, v142
	v_add_u32_e32 v142, v142, v141
	v_lshl_add_u32 v132, v142, 2, s39
	v_add_u32_e32 v133, 0x400, v132
	v_add_u32_e32 v134, 0x840, v132
	v_add_u32_e32 v135, 0xc40, v132
	v_add_u32_e32 v136, 0x1080, v132
	v_add_u32_e32 v137, 0x1480, v132
	v_add_u32_e32 v138, 0x18c0, v132
	v_add_u32_e32 v139, 0x1cc0, v132
	v_and_b32_e32 v141, 7, v200
	v_lshrrev_b32_e32 v142, 3, v200
	v_mul_u32_u24_e32 v143, 0x108, v141
	v_add_u32_e32 v143, v143, v142
	v_lshl_add_u32 v140, v143, 2, s39
	v_lshlrev_b32_e32 v141, 4, v141
	v_lshl_add_u32 v36, v142, 11, v141
	v_mov_b32_e32 v37, 0
	s_mov_b64 s[100:101], 0x4000
	v_lshl_add_u64 v[20:21], s[42:43], 0, v[36:37]
	v_lshl_add_u64 v[22:23], v[20:21], 0, s[100:101]
	v_lshl_add_u64 v[24:25], v[22:23], 0, s[100:101]
	v_lshl_add_u64 v[26:27], v[24:25], 0, s[100:101]
	s_waitcnt vmcnt(0)
	ds_write2_b32 v132, v38, v39 offset1:66
	ds_write2_b32 v132, v40, v41 offset0:132 offset1:198
	ds_write2_b32 v133, v42, v43 offset0:8 offset1:74
	ds_write2_b32 v133, v44, v45 offset0:140 offset1:206
	ds_write2_b32 v134, v46, v47 offset1:66
	ds_write2_b32 v134, v48, v49 offset0:132 offset1:198
	ds_write2_b32 v135, v50, v51 offset0:8 offset1:74
	ds_write2_b32 v135, v52, v53 offset0:140 offset1:206
	ds_write2_b32 v136, v54, v55 offset1:66
	ds_write2_b32 v136, v56, v57 offset0:132 offset1:198
	ds_write2_b32 v137, v70, v71 offset0:8 offset1:74
	ds_write2_b32 v137, v72, v73 offset0:140 offset1:206
	ds_write2_b32 v138, v74, v75 offset1:66
	ds_write2_b32 v138, v76, v77 offset0:132 offset1:198
	ds_write2_b32 v139, v78, v79 offset0:8 offset1:74
	ds_write2_b32 v139, v80, v81 offset0:140 offset1:206
	ds_read2_b32 v[82:83], v140 offset1:8
	ds_read2_b32 v[84:85], v140 offset0:33 offset1:41
	ds_read2_b32 v[86:87], v140 offset0:66 offset1:74
	ds_read2_b32 v[88:89], v140 offset0:99 offset1:107
	ds_read2_b32 v[90:91], v140 offset0:132 offset1:140
	ds_read2_b32 v[92:93], v140 offset0:165 offset1:173
	ds_read2_b32 v[94:95], v140 offset0:198 offset1:206
	ds_read2_b32 v[96:97], v140 offset0:231 offset1:239
	ds_read2_b32 v[98:99], v140 offset0:16 offset1:24
	ds_read2_b32 v[100:101], v140 offset0:49 offset1:57
	ds_read2_b32 v[102:103], v140 offset0:82 offset1:90
	ds_read2_b32 v[104:105], v140 offset0:115 offset1:123
	s_waitcnt lgkmcnt(4)
	v_cvt_pk_bf16_f32 v116, v82, v84
	v_cvt_pk_bf16_f32 v117, v86, v88
	v_cvt_pk_bf16_f32 v118, v90, v92
	v_cvt_pk_bf16_f32 v119, v94, v96
	v_cvt_pk_bf16_f32 v120, v83, v85
	v_cvt_pk_bf16_f32 v121, v87, v89
	v_cvt_pk_bf16_f32 v122, v91, v93
	v_cvt_pk_bf16_f32 v123, v95, v97
	ds_read2_b32 v[106:107], v140 offset0:148 offset1:156
	ds_read2_b32 v[110:111], v140 offset0:181 offset1:189
	ds_read2_b32 v[112:113], v140 offset0:214 offset1:222
	ds_read2_b32 v[114:115], v140 offset0:247 offset1:255
	global_store_dwordx4 v[20:21], v[116:119], off nt
	global_store_dwordx4 v[22:23], v[120:123], off nt
	s_waitcnt lgkmcnt(0)
	v_cvt_pk_bf16_f32 v124, v98, v100
	v_cvt_pk_bf16_f32 v125, v102, v104
	v_cvt_pk_bf16_f32 v126, v106, v110
	v_cvt_pk_bf16_f32 v127, v112, v114
	v_cvt_pk_bf16_f32 v128, v99, v101
	v_cvt_pk_bf16_f32 v129, v103, v105
	v_cvt_pk_bf16_f32 v130, v107, v111
	v_cvt_pk_bf16_f32 v131, v113, v115
	global_store_dwordx4 v[24:25], v[124:127], off nt
	global_store_dwordx4 v[26:27], v[128:131], off nt
.Lbw4_skip:
	s_waitcnt lgkmcnt(0)
	s_barrier
	v_readlane_b32 s38, v255, 61
	s_cmp_lg_u32 s38, 0
	v_mov_b32_e32 v82, v200
	s_lshl_b32 s0, s62, 6
	v_readlane_b32 s6, v251, 2
	v_readlane_b32 s7, v251, 3
	v_writelane_b32 v254, s0, 27
	v_add_u32_e32 v84, s0, v82
	s_mov_b64 s[2:3], s[6:7]
	v_readlane_b32 s0, v253, 49
	v_readlane_b32 s5, v251, 1
	s_cmp_lg_u32 s0, 0
	v_writelane_b32 v254, s2, 28
	s_cselect_b64 s[4:5], -1, 0
	s_nop 0
	v_writelane_b32 v254, s3, 29
	s_and_b64 s[2:3], s[4:5], exec
	s_cselect_b32 s69, 0x80, s63
	s_lshl_b32 s0, s0, 8
	v_writelane_b32 v254, s0, 30
	s_cmp_gt_i32 s96, s69
	s_cselect_b64 s[2:3], -1, 0
	v_writelane_b32 v254, s4, 31
	s_nop 1
	v_writelane_b32 v254, s5, 32
	s_and_b64 s[4:5], s[4:5], s[2:3]
	s_mov_b64 s[2:3], -1
	s_and_b64 vcc, exec, s[4:5]
	s_cbranch_vccnz .LBB0_1047
	v_writelane_b32 v254, s62, 33
	v_readlane_b32 s68, v253, 11
	v_readlane_b32 s0, v254, 30
	s_add_i32 s83, s69, s0
	v_readlane_b32 s0, v252, 61
	s_cmp_ge_i32 s0, s83
	v_readlane_b32 s67, v253, 12
	s_movk_i32 s62, 0x67f
	s_cbranch_scc1 .LBB0_1046
; #define LAUNDER(x) do {} while (0)
; #define LAUNDER_S(x) do {} while (0)
; #define LAS __attribute__((address_space(3)))
; template <int KIND>
; DEV void seq_dma(const Frame& F, const SeqCtx& C, int n, LAS unsigned char* img) {
;     const int p = C.chain * NCH + n, w = F.wave; int ln = F.lane; LAUNDER(ln);
;     if (w < 2) {
;         if (KIND == 0) { const GAS char* g = (const GAS char*)(F.ws + WS_CLW) + (size_t)p * 16384; LAUNDER_S(g);
; #pragma unroll
;             for (int i = 0; i < 8; ++i) { const int r = 4 * (8 * w + i) + (ln >> 4), pp = ln & 15; glds16(g + r * 256 + 16 * (pp ^ (r & 15)), img + SQ_W + 1024 * (8 * w + i)); } }
;     } else if (w < 4) {
;         const GAS char* g = (const GAS char*)(F.ws + WS_CLQ) + (size_t)p * 16384; LAUNDER_S(g);
; #pragma unroll
;         for (int i = 0; i < 8; ++i) { const int c = 8 * (w - 2) + i, r = 4 * c + (ln >> 4), pp = ln & 15; glds16(g + r * 256 + 16 * (pp ^ (r & 15)), img + SQ_Q + 1024 * c); }
;     } else if (w < 6) {
;         const GAS char* g = (const GAS char*)(F.ws + WS_CLK) + (size_t)p * 16384; LAUNDER_S(g);
; #pragma unroll
;         for (int i = 0; i < 8; ++i) { const int c = 8 * (w - 4) + i, r = 8 * c + (ln >> 3), pp = ln & 7; glds16(g + r * 128 + 16 * (pp ^ ((r >> 1) & 7)), img + SQ_K + 1024 * c); }
;     } else if (w == 6) {
;         const GAS char* g = (const GAS char*)(F.ws + WS_CLA) + (size_t)p * 8192; LAUNDER_S(g);
; #pragma unroll
;         for (int i = 0; i < 8; ++i) { const int r = 8 * i + (ln >> 3), pp = ln & 7; glds16(g + r * 128 + 16 * (pp ^ ((r >> 1) & 7)), img + SQ_A + 1024 * i); }
;     } else {
;     ...
; #pragma unroll
;             for (int i = 0; i < 4; ++i) { const int r = 16 * i + (ln >> 2); glds16(g + r * 256 + 16 * (ln & 3), img + SQ_U + 1024 * i); }
;         } else { const int r0 = tok_row(C.b, C.d, n * 64); const long st = C.d ? -(long)C.vld * 2 : (long)C.vld * 2;
;             const GAS char* g = (const GAS char*)C.vsrc + (long)r0 * C.vld * 2 + 64 * C.sl; LAUNDER_S(g);
; #pragma unroll
;             for (int i = 0; i < 4; ++i) { const int r = 16 * i + (ln >> 2); glds16(g + (long)r * st + 16 * (ln & 3), img + SQ_U + 1024 * i); }
;         }
;         const GAS char* cs = (const GAS char*)(F.ws + WS_CLS) + (size_t)p * 2048; LAUNDER_S(cs);
;         glds16(cs + 16 * ln, img + SQ_C);
;         if (KIND == 2) glds16(cs + 1024 + 16 * ln, img + SQ_C + 1024);
;     }
; }
	v_readlane_b32 s7, v254, 33
	s_mul_i32 s0, s7, 0x3800
	v_readlane_b32 s2, v253, 62
	s_add_i32 s77, s0, 0
	s_and_b32 s0, s2, 2
	v_writelane_b32 v254, s0, 34
	s_lshl_b32 s0, s2, 4
	s_and_b32 s0, s0, 32
	v_writelane_b32 v254, s0, 35
	v_readlane_b32 s3, v253, 63
	v_readlane_b32 s8, v254, 28
	v_readlane_b32 s9, v254, 29
	s_add_u32 s36, s8, 0x415d4c00
	s_addc_u32 s37, s9, 0
	s_add_u32 s0, s8, 0x40d54c00
	v_writelane_b32 v254, s0, 36
	s_addc_u32 s0, s9, 0
	s_cmpk_lt_i32 s7, 0x44
	v_writelane_b32 v254, s0, 37
	s_cselect_b64 s[2:3], -1, 0
	v_writelane_b32 v254, s2, 38
	s_lshl_b32 s6, s72, 1
	s_add_u32 s0, s8, 0x4a655400
	v_writelane_b32 v254, s3, 39
	v_writelane_b32 v254, s0, 40
	s_addc_u32 s0, s9, 0
	v_writelane_b32 v254, s0, 41
	s_add_u32 s0, s8, 0x415d5400
	v_writelane_b32 v254, s0, 42
	s_addc_u32 s0, s9, 0
	s_cmp_gt_i32 s7, 1
	s_cselect_b64 s[40:41], -1, 0
	s_cmp_lt_u32 s7, 4
	s_cselect_b64 s[42:43], -1, 0
	s_cmp_gt_u32 s7, 3
	s_cselect_b64 s[44:45], -1, 0
	s_cmp_gt_u32 s7, 5
	s_cselect_b64 s[46:47], -1, 0
	s_cmp_lg_u32 s7, 6
	v_writelane_b32 v254, s0, 43
	s_cselect_b64 s[2:3], -1, 0
	s_add_u32 s0, s8, 0x60b54c00
	v_writelane_b32 v254, s0, 44
	s_addc_u32 s0, s9, 0
	v_writelane_b32 v254, s0, 45
	s_add_u32 s0, s8, 0x5a554c00
	v_writelane_b32 v254, s0, 46
	s_addc_u32 s0, s9, 0
	v_writelane_b32 v254, s0, 47
	s_add_u32 s0, s8, 0x56154c00
	v_writelane_b32 v254, s0, 8
	s_addc_u32 s0, s9, 0
	v_writelane_b32 v253, s2, 49
	v_writelane_b32 v254, s0, 2
	s_lshl_b32 s0, s7, 3
	v_writelane_b32 v253, s3, 50
	s_sub_i32 s2, s0, 32
	s_lshl_b32 s3, s2, 3
	v_writelane_b32 v254, s3, 6
	s_lshl_b32 s2, s2, 10
	v_writelane_b32 v254, s2, 13
	s_sub_i32 s2, s0, 31
	s_lshl_b32 s3, s2, 3
	v_writelane_b32 v254, s3, 15
	s_lshl_b32 s2, s2, 10
	v_writelane_b32 v254, s2, 17
	s_sub_i32 s2, s0, 30
	s_lshl_b32 s3, s2, 3
	v_writelane_b32 v254, s3, 19
	s_lshl_b32 s2, s2, 10
	v_writelane_b32 v254, s2, 21
	s_sub_i32 s2, s0, 29
	s_lshl_b32 s3, s2, 3
	v_writelane_b32 v254, s3, 23
	s_lshl_b32 s2, s2, 10
	v_writelane_b32 v254, s2, 25
	s_sub_i32 s2, s0, 28
	s_lshl_b32 s3, s2, 3
	s_lshl_b32 s2, s2, 10
	v_writelane_b32 v253, s2, 51
	s_sub_i32 s2, s0, 27
	v_writelane_b32 v254, s3, 11
	s_lshl_b32 s3, s2, 3
	v_writelane_b32 v254, s3, 10
	s_lshl_b32 s2, s2, 10
	v_writelane_b32 v254, s2, 4
	s_sub_i32 s2, s0, 26
	s_lshl_b32 s3, s2, 3
	s_lshl_b32 s2, s2, 10
	v_writelane_b32 v254, s2, 0
	s_sub_i32 s2, s0, 25
	v_writelane_b32 v253, s3, 60
	s_lshl_b32 s3, s2, 3
	s_lshl_b32 s2, s2, 10
	v_writelane_b32 v253, s3, 56
	s_add_u32 s11, s8, 0x51d54c00
	v_writelane_b32 v253, s2, 58
	s_addc_u32 s12, s9, 0
	s_add_i32 s2, s0, -16
	s_lshl_b32 s13, s2, 2
	s_lshl_b32 s22, s2, 10
	s_add_i32 s2, s0, -15
	s_lshl_b32 s23, s2, 2
	s_lshl_b32 s78, s2, 10
	s_add_i32 s2, s0, -14
	s_lshl_b32 s79, s2, 2
	s_lshl_b32 s38, s2, 10
	s_add_i32 s2, s0, -13
	v_cvt_f32_ubyte0_e32 v0, s72
	s_lshl_b32 s39, s2, 2
	s_lshl_b32 s4, s2, 10
	s_add_i32 s2, s0, -12
	v_rcp_iflag_f32_e32 v0, v0
	s_lshl_b32 s5, s2, 2
	s_lshl_b32 s14, s2, 10
	s_add_i32 s2, s0, -11
	s_lshl_b32 s15, s2, 2
	s_lshl_b32 s16, s2, 10
	s_add_i32 s2, s0, -10
	s_lshl_b32 s17, s2, 2
	s_lshl_b32 s33, s2, 10
	s_add_i32 s2, s0, -9
	v_readlane_b32 s10, v254, 27
	s_lshl_b32 s92, s7, 5
	s_lshl_b32 s74, s2, 2
	s_lshl_b32 s30, s2, 10
	s_add_i32 s31, s68, s10
	s_sub_i32 s90, s92, 64
	s_lshl_b32 s91, s7, 11
	s_and_b32 s2, s7, -2
	v_mul_f32_e32 v0, 0x4f7ffffe, v0
	s_cmp_lg_u32 s2, 2
	v_cvt_u32_f32_e32 v0, v0
	s_cselect_b64 s[50:51], -1, 0
	s_cmp_lt_i32 s7, 4
	s_cselect_b64 s[52:53], -1, 0
	s_add_i32 s87, s92, 0xffffff80
	s_lshl_b32 s2, s87, 1
	s_add_i32 s18, s67, s2
	v_readfirstlane_b32 s3, v0
	v_cvt_f32_ubyte0_e32 v0, s6
	s_add_u32 s2, s8, 0x613d4c00
	v_rcp_iflag_f32_e32 v0, v0
	v_writelane_b32 v254, s2, 48
	s_addc_u32 s2, s9, 0
	v_writelane_b32 v254, s2, 49
	s_add_u32 s2, s8, 0x5c754c00
	v_writelane_b32 v254, s2, 50
	s_addc_u32 s2, s9, 0
	s_add_u32 s19, s8, 0x4d954c00
	v_mul_f32_e32 v0, 0x4f7ffffe, v0
	v_writelane_b32 v254, s2, 51
	s_addc_u32 s20, s9, 0
	s_sub_i32 s2, 0, s72
	v_cvt_u32_f32_e32 v0, v0
	s_mul_i32 s2, s2, s3
	s_mul_hi_u32 s2, s3, s2
	s_add_i32 s2, s3, s2
	v_writelane_b32 v254, s2, 52
	s_sub_i32 s2, 0, s6
	v_readfirstlane_b32 s3, v0
	s_mul_i32 s2, s2, s3
	s_mul_hi_u32 s2, s3, s2
	v_writelane_b32 v254, s6, 53
	s_add_i32 s2, s3, s2
	v_writelane_b32 v254, s2, 54
	s_or_b32 s2, s0, 1
	s_lshl_b32 s21, s2, 2
	s_lshl_b32 s76, s2, 10
	s_or_b32 s2, s0, 2
	s_lshl_b32 s73, s2, 2
	s_lshl_b32 s75, s2, 10
	s_or_b32 s2, s0, 3
	s_lshl_b32 s82, s2, 2
	s_lshl_b32 s48, s2, 10
	s_or_b32 s2, s0, 4
	s_lshl_b32 s49, s2, 2
	s_lshl_b32 s93, s2, 10
	s_or_b32 s2, s0, 5
	s_lshl_b32 s94, s2, 2
	s_lshl_b32 s95, s2, 10
	s_or_b32 s2, s0, 6
	s_or_b32 s0, s0, 7
	s_lshl_b32 s80, s0, 2
	s_lshl_b32 s81, s0, 10
	s_lshl_b32 s0, s90, 2
	v_readlane_b32 s6, v253, 13
	s_add_i32 s0, s6, s0
	s_lshl_b32 s96, s2, 2
	s_lshl_b32 s97, s2, 10
	v_writelane_b32 v253, s0, 55
	s_lshl_b32 s85, s7, 13
	v_readlane_b32 s0, v252, 62
	s_add_u32 s0, s8, s0
	v_readlane_b32 s2, v252, 63
	s_addc_u32 s2, s9, s2
	s_mul_i32 s3, s69, 0xffff7800
	v_ashrrev_i32_e32 v6, 4, v82
; #define WAIT_VM(n) do {} while (0)
; #define LAUNDER(x) do {} while (0)
; #define LAS __attribute__((address_space(3)))
; #define GAS __attribute__((address_space(1)))
; #define WAIT_VM(n) asm volatile("s_waitcnt vmcnt(" #n ")" ::: "memory")
; #define LAUNDER(x) asm volatile("" : "+v"(x))
; template <int KIND>
; DEV void seq_step(const Frame& F, const SeqCtx& C, int n, f32x16& acc, LAS unsigned char* lds) {
;     int lz = F.lane; LAUNDER(lz); const int h = lz >> 5, l31 = lz & 31;
;     LAS unsigned char* img = lds + (n & 1) * SQ_STAGE; LAS unsigned char* nimg = lds + ((n + 1) & 1) * SQ_STAGE;
;     LAS bf16_t* Sb = (LAS bf16_t*)(lds + SQ_SB); LAS bf16_t* Vn = (LAS bf16_t*)(lds + SQ_VN); LAS float* nvec = (LAS float*)(lds + SQ_NV); LAS float* den = (LAS float*)(lds + SQ_DEN);
;     const LAS float* CS = (const LAS float*)(img + SQ_C);
;     if (C.probe != 3) seq_dma<KIND>(F, C, C.probe == 2 ? 0 : (n + 1 < NCH ? n + 1 : NCH - 1), nimg);
;     if (F.wave < 2) {
;         const int mt_ = F.wave;
; #pragma unroll
;         for (int r = 0; r < 16; ++r) acc[r] = bf2f(*(const LAS bf16_t*)(img + SQ_U + (32 * mt_ + 8 * (r >> 2) + 4 * h + (r & 3)) * 64 + 2 * l31));
;     const int odd = l & 1, nhh = odd ? 4 : 8;
;     ...
;     const GAS bf16_t* P = (const GAS bf16_t*)(F.ws + WS_P); const GAS bf16_t* Q = (const GAS bf16_t*)(F.ws + WS_QKV);
;     ...
;     for (int i = F.tid; i < 32 * 136 / 2; i += NTHREADS) ((LAS unsigned*)(F.lds + SQ_SB))[i] = 0u;
;     if (F.tid < 128) ((LAS float*)(F.lds + SQ_NV))[F.tid] = 0.f;
;     __syncthreads();
;     if (C.kind == 0) seq_kind_loop<0>(F, C, F.lds); else if (C.kind == 1) seq_kind_loop<1>(F, C, F.lds); else seq_kind_loop<2>(F, C, F.lds);
;     WAIT_VM(0);
; }
	s_add_u32 s54, s0, s3
	s_mul_hi_i32 s0, s69, 0xffff7800
	v_ashrrev_i32_e32 v83, 31, v82
	v_lshlrev_b32_e32 v92, 3, v6
	s_addc_u32 s55, s2, s0
	v_lshl_add_u64 v[2:3], v[82:83], 2, s[8:9]
	s_mov_b64 s[2:3], 0x32bc8000
	v_ashrrev_i32_e32 v93, 31, v92
	v_and_b32_e32 v86, 15, v82
	v_lshl_add_u64 v[88:89], v[2:3], 0, s[2:3]
	v_lshlrev_b64 v[2:3], 1, v[92:93]
	v_lshl_add_u64 v[4:5], s[8:9], 0, v[2:3]
	s_mov_b64 s[2:3], 0x32bd8000
	v_lshlrev_b32_e32 v0, 8, v86
	v_lshl_add_u64 v[94:95], v[4:5], 0, s[2:3]
	v_lshl_add_u64 v[4:5], s[8:9], 0, v[0:1]
	v_lshl_add_u64 v[2:3], v[4:5], 0, v[2:3]
	v_add_u32_e32 v5, 0xffffff00, v84
	v_and_b32_e32 v7, 3, v82
	s_lshl_b32 s0, s7, 9
	v_ashrrev_i32_e32 v160, 2, v5
	v_lshlrev_b32_e32 v8, 2, v7
	v_lshlrev_b32_e32 v87, 2, v82
	s_add_i32 s0, s0, 0
	s_mov_b64 s[2:3], 0x32c58000
	v_bitop3_b32 v10, v160, v8, 15 bitop3:0x6c
	v_add_u32_e32 v91, s0, v87
	v_lshl_add_u64 v[96:97], v[2:3], 0, s[2:3]
	v_mov_b32_e32 v3, s77
	s_movk_i32 s0, 0x50
	v_lshlrev_b32_e32 v162, 4, v10
	v_or_b32_e32 v10, 1, v8
	v_mad_u32_u24 v3, v86, s0, v3
	v_mul_lo_u32 v4, v82, s0
	v_readlane_b32 s0, v253, 10
	v_bitop3_b32 v10, v160, v10, 15 bitop3:0x6c
	v_lshlrev_b32_e32 v163, 4, v10
	v_lshl_add_u32 v159, v84, 2, s0
	v_or_b32_e32 v10, 2, v8
	s_sub_i32 s0, 0, s10
	v_bitop3_b32 v10, v160, v10, 15 bitop3:0x6c
	v_and_b32_e32 v5, -4, v5
	v_writelane_b32 v254, s0, 55
	s_movk_i32 s0, 0x2200
	v_lshlrev_b32_e32 v164, 4, v10
	v_add_u32_e32 v166, s6, v5
	v_lshl_add_u32 v10, s7, 8, v87
	v_cmp_gt_i32_e64 s[6:7], s0, v84
	v_or_b32_e32 v110, s10, v86
	v_or_b32_e32 v114, 16, v110
	v_writelane_b32 v254, s6, 56
	v_or_b32_e32 v118, 32, v110
	v_or_b32_e32 v122, 48, v110
	v_writelane_b32 v254, s7, 57
	v_cmp_gt_i32_e64 s[6:7], s63, v110
	s_movk_i32 s0, 0x880
	v_max_i32_e32 v5, 0x2000, v84
	v_writelane_b32 v254, s6, 58
	v_or_b32_e32 v8, 3, v8
	v_sub_u32_e32 v5, v5, v84
	v_writelane_b32 v254, s7, 59
	v_cmp_gt_i32_e64 s[6:7], s63, v114
	v_bitop3_b32 v8, v160, v8, 15 bitop3:0x6c
	v_add_u32_e32 v5, 0x1ff, v5
	v_writelane_b32 v254, s6, 60
	v_lshlrev_b32_e32 v165, 4, v8
	v_lshrrev_b32_e32 v8, 9, v5
	v_writelane_b32 v254, s7, 61
	v_cmp_gt_i32_e64 s[6:7], s63, v118
	v_add_u32_e32 v8, 1, v8
	v_and_b32_e32 v168, 0xfffffe, v8
	v_writelane_b32 v254, s6, 62
	v_and_b32_e32 v2, -16, v82
	v_add_u32_e32 v0, s77, v0
	v_writelane_b32 v254, s7, 63
	v_cmp_gt_i32_e64 s[6:7], s63, v122
	v_lshlrev_b32_e32 v83, 2, v6
	v_lshlrev_b32_e32 v9, 7, v7
	v_writelane_b32 v255, s6, 0
	v_or_b32_e32 v127, 1, v83
	v_or_b32_e32 v129, 2, v83
	v_writelane_b32 v255, s7, 1
	v_cmp_gt_i32_e64 s[6:7], s0, v84
	s_movk_i32 s0, 0x80
	v_or_b32_e32 v131, 3, v83
	v_writelane_b32 v255, s6, 2
	v_add_u32_e32 v175, v0, v2
	v_add_u32_e32 v0, 0, v9
	v_writelane_b32 v255, s7, 3
	v_cmp_gt_i32_e64 s[6:7], s0, v84
	s_movk_i32 s0, 0x180
	v_lshlrev_b32_e32 v90, 4, v86
	v_writelane_b32 v255, s6, 4
	v_add_u32_e32 v111, 0xffffff00, v110
	v_sub_u32_e32 v112, 0x10ff, v110
	v_writelane_b32 v255, s7, 5
	v_cmp_eq_u32_e64 s[6:7], 0, v7
	v_sub_u32_e32 v113, 0xff, v110
	v_add_u32_e32 v115, 0xffffff10, v110
	v_writelane_b32 v255, s6, 6
	v_sub_u32_e32 v116, 0x10ff, v114
	v_sub_u32_e32 v117, 0xff, v114
	v_writelane_b32 v255, s7, 7
	v_cmp_gt_i32_e64 s[6:7], s0, v84
	s_movk_i32 s0, 0x1ff
	v_add_u32_e32 v119, 0xffffff20, v110
	v_writelane_b32 v255, s6, 8
	v_sub_u32_e32 v120, 0x10ff, v118
	v_sub_u32_e32 v121, 0xff, v118
	v_writelane_b32 v255, s7, 9
	v_cmp_lt_u32_e64 s[6:7], s0, v5
	v_add_u32_e32 v123, 0xffffff30, v110
	v_sub_u32_e32 v124, 0x10ff, v122
	v_writelane_b32 v255, s6, 10
	v_sub_u32_e32 v125, 0xff, v122
	v_sub_u32_e32 v126, 0, v83
	v_writelane_b32 v255, s7, 11
	v_cmp_ne_u32_e64 s[6:7], v8, v168
	v_sub_u32_e32 v128, 0, v127
	v_sub_u32_e32 v130, 0, v129
	v_writelane_b32 v255, s6, 12
	v_sub_u32_e32 v132, 0, v131
	v_add_u32_e32 v133, 16, v83
	v_writelane_b32 v255, s7, 13
	v_writelane_b32 v255, s69, 14
	v_sub_u32_e32 v134, -16, v83
	v_add_u32_e32 v135, 17, v83
	v_sub_u32_e32 v136, 0xffffffef, v83
	v_add_u32_e32 v137, 18, v83
	v_sub_u32_e32 v138, 0xffffffee, v83
	v_add_u32_e32 v139, 19, v83
	v_sub_u32_e32 v140, 0xffffffed, v83
	v_add_u32_e32 v141, 32, v83
	v_sub_u32_e32 v142, 0xffffffe0, v83
	v_add_u32_e32 v143, 33, v83
	v_sub_u32_e32 v144, 0xffffffdf, v83
	v_add_u32_e32 v145, 34, v83
	v_sub_u32_e32 v147, 0xffffffde, v83
	v_add_u32_e32 v148, 35, v83
	v_sub_u32_e32 v150, 0xffffffdd, v83
	v_add_u32_e32 v151, 48, v83
	v_sub_u32_e32 v152, 0xffffffd0, v83
	v_add_u32_e32 v153, 49, v83
	v_sub_u32_e32 v154, 0xffffffcf, v83
	v_add_u32_e32 v155, 50, v83
	v_sub_u32_e32 v156, 0xffffffce, v83
	v_add_u32_e32 v157, 51, v83
	v_sub_u32_e32 v158, 0xffffffcd, v83
	v_lshlrev_b32_e32 v161, 8, v160
	v_add_u32_e32 v167, 0xfffffc00, v159
	v_lshl_add_u32 v169, v168, 9, v84
	v_add_u32_e32 v85, 0x200, v84
	v_add_u32_e32 v170, 0, v10
	v_add_u32_e32 v171, 0xfffffe00, v84
	v_add_u32_e32 v172, s67, v10
	v_add_u32_e32 v173, v3, v2
	v_add_u32_e32 v174, s77, v4
	v_add_u32_e32 v176, 0x24400, v0
	v_readlane_b32 s86, v252, 61
	v_cmp_gt_i32_e64 s[2:3], 2, v6
	v_writelane_b32 v255, s83, 15
	s_branch .LBB0_817

; #define WAIT_VM(n) do {} while (0)
; #define LAUNDER_S(x) do {} while (0)
; #define WAIT_VM(n) asm volatile("s_waitcnt vmcnt(" #n ")" ::: "memory")
; #define LAUNDER_S(x) asm volatile("" : "+s"(x))
; DEV void xcd_barrier(const XcdBarrier& b) {
;     WAIT_VM(0);
;     __syncthreads();
;     int bw = b.wave; LAUNDER_S(bw);
; DEV void phase_prologue_a(const Frame& F0) {
;     ...
;         constexpr int GU_NB = 2 * FF / 32, GU_ITEMS = 16 * GU_NB;
;         for (int it = F.gw; it < NE * GU_ITEMS; it += F.NGW) { const int e = it / GU_ITEMS, r = it % GU_ITEMS, kb = r / GU_NB, nb = r % GU_NB; const int d0 = 32 * nb, j = d0 >> 8, w = d0 & 255;
;             const float* src = (w < 128 ? GIN(I_WGATE) : GIN(I_WUP)) + ((size_t)l * NE + e) * 1024 * FF;
;             tr_item(src, FF, 128 * j + (w & 127), 64 * kb, (bf16_t*)(F.ws + WS_WGU) + ((size_t)l * NE + e) * 2 * FF * 1024, 1024, d0, scr, F.lane); }
.LBB0_1158:
	s_waitcnt vmcnt(0)
	v_readlane_b32 s0, v251, 29
	s_waitcnt vmcnt(0) lgkmcnt(0)
	s_cselect_b32 s38, 1, 0
	v_writelane_b32 v255, s38, 61
	v_readlane_b32 s38, v255, 59
	s_add_i32 s39, s38, 1
	v_writelane_b32 v255, s39, 59
	s_mov_b32 s41, 0
	v_readlane_b32 s39, v251, 29
	s_cmp_eq_u32 s39, 0
	s_cbranch_scc1 .Lbw5_none
	v_readlane_b32 s40, v255, 51
	s_cmp_lg_u32 s40, 0x100
	s_cbranch_scc1 .Lbw5_none
	v_readlane_b32 s40, v255, 48
	s_mul_i32 s40, s40, 7
	s_mul_i32 s38, s38, 0x700
	s_add_i32 s40, s40, s38
	s_add_i32 s40, s40, s39
	s_add_i32 s40, s40, -1
	s_cmp_lt_u32 s40, 0x11f00
	s_cbranch_scc0 .Lbw5_none
	s_mov_b32 s41, 1
	s_cmp_lt_u32 s40, 0x8000
	s_cbranch_scc1 .Lbw5_have
	s_mov_b32 s41, 2
	s_sub_i32 s40, s40, 0x8000
	s_cmp_lt_u32 s40, 0x5200
	s_cbranch_scc1 .Lbw5_have
	s_mov_b32 s41, 3
	s_sub_i32 s40, s40, 0x5200

; #define LAS __attribute__((address_space(3)))
; #define NT_LOAD(p) __builtin_nontemporal_load(p)
; DEV void tr_item(const float* W, int ldw, int col0, int k0, bf16_t* WT, int K, int row0, LAS float* scr, int lane) {
; #pragma unroll 8
;     for (int i = 0; i < 32; ++i) { const int kk = 2 * i + (lane >> 5); scr[kk * 33 + (lane & 31)] = NT_LOAD(&W[(size_t)(k0 + kk) * ldw + col0 + (lane & 31)]); }
; DEV void phase_prologue_a(const Frame& F0) {
;     ...
;         constexpr int GU_NB = 2 * FF / 32, GU_ITEMS = 16 * GU_NB;
;         for (int it = F.gw; it < NE * GU_ITEMS; it += F.NGW) { const int e = it / GU_ITEMS, r = it % GU_ITEMS, kb = r / GU_NB, nb = r % GU_NB; const int d0 = 32 * nb, j = d0 >> 8, w = d0 & 255;
;             const float* src = (w < 128 ? GIN(I_WGATE) : GIN(I_WUP)) + ((size_t)l * NE + e) * 1024 * FF;
;             tr_item(src, FF, 128 * j + (w & 127), 64 * kb, (bf16_t*)(F.ws + WS_WGU) + ((size_t)l * NE + e) * 2 * FF * 1024, 1024, d0, scr, F.lane); }
.Lbw5_gate:
	s_add_u32 s42, s100, s42
	s_addc_u32 s43, s101, 0
	s_lshl_b32 s39, s41, 16
	s_or_b32 s41, s39, s40
	v_lshrrev_b32_e32 v127, 5, v200
	v_and_b32_e32 v128, 31, v200
	v_lshlrev_b32_e32 v128, 2, v128
	v_lshl_add_u32 v36, v127, 13, v128
	v_mov_b32_e32 v37, 0
	s_mov_b64 s[100:101], 0x4000
	v_lshl_add_u64 v[20:21], s[42:43], 0, v[36:37]
	v_lshl_add_u64 v[22:23], v[20:21], 0, s[100:101]
	v_lshl_add_u64 v[24:25], v[22:23], 0, s[100:101]
	v_lshl_add_u64 v[26:27], v[24:25], 0, s[100:101]
	v_lshl_add_u64 v[28:29], v[26:27], 0, s[100:101]
	v_lshl_add_u64 v[30:31], v[28:29], 0, s[100:101]
	v_lshl_add_u64 v[32:33], v[30:31], 0, s[100:101]
	v_lshl_add_u64 v[34:35], v[32:33], 0, s[100:101]
	s_mov_b64 s[100:101], 0x20000
	global_load_dword v38, v[20:21], off nt
	global_load_dword v39, v[22:23], off nt
	global_load_dword v40, v[24:25], off nt
	global_load_dword v41, v[26:27], off nt
	global_load_dword v42, v[28:29], off nt
	global_load_dword v43, v[30:31], off nt
	global_load_dword v44, v[32:33], off nt
	global_load_dword v45, v[34:35], off nt
	v_lshl_add_u64 v[20:21], v[20:21], 0, s[100:101]
	v_lshl_add_u64 v[22:23], v[22:23], 0, s[100:101]
	v_lshl_add_u64 v[24:25], v[24:25], 0, s[100:101]
	v_lshl_add_u64 v[26:27], v[26:27], 0, s[100:101]
	v_lshl_add_u64 v[28:29], v[28:29], 0, s[100:101]
	v_lshl_add_u64 v[30:31], v[30:31], 0, s[100:101]
	v_lshl_add_u64 v[32:33], v[32:33], 0, s[100:101]
	v_lshl_add_u64 v[34:35], v[34:35], 0, s[100:101]
	global_load_dword v46, v[20:21], off nt
	global_load_dword v47, v[22:23], off nt
	global_load_dword v48, v[24:25], off nt
	global_load_dword v49, v[26:27], off nt
	global_load_dword v50, v[28:29], off nt
	global_load_dword v51, v[30:31], off nt
	global_load_dword v52, v[32:33], off nt
	global_load_dword v53, v[34:35], off nt
	v_lshl_add_u64 v[20:21], v[20:21], 0, s[100:101]
	v_lshl_add_u64 v[22:23], v[22:23], 0, s[100:101]
	v_lshl_add_u64 v[24:25], v[24:25], 0, s[100:101]
	v_lshl_add_u64 v[26:27], v[26:27], 0, s[100:101]
	v_lshl_add_u64 v[28:29], v[28:29], 0, s[100:101]
	v_lshl_add_u64 v[30:31], v[30:31], 0, s[100:101]
	v_lshl_add_u64 v[32:33], v[32:33], 0, s[100:101]
	v_lshl_add_u64 v[34:35], v[34:35], 0, s[100:101]
	global_load_dword v54, v[20:21], off nt
	global_load_dword v55, v[22:23], off nt
	global_load_dword v56, v[24:25], off nt
	global_load_dword v57, v[26:27], off nt
	global_load_dword v58, v[28:29], off nt
	global_load_dword v59, v[30:31], off nt
	global_load_dword v60, v[32:33], off nt
	global_load_dword v61, v[34:35], off nt
	v_lshl_add_u64 v[20:21], v[20:21], 0, s[100:101]
	v_lshl_add_u64 v[22:23], v[22:23], 0, s[100:101]
	v_lshl_add_u64 v[24:25], v[24:25], 0, s[100:101]
	v_lshl_add_u64 v[26:27], v[26:27], 0, s[100:101]
	v_lshl_add_u64 v[28:29], v[28:29], 0, s[100:101]
	v_lshl_add_u64 v[30:31], v[30:31], 0, s[100:101]
	v_lshl_add_u64 v[32:33], v[32:33], 0, s[100:101]
	v_lshl_add_u64 v[34:35], v[34:35], 0, s[100:101]
	global_load_dword v62, v[20:21], off nt
	global_load_dword v63, v[22:23], off nt
	global_load_dword v64, v[24:25], off nt
	global_load_dword v65, v[26:27], off nt
	global_load_dword v66, v[28:29], off nt
	global_load_dword v67, v[30:31], off nt
	global_load_dword v68, v[32:33], off nt
	global_load_dword v69, v[34:35], off nt

; #define WAVE_LDS_SYNC() do { int _z = 0; (void)emu::wave_xchg(&_z, 4); } while (0)
; #define LAS __attribute__((address_space(3)))
; #define WAVE_LDS_SYNC() asm volatile("s_waitcnt lgkmcnt(0)" ::: "memory")
; #define NT_LOAD(p) __builtin_nontemporal_load(p)
; #define NT_STORE(v, p) __builtin_nontemporal_store((v), (p))
; DEV unsigned pk2(float lo, float hi) { return f2bf(lo) | (f2bf(hi) << 16); }
; DEV unsigned pk2(float lo, float hi) { const f32x2n_t v = {lo, hi}; return __builtin_bit_cast(unsigned, __builtin_convertvector(v, bf16x2n_t)); }
; DEV void tr_item(const float* W, int ldw, int col0, int k0, bf16_t* WT, int K, int row0, LAS float* scr, int lane) {
; #pragma unroll 8
;     for (int i = 0; i < 32; ++i) { const int kk = 2 * i + (lane >> 5); scr[kk * 33 + (lane & 31)] = NT_LOAD(&W[(size_t)(k0 + kk) * ldw + col0 + (lane & 31)]); }
;     WAVE_LDS_SYNC();
;     const int c = lane & 7;
; #pragma unroll
;     for (int j = 0; j < 4; ++j) { const int n = (lane >> 3) + 8 * j; const LAS float* s = scr + (8 * c) * 33 + n;
;         u32x4 o; o.x = pk2(s[0 * 33], s[1 * 33]); o.y = pk2(s[2 * 33], s[3 * 33]); o.z = pk2(s[4 * 33], s[5 * 33]); o.w = pk2(s[6 * 33], s[7 * 33]);
;         NT_STORE(o, (u32x4*)(WT + (size_t)(row0 + n) * K + k0 + 8 * c)); }
;     WAVE_LDS_SYNC();
.LBB0_1202:
	s_or_b64 exec, exec, s[34:35]
	v_readlane_b32 s4, v251, 0
	v_readlane_b32 s0, v251, 29
	v_readlane_b32 s2, v251, 30
	v_readlane_b32 s5, v251, 1
	s_waitcnt lgkmcnt(0)
	s_barrier
	s_cselect_b32 s38, 1, 0
	v_writelane_b32 v255, s38, 61
	s_nop 0
	v_readlane_b32 s40, v255, 60
	s_cmp_eq_u32 s40, 0
	s_cbranch_scc1 .Lbw5_skip
	s_lshr_b32 s41, s40, 16
	s_and_b32 s40, s40, 0xffff
	s_and_b32 s38, s40, 0x7ff
	s_lshr_b32 s39, s38, 7
	s_and_b32 s38, s38, 0x7f
	s_lshl_b32 s42, s38, 16
	s_lshl_b32 s39, s39, 7
	s_add_i32 s42, s42, s39
	s_lshr_b32 s39, s40, 11
	s_lshl_b32 s39, s39, 23
	s_add_i32 s42, s42, s39
	s_lshl_b32 s39, s41, 27
	s_add_u32 s42, s42, s39
	s_add_u32 s42, s42, 0x2bc8000
	v_readlane_b32 s100, v255, 53
	v_readlane_b32 s101, v255, 54
	s_add_u32 s42, s100, s42
	s_addc_u32 s43, s101, 0
	v_readlane_b32 s39, v251, 29
	s_lshl_b32 s39, s39, 14
	v_and_b32_e32 v127, 31, v200
	v_lshrrev_b32_e32 v128, 5, v200
	v_mul_u32_u24_e32 v128, 33, v128
	v_add_u32_e32 v128, v128, v127
	v_lshl_add_u32 v118, v128, 2, s39
	v_add_u32_e32 v119, 0x400, v118
	v_add_u32_e32 v120, 0x840, v118
	v_add_u32_e32 v121, 0xc40, v118
	v_add_u32_e32 v122, 0x1080, v118
	v_add_u32_e32 v123, 0x1480, v118
	v_add_u32_e32 v124, 0x18c0, v118
	v_add_u32_e32 v125, 0x1cc0, v118
	v_and_b32_e32 v127, 7, v200
	v_lshrrev_b32_e32 v128, 3, v200
	v_mul_u32_u24_e32 v129, 0x108, v127
	v_add_u32_e32 v129, v129, v128
	v_lshl_add_u32 v126, v129, 2, s39
	v_lshlrev_b32_e32 v127, 4, v127
	v_lshl_add_u32 v36, v128, 11, v127
	v_mov_b32_e32 v37, 0
	s_mov_b64 s[100:101], 0x4000
	v_lshl_add_u64 v[20:21], s[42:43], 0, v[36:37]
	v_lshl_add_u64 v[22:23], v[20:21], 0, s[100:101]
	v_lshl_add_u64 v[24:25], v[22:23], 0, s[100:101]
	v_lshl_add_u64 v[26:27], v[24:25], 0, s[100:101]
	s_waitcnt vmcnt(0)
	ds_write2_b32 v118, v38, v39 offset1:66
	ds_write2_b32 v118, v40, v41 offset0:132 offset1:198
	ds_write2_b32 v119, v42, v43 offset0:8 offset1:74
	ds_write2_b32 v119, v44, v45 offset0:140 offset1:206
	ds_write2_b32 v120, v46, v47 offset1:66
	ds_write2_b32 v120, v48, v49 offset0:132 offset1:198
	ds_write2_b32 v121, v50, v51 offset0:8 offset1:74
	ds_write2_b32 v121, v52, v53 offset0:140 offset1:206
	ds_write2_b32 v122, v54, v55 offset1:66
	ds_write2_b32 v122, v56, v57 offset0:132 offset1:198
	ds_write2_b32 v123, v58, v59 offset0:8 offset1:74
	ds_write2_b32 v123, v60, v61 offset0:140 offset1:206
	ds_write2_b32 v124, v62, v63 offset1:66
	ds_write2_b32 v124, v64, v65 offset0:132 offset1:198
	ds_write2_b32 v125, v66, v67 offset0:8 offset1:74
	ds_write2_b32 v125, v68, v69 offset0:140 offset1:206
	ds_read2_b32 v[70:71], v126 offset1:8
	ds_read2_b32 v[72:73], v126 offset0:33 offset1:41
	ds_read2_b32 v[74:75], v126 offset0:66 offset1:74
	ds_read2_b32 v[76:77], v126 offset0:99 offset1:107
	ds_read2_b32 v[78:79], v126 offset0:132 offset1:140
	ds_read2_b32 v[80:81], v126 offset0:165 offset1:173
	ds_read2_b32 v[82:83], v126 offset0:198 offset1:206
	ds_read2_b32 v[84:85], v126 offset0:231 offset1:239
	ds_read2_b32 v[86:87], v126 offset0:16 offset1:24
	ds_read2_b32 v[88:89], v126 offset0:49 offset1:57
	ds_read2_b32 v[90:91], v126 offset0:82 offset1:90
	ds_read2_b32 v[92:93], v126 offset0:115 offset1:123
	s_waitcnt lgkmcnt(4)
	v_cvt_pk_bf16_f32 v102, v70, v72
	v_cvt_pk_bf16_f32 v103, v74, v76
	v_cvt_pk_bf16_f32 v104, v78, v80
	v_cvt_pk_bf16_f32 v105, v82, v84
	v_cvt_pk_bf16_f32 v106, v71, v73
	v_cvt_pk_bf16_f32 v107, v75, v77
	v_cvt_pk_bf16_f32 v108, v79, v81
	v_cvt_pk_bf16_f32 v109, v83, v85
	ds_read2_b32 v[94:95], v126 offset0:148 offset1:156
	ds_read2_b32 v[96:97], v126 offset0:181 offset1:189
	ds_read2_b32 v[98:99], v126 offset0:214 offset1:222
	ds_read2_b32 v[100:101], v126 offset0:247 offset1:255
	global_store_dwordx4 v[20:21], v[102:105], off nt
	global_store_dwordx4 v[22:23], v[106:109], off nt
	s_waitcnt lgkmcnt(0)
	v_cvt_pk_bf16_f32 v110, v86, v88
	v_cvt_pk_bf16_f32 v111, v90, v92
	v_cvt_pk_bf16_f32 v112, v94, v96
	v_cvt_pk_bf16_f32 v113, v98, v100
	v_cvt_pk_bf16_f32 v114, v87, v89
	v_cvt_pk_bf16_f32 v115, v91, v93
	v_cvt_pk_bf16_f32 v116, v95, v97
	v_cvt_pk_bf16_f32 v117, v99, v101
	global_store_dwordx4 v[24:25], v[110:113], off nt
	global_store_dwordx4 v[26:27], v[114:117], off nt
; #define ROW_LOOP_SPREAD(r, NROWS) for (int _it = 0, _nf = (NROWS) / F.NGW, r = (_nf > 0 ? F.gw : F.wave * F.G + F.bid); _it <= _nf && r < (NROWS); ++_it, r = _it * F.NGW + (_it < _nf ? F.gw : F.wave * F.G + F.bid))
; DEV void phase_merge(const Frame& F0, int l) {
;     const Frame F = refresh(F0);
;     const int odd = l & 1, li = l >> 1; const bf16_t* P = (const bf16_t*)(F.ws + WS_P);
;     const bf16_t* O0 = (const bf16_t*)(F.ws + WS_O); const bf16_t* O1 = O0 + (size_t)MROWS * 1024;
;     bf16_t* MG = (bf16_t*)(F.ws + WS_MERGED);
;     const int nrows = (l == DEPTH - 1) ? LATR : MROWS;
;     ROW_LOOP_SPREAD(r, nrows) {
;         if (!odd) {
;             const int c0 = 16 * F.lane; float v[16];
; #pragma unroll
;             for (int q = 0; q < 4; ++q) { const u32x2 a = *(const u32x2*)(O0 + (size_t)r * 1024 + c0 + 4 * q), bq = *(const u32x2*)(O1 + (size_t)r * 1024 + c0 + 4 * q);
.Lbw5_skip:
	s_waitcnt lgkmcnt(0)
	s_barrier
	v_readlane_b32 s38, v255, 61
	s_cmp_lg_u32 s38, 0
	s_add_i32 s14, s0, s2
	v_readlane_b32 s4, v253, 62
	s_cmp_lg_u32 s4, 3
	v_readlane_b32 s5, v253, 63
	s_cselect_b64 s[58:59], -1, 0
	s_cmp_eq_u32 s4, 3
	s_cselect_b64 s[4:5], -1, 0
	v_writelane_b32 v253, s4, 51
	v_readlane_b32 s8, v252, 54
	v_readlane_b32 s6, v251, 2
	v_writelane_b32 v253, s5, 52
	s_and_b64 s[4:5], s[4:5], exec
	s_movk_i32 s4, 0x4400
	s_cselect_b32 s70, 0x4000, s4
	v_readlane_b32 s4, v252, 55
	s_mul_hi_u32 s4, s70, s4
	s_mul_i32 s5, s4, s8
	v_readlane_b32 s7, v251, 3
	s_sub_i32 s5, s70, s5
	s_mov_b64 s[2:3], s[6:7]
	s_add_i32 s6, s4, 1
	s_sub_i32 s7, s5, s8
	s_cmp_ge_u32 s5, s8
	s_cselect_b32 s4, s6, s4
	s_cselect_b32 s5, s7, s5
	s_add_i32 s6, s4, 1
	s_cmp_ge_u32 s5, s8
	s_cselect_b32 s4, s6, s4
	s_xor_b32 s4, s4, s55
	s_mul_i32 s16, s0, s96
	s_sub_i32 s15, s4, s55
	s_add_i32 s16, s16, s95
	s_cmp_gt_i32 s15, 0
	s_cselect_b32 s8, s14, s16
	s_cmp_gt_i32 s15, -1
	s_cselect_b64 s[4:5], -1, 0
	s_cmp_lt_i32 s8, s70
	s_cselect_b64 s[6:7], -1, 0
	s_and_b64 s[4:5], s[4:5], s[6:7]
	v_mov_b32_e32 v2, v200
	s_andn2_b64 vcc, exec, s[4:5]
	s_cbranch_vccnz .LBB0_1209
	v_lshlrev_b32_e32 v34, 3, v2
	s_add_u32 s6, s2, 0x415d4c00
	v_readlane_b32 s4, v253, 62
	v_ashrrev_i32_e32 v35, 31, v34
	s_addc_u32 s7, s3, 0
	s_lshr_b32 s4, s4, 1
	v_lshl_add_u64 v[4:5], v[34:35], 1, s[2:3]
	s_mov_b64 s[2:3], 0x613d4c00
	v_lshl_add_u64 v[36:37], v[4:5], 0, s[2:3]
	s_mov_b64 s[2:3], 0x635d4c00
	s_lshl_b32 s0, s4, 9
	v_readlane_b32 s36, v251, 31
	v_lshl_add_u64 v[38:39], v[4:5], 0, s[2:3]
	s_mov_b64 s[2:3], 0x393a8800
	v_ashrrev_i32_e32 v3, 31, v2
	s_lshl_b32 s4, s4, 7
	s_lshl_b64 s[10:11], s[0:1], 2
	v_readlane_b32 s38, v251, 33
	v_readlane_b32 s20, v251, 4
	v_lshl_add_u64 v[40:41], v[4:5], 0, s[2:3]
	v_lshlrev_b64 v[6:7], 4, v[2:3]
	v_readlane_b32 s39, v251, 34
	s_add_u32 s12, s38, s10
	v_readlane_b32 s22, v251, 6
	v_readlane_b32 s23, v251, 7
	v_readlane_b32 s5, v253, 63
	s_mov_b64 s[2:3], 0x3b5a8800
	v_lshl_add_u64 v[44:45], v[36:37], 0, v[6:7]
	v_lshl_add_u64 v[46:47], v[38:39], 0, v[6:7]
	v_lshl_add_u64 v[50:51], v[40:41], 0, v[6:7]
	v_readlane_b32 s37, v251, 32
	v_readlane_b32 s40, v251, 35
	v_readlane_b32 s41, v251, 36
	v_readlane_b32 s42, v251, 37
	v_readlane_b32 s43, v251, 38
	v_readlane_b32 s44, v251, 39
	v_readlane_b32 s45, v251, 40
	v_readlane_b32 s46, v251, 41
	v_readlane_b32 s47, v251, 42
	v_readlane_b32 s48, v251, 43
	v_readlane_b32 s49, v251, 44
	v_readlane_b32 s50, v251, 45
	v_readlane_b32 s51, v251, 46
	s_addc_u32 s13, s39, s11
	v_lshlrev_b64 v[6:7], 2, v[34:35]
	s_mov_b64 s[18:19], s[22:23]
	v_lshl_add_u64 v[42:43], v[4:5], 0, s[2:3]
	v_cmp_lt_i32_e64 s[2:3], 31, v2
	v_mov_b32_e32 v0, 0x600
	v_mov_b32_e32 v3, 0xc00
	s_mov_b32 s5, s1
	v_lshl_add_u64 v[52:53], s[12:13], 0, v[6:7]
	s_add_u32 s12, s18, s10
	v_readlane_b32 s36, v251, 12
	v_lshlrev_b32_e32 v4, 4, v2
	v_cndmask_b32_e64 v0, v0, v3, s[2:3]
	s_addc_u32 s13, s19, s11
	s_lshl_b64 s[4:5], s[4:5], 2
	v_readlane_b32 s42, v251, 18
	v_add_u32_e32 v8, v0, v4
	v_readlane_b32 s43, v251, 19
	s_add_u32 s4, s42, s4
	v_lshlrev_b32_e32 v0, 6, v2
	v_readlane_b32 s44, v251, 20
	s_addc_u32 s5, s43, s5
	v_and_b32_e32 v2, 0x1c0, v0
	v_mov_b32_e32 v3, v1
	v_readlane_b32 s45, v251, 21
	v_lshl_add_u64 v[2:3], s[4:5], 0, v[2:3]
	s_add_u32 s4, s44, s10
	v_mov_b32_e32 v5, v1
	s_addc_u32 s5, s45, s11
	v_lshl_add_u64 v[4:5], v[4:5], 2, s[4:5]
	s_movk_i32 s4, 0xf800
	s_mov_b32 s5, -1
	v_ashrrev_i32_e32 v9, 31, v8
	v_lshl_add_u64 v[4:5], v[4:5], 0, s[4:5]
	v_lshl_add_u64 v[48:49], v[8:9], 1, s[6:7]
	v_lshl_add_u64 v[54:55], s[12:13], 0, v[6:7]
	v_cndmask_b32_e64 v57, v3, v5, s[2:3]
	v_cndmask_b32_e64 v56, v2, v4, s[2:3]
	s_mov_b32 s17, 0
	s_mov_b32 s0, s54
	v_readlane_b32 s21, v251, 5
	v_readlane_b32 s24, v251, 8
	v_readlane_b32 s25, v251, 9
	v_readlane_b32 s26, v251, 10
	v_readlane_b32 s27, v251, 11
	v_readlane_b32 s37, v251, 13
	v_readlane_b32 s38, v251, 14
	v_readlane_b32 s39, v251, 15
	v_readlane_b32 s40, v251, 16
	v_readlane_b32 s41, v251, 17
	v_readlane_b32 s46, v251, 22
	v_readlane_b32 s47, v251, 23
	v_readlane_b32 s48, v251, 24
	v_readlane_b32 s49, v251, 25
	v_readlane_b32 s50, v251, 26
	v_readlane_b32 s51, v251, 27
	s_branch .LBB0_1205

; #define WAVE_LDS_SYNC() do { int _z = 0; (void)emu::wave_xchg(&_z, 4); } while (0)
; #define LAS __attribute__((address_space(3)))
; #define WAVE_LDS_SYNC() asm volatile("s_waitcnt lgkmcnt(0)" ::: "memory")
; #define NT_LOAD(p) __builtin_nontemporal_load(p)
; #define NT_STORE(v, p) __builtin_nontemporal_store((v), (p))
; DEV unsigned pk2(float lo, float hi) { return f2bf(lo) | (f2bf(hi) << 16); }
; DEV unsigned pk2(float lo, float hi) { const f32x2n_t v = {lo, hi}; return __builtin_bit_cast(unsigned, __builtin_convertvector(v, bf16x2n_t)); }
; DEV void tr_item(const float* W, int ldw, int col0, int k0, bf16_t* WT, int K, int row0, LAS float* scr, int lane) {
; #pragma unroll 8
;     for (int i = 0; i < 32; ++i) { const int kk = 2 * i + (lane >> 5); scr[kk * 33 + (lane & 31)] = NT_LOAD(&W[(size_t)(k0 + kk) * ldw + col0 + (lane & 31)]); }
;     WAVE_LDS_SYNC();
;     const int c = lane & 7;
; #pragma unroll
;     for (int j = 0; j < 4; ++j) { const int n = (lane >> 3) + 8 * j; const LAS float* s = scr + (8 * c) * 33 + n;
;         u32x4 o; o.x = pk2(s[0 * 33], s[1 * 33]); o.y = pk2(s[2 * 33], s[3 * 33]); o.z = pk2(s[4 * 33], s[5 * 33]); o.w = pk2(s[6 * 33], s[7 * 33]);
;         NT_STORE(o, (u32x4*)(WT + (size_t)(row0 + n) * K + k0 + 8 * c)); }
;     WAVE_LDS_SYNC();
.LBB0_1253:
	s_or_b64 exec, exec, s[34:35]
	s_mov_b64 s[2:3], -1
	s_and_b64 vcc, exec, s[56:57]
	s_waitcnt lgkmcnt(0)
	s_barrier
	s_cselect_b32 s38, 1, 0
	v_writelane_b32 v255, s38, 61
	s_nop 0
	v_readlane_b32 s40, v255, 60
	s_cmp_eq_u32 s40, 0
	s_cbranch_scc1 .Lbw6_skip
	s_lshr_b32 s41, s40, 16
	s_and_b32 s40, s40, 0xffff
	s_and_b32 s38, s40, 0x7ff
	s_lshr_b32 s39, s38, 7
	s_and_b32 s38, s38, 0x7f
	s_lshl_b32 s42, s38, 16
	s_lshl_b32 s39, s39, 7
	s_add_i32 s42, s42, s39
	s_lshr_b32 s39, s40, 11
	s_lshl_b32 s39, s39, 23
	s_add_i32 s42, s42, s39
	s_lshl_b32 s39, s41, 27
	s_add_u32 s42, s42, s39
	s_add_u32 s42, s42, 0x2bc8000
	v_readlane_b32 s100, v255, 53
	v_readlane_b32 s101, v255, 54
	s_add_u32 s42, s100, s42
	s_addc_u32 s43, s101, 0
	v_readlane_b32 s39, v251, 29
	s_lshl_b32 s39, s39, 14
	v_and_b32_e32 v127, 31, v200
	v_lshrrev_b32_e32 v128, 5, v200
	v_mul_u32_u24_e32 v128, 33, v128
	v_add_u32_e32 v128, v128, v127
	v_lshl_add_u32 v118, v128, 2, s39
	v_add_u32_e32 v119, 0x400, v118
	v_add_u32_e32 v120, 0x840, v118
	v_add_u32_e32 v121, 0xc40, v118
	v_add_u32_e32 v122, 0x1080, v118
	v_add_u32_e32 v123, 0x1480, v118
	v_add_u32_e32 v124, 0x18c0, v118
	v_add_u32_e32 v125, 0x1cc0, v118
	v_and_b32_e32 v127, 7, v200
	v_lshrrev_b32_e32 v128, 3, v200
	v_mul_u32_u24_e32 v129, 0x108, v127
	v_add_u32_e32 v129, v129, v128
	v_lshl_add_u32 v126, v129, 2, s39
	v_lshlrev_b32_e32 v127, 4, v127
	v_lshl_add_u32 v36, v128, 11, v127
	v_mov_b32_e32 v37, 0
	s_mov_b64 s[100:101], 0x4000
	v_lshl_add_u64 v[20:21], s[42:43], 0, v[36:37]
	v_lshl_add_u64 v[22:23], v[20:21], 0, s[100:101]
	v_lshl_add_u64 v[24:25], v[22:23], 0, s[100:101]
	v_lshl_add_u64 v[26:27], v[24:25], 0, s[100:101]
	s_waitcnt vmcnt(0)
	ds_write2_b32 v118, v38, v39 offset1:66
	ds_write2_b32 v118, v40, v41 offset0:132 offset1:198
	ds_write2_b32 v119, v42, v43 offset0:8 offset1:74
	ds_write2_b32 v119, v44, v45 offset0:140 offset1:206
	ds_write2_b32 v120, v46, v47 offset1:66
	ds_write2_b32 v120, v48, v49 offset0:132 offset1:198
	ds_write2_b32 v121, v50, v51 offset0:8 offset1:74
	ds_write2_b32 v121, v52, v53 offset0:140 offset1:206
	ds_write2_b32 v122, v54, v55 offset1:66
	ds_write2_b32 v122, v56, v57 offset0:132 offset1:198
	ds_write2_b32 v123, v58, v59 offset0:8 offset1:74
	ds_write2_b32 v123, v60, v61 offset0:140 offset1:206
	ds_write2_b32 v124, v62, v63 offset1:66
	ds_write2_b32 v124, v64, v65 offset0:132 offset1:198
	ds_write2_b32 v125, v66, v67 offset0:8 offset1:74
	ds_write2_b32 v125, v68, v69 offset0:140 offset1:206
	ds_read2_b32 v[70:71], v126 offset1:8
	ds_read2_b32 v[72:73], v126 offset0:33 offset1:41
	ds_read2_b32 v[74:75], v126 offset0:66 offset1:74
	ds_read2_b32 v[76:77], v126 offset0:99 offset1:107
	ds_read2_b32 v[78:79], v126 offset0:132 offset1:140
	ds_read2_b32 v[80:81], v126 offset0:165 offset1:173
	ds_read2_b32 v[82:83], v126 offset0:198 offset1:206
	ds_read2_b32 v[84:85], v126 offset0:231 offset1:239
	ds_read2_b32 v[86:87], v126 offset0:16 offset1:24
	ds_read2_b32 v[88:89], v126 offset0:49 offset1:57
	ds_read2_b32 v[90:91], v126 offset0:82 offset1:90
	ds_read2_b32 v[92:93], v126 offset0:115 offset1:123
	s_waitcnt lgkmcnt(4)
	v_cvt_pk_bf16_f32 v102, v70, v72
	v_cvt_pk_bf16_f32 v103, v74, v76
	v_cvt_pk_bf16_f32 v104, v78, v80
	v_cvt_pk_bf16_f32 v105, v82, v84
	v_cvt_pk_bf16_f32 v106, v71, v73
	v_cvt_pk_bf16_f32 v107, v75, v77
	v_cvt_pk_bf16_f32 v108, v79, v81
	v_cvt_pk_bf16_f32 v109, v83, v85
	ds_read2_b32 v[94:95], v126 offset0:148 offset1:156
	ds_read2_b32 v[96:97], v126 offset0:181 offset1:189
	ds_read2_b32 v[98:99], v126 offset0:214 offset1:222
	ds_read2_b32 v[100:101], v126 offset0:247 offset1:255
	global_store_dwordx4 v[20:21], v[102:105], off nt
	global_store_dwordx4 v[22:23], v[106:109], off nt
	s_waitcnt lgkmcnt(0)
	v_cvt_pk_bf16_f32 v110, v86, v88
	v_cvt_pk_bf16_f32 v111, v90, v92
	v_cvt_pk_bf16_f32 v112, v94, v96
	v_cvt_pk_bf16_f32 v113, v98, v100
	v_cvt_pk_bf16_f32 v114, v87, v89
	v_cvt_pk_bf16_f32 v115, v91, v93
	v_cvt_pk_bf16_f32 v116, v95, v97
	v_cvt_pk_bf16_f32 v117, v99, v101
	global_store_dwordx4 v[24:25], v[110:113], off nt
	global_store_dwordx4 v[26:27], v[114:117], off nt
; #define S_BARRIER() emu::block_barrier()
; #define WAIT_VM(n) do {} while (0)
; template <class Epi, class Sched>
; DEV void gemm_phase(LAS unsigned char* lds, const int K, const Sched& S, const Epi& E, const int wid, const int lane) {
;     ...
; #pragma unroll
;     for (int i = 0; i < 2; ++i) { int R, C; stage_rc(tid * 16 + i * 8192, R, C); const int Rb = Epi::PERM ? ((R & ~31) + perm32(R & 31)) : R; Ri[i] = R; Ci[i] = C;
;         voffA[i] = (unsigned)(R * K + C) * 2u; voffB[i] = (unsigned)(Rb * K + C) * 2u; }
;     unsigned goffC[2][2] = {{0u, 0u}, {0u, 0u}}, goffN[2][2] = {{0u, 0u}, {0u, 0u}};
;     constexpr int GIDX_OFF = STAGE_BYTES;
;     const size_t kstep = (size_t)(BK * 2);
;     const size_t hstep = (size_t)HALF * K * 2;
;     const unsigned ldsw = (unsigned)wid * 1024u;
;     const int aoff = lds_byte(wr * 64 + fr, fq * 8), boff = lds_byte(wc * 32 + fr, fq * 8);
;     ...
;     Unit cur, nxt; int ui = 0;
;     if (!S.next(0, cur)) return;
;     f32x4 acc[2][2][4][2];
; #pragma unroll
;     for (int a = 0; a < 2; ++a)
; #pragma unroll
;         for (int b = 0; b < 2; ++b)
; #pragma unroll
;             for (int m = 0; m < 4; ++m)
; #pragma unroll
;                 for (int n = 0; n < 2; ++n) acc[a][b][m][n] = (f32x4){0.f, 0.f, 0.f, 0.f};
;     bf16x8 At[4][2], B0[2][2], B1[2][2];
;     const char* cA = cur.A; const char* cB = cur.B;
;     if constexpr (Sched::GATHER_A) {
; #pragma unroll
;         for (int hh = 0; hh < 2; ++hh)
; #pragma unroll
;             for (int i = 0; i < 2; ++i) { goffC[hh][i] = (unsigned)S.gidx[S.idx_base(cur) + hh * HALF + Ri[i]] * (unsigned)(K * 2) + (unsigned)(Ci[i] * 2); goffN[hh][i] = goffC[hh][i]; }
;     }
;     PG8_STAGE(PG8_SB(0, 0), cB, voffB); PG8_STAGE(PG8_SB(0, 1), cB + hstep, voffB); PG8_STAGEA(PG8_SA(0, 0), cA, 0, false); PG8_STAGEA(PG8_SA(0, 1), cA, 1, false);
;     if (wr == 1) S_BARRIER();
;     WAIT_VM(2); S_BARRIER();
; DEV void gemm_glu(const Frame& F0, int l, int vcu) {
;     const Frame F = refresh(F0);
;     const int li = l >> 1;
;     pg8::PlainOrder S; S.init((const void*)(F.ws + WS_YS), (const bf16_t*)(F.ws + WS_WGLU) + (size_t)li * 512 * 512, 512, (l == DEPTH - 1) ? LATPAD : MPAD, 512, F.G, vcu);
;     EpiGlu E; E.MG = (bf16_t*)(F.ws + WS_MERGED); E.YS = (const bf16_t*)(F.ws + WS_YS); E.bias = GIN(I_ODBGLU) + li * 512;
;     pg8::gemm_phase(F.lds, 512, S, E, F.wave, F.lane);
.Lbw6_skip:
	s_waitcnt lgkmcnt(0)
	s_barrier
	v_readlane_b32 s38, v255, 61
	s_cmp_lg_u32 s38, 0
	s_cbranch_vccz .LBB0_1315
	v_readlane_b32 s4, v251, 0
	v_readlane_b32 s5, v251, 1
	v_readlane_b32 s4, v253, 51
	v_readlane_b32 s5, v253, 52
	s_and_b64 s[4:5], s[4:5], exec
	s_cselect_b32 s33, 64, 0x44
	v_readlane_b32 s6, v251, 2
	v_readlane_b32 s7, v251, 3
	s_lshl_b32 s0, s33, 1
	v_readlane_b32 s12, v251, 29
	v_mov_b32_e32 v16, v200
	s_mov_b64 s[2:3], s[6:7]
	s_cmp_ge_i32 s95, s0
	s_cbranch_scc1 .LBB0_1270
	v_readlane_b32 s4, v253, 62
	s_lshr_b32 s10, s4, 1
	v_readlane_b32 s5, v253, 63
	s_add_u32 s4, s2, 0x3b5a8800
	s_addc_u32 s5, s3, 0
	s_lshl_b32 s6, s10, 19
	s_add_u32 s6, s2, s6
	s_addc_u32 s7, s3, 0
	s_add_u32 s30, s6, 0x2ac8000
	s_addc_u32 s31, s7, 0
	s_lshl_b32 s34, s12, 10
	v_lshl_add_u32 v0, v16, 4, s34
	v_add_u32_e32 v2, 0x2000, v0
	v_ashrrev_i32_e32 v3, 31, v2
	v_lshrrev_b32_e32 v3, 22, v3
	v_add_u32_e32 v3, v2, v3
	v_ashrrev_i32_e32 v10, 10, v3
	v_mul_i32_i24_e32 v3, 0x400, v10
	v_sub_u32_e32 v2, v2, v3
	v_lshrrev_b32_e32 v3, 4, v2
	v_bitop3_b32 v2, v3, v2, 32 bitop3:0x6c
	v_ashrrev_i32_e32 v3, 31, v2
	v_lshrrev_b32_e32 v3, 26, v3
	v_add_u32_e32 v3, v2, v3
	v_ashrrev_i32_e32 v11, 6, v3
	v_lshlrev_b32_e32 v4, 3, v10
	v_and_b32_e32 v3, 0xffc0, v3
	v_and_b32_e32 v4, -16, v4
	v_sub_u32_e32 v2, v2, v3
	v_add_u32_e32 v4, v11, v4
	v_lshrrev_b16_e32 v3, 7, v2
	v_and_b32_e32 v5, 3, v11
	s_mov_b32 s6, 0x3fffe0
	v_lshrrev_b32_e32 v6, 2, v4
	v_lshlrev_b32_e32 v7, 1, v4
	v_and_b32_e32 v3, 1, v3
	v_and_or_b32 v5, v4, s6, v5
	v_and_b32_e32 v6, 4, v6
	v_and_b32_e32 v7, 24, v7
	v_add_u16_e32 v2, v2, v3
	v_or3_b32 v5, v5, v6, v7
	v_lshlrev_b32_e32 v6, 5, v10
	v_ashrrev_i16_sdwa v2, v202, sext(v2) dst_sel:DWORD dst_unused:UNUSED_PAD src0_sel:DWORD src1_sel:BYTE_0
	v_and_b32_e32 v6, 32, v6
	v_bfe_i32 v13, v2, 0, 16
	v_add_lshl_u32 v2, v6, v13, 1
	v_lshl_add_u32 v130, v5, 10, v2
	v_lshl_add_u32 v132, v4, 10, v2
	v_ashrrev_i32_e32 v2, 31, v0
	v_lshrrev_b32_e32 v2, 22, v2
	v_add_u32_e32 v2, v0, v2
	v_ashrrev_i32_e32 v12, 10, v2
	v_mul_i32_i24_e32 v2, 0x400, v12
	v_sub_u32_e32 v0, v0, v2
	v_lshrrev_b32_e32 v2, 4, v0
	v_bitop3_b32 v0, v2, v0, 32 bitop3:0x6c
	v_ashrrev_i32_e32 v2, 31, v0
	v_lshrrev_b32_e32 v2, 26, v2
	v_add_u32_e32 v2, v0, v2
	v_lshlrev_b32_e32 v3, 3, v12
	v_ashrrev_i32_e32 v14, 6, v2
	v_and_b32_e32 v3, -16, v3
	v_add_u32_e32 v3, v14, v3
	v_and_b32_e32 v4, 3, v14
	v_and_or_b32 v4, v3, s6, v4
	s_lshr_b32 s35, s33, 2
	v_readlane_b32 s6, v252, 24
	s_ashr_i32 s13, s12, 2
	s_add_i32 s36, s35, 1
	v_readlane_b32 s7, v252, 25
	s_and_b64 s[6:7], s[6:7], exec
	s_cselect_b32 s6, s36, s35
	v_readlane_b32 s7, v252, 23
	s_mul_i32 s6, s6, s7
	v_readlane_b32 s7, v252, 21
	s_add_i32 s6, s6, s7
	s_ashr_i32 s7, s6, 31
	s_lshr_b32 s7, s7, 28
	s_add_i32 s7, s6, s7
	v_lshrrev_b32_e32 v5, 2, v3
	v_lshlrev_b32_e32 v6, 1, v3
	v_and_b32_e32 v2, 0xc0, v2
	s_ashr_i32 s8, s7, 4
	v_and_b32_e32 v5, 4, v5
	v_and_b32_e32 v6, 24, v6
	v_sub_u32_e32 v0, v0, v2
	s_lshl_b32 s9, s8, 3
	v_or3_b32 v4, v4, v5, v6
	v_lshlrev_b32_e32 v5, 5, v12
	v_ashrrev_i16_sdwa v0, v202, sext(v0) dst_sel:DWORD dst_unused:UNUSED_PAD src0_sel:DWORD src1_sel:BYTE_0
	s_sub_i32 s8, s33, s9
	v_and_b32_e32 v5, 32, v5
	v_bfe_i32 v15, v0, 0, 16
	s_min_u32 s11, s8, 8
	s_and_b32 s7, s7, -16
	v_add_lshl_u32 v2, v5, v15, 1
	s_sub_i32 s14, s6, s7
	v_cvt_f32_ubyte0_e32 v5, s11
	v_lshl_add_u32 v0, v4, 10, v2
	v_cvt_f32_i32_e32 v4, s14
	v_rcp_iflag_f32_e32 v6, v5
	v_lshl_add_u32 v134, v3, 10, v2
	s_ashr_i32 s6, s14, 30
	s_or_b32 s8, s6, 1
	v_mul_f32_e32 v2, v4, v6
	v_trunc_f32_e32 v2, v2
	v_fma_f32 v3, -v2, v5, v4
	v_cvt_i32_f32_e32 v2, v2
	v_cmp_ge_f32_e64 s[6:7], |v3|, v5
	s_and_b64 s[6:7], s[6:7], exec
	s_cselect_b32 s6, s8, 0
	v_readfirstlane_b32 s7, v2
	s_add_i32 s8, s7, s6
	s_mul_i32 s6, s8, s11
	s_sub_i32 s6, s14, s6
	s_sext_i32_i8 s6, s6
	s_add_i32 s22, s9, s6
	s_ashr_i32 s23, s22, 31
	s_lshl_b64 s[6:7], s[22:23], 18
	s_add_u32 s24, s4, s6
	s_addc_u32 s25, s5, s7
	s_bfe_i64 s[6:7], s[8:9], 0x80000
	s_lshl_b64 s[6:7], s[6:7], 18
	s_add_u32 s26, s30, s6
	s_addc_u32 s27, s31, s7
	s_add_i32 s23, s34, 0
	s_add_i32 m0, s23, 0x10000
	v_add_u32_e32 v136, 0x20000, v134
	global_load_lds_dwordx4 v0, s[26:27]
	s_add_i32 m0, s23, 0x12000
	s_add_u32 s6, s26, 0x20000
	global_load_lds_dwordx4 v130, s[26:27]
	s_addc_u32 s7, s27, 0
	s_add_i32 m0, s23, 0x14000
	s_add_i32 s37, s23, 0x2000
	global_load_lds_dwordx4 v0, s[6:7]
	s_add_i32 m0, s23, 0x16000
	s_add_i32 s38, s23, 0x4000
	global_load_lds_dwordx4 v130, s[6:7]
	s_mov_b32 m0, s23
	s_add_i32 s39, s23, 0x6000
	global_load_lds_dwordx4 v134, s[24:25]
	s_mov_b32 m0, s37
	v_add_u32_e32 v138, 0x20000, v132
	global_load_lds_dwordx4 v132, s[24:25]
	s_mov_b32 m0, s38
	v_mov_b32_e32 v131, v1
	global_load_lds_dwordx4 v136, s[24:25]
	s_mov_b32 m0, s39
	v_mov_b32_e32 v135, v1
	global_load_lds_dwordx4 v138, s[24:25]
	v_mov_b32_e32 v133, v1
	s_cmp_eq_u32 s13, 1
	v_lshl_add_u64 v[8:9], s[26:27], 0, v[0:1]
	v_lshl_add_u64 v[6:7], s[26:27], 0, v[130:131]
	v_lshl_add_u64 v[2:3], s[24:25], 0, v[134:135]
	s_cselect_b64 s[6:7], -1, 0
	s_cmp_lg_u32 s13, 1
	v_lshl_add_u64 v[4:5], s[24:25], 0, v[132:133]
	s_cbranch_scc1 .LBB0_1257
	s_barrier

; #define WAVE_LDS_SYNC() do { int _z = 0; (void)emu::wave_xchg(&_z, 4); } while (0)
; #define LAS __attribute__((address_space(3)))
; #define WAVE_LDS_SYNC() asm volatile("s_waitcnt lgkmcnt(0)" ::: "memory")
; #define NT_LOAD(p) __builtin_nontemporal_load(p)
; #define NT_STORE(v, p) __builtin_nontemporal_store((v), (p))
; DEV unsigned pk2(float lo, float hi) { return f2bf(lo) | (f2bf(hi) << 16); }
; DEV unsigned pk2(float lo, float hi) { const f32x2n_t v = {lo, hi}; return __builtin_bit_cast(unsigned, __builtin_convertvector(v, bf16x2n_t)); }
; DEV void xcd_barrier(const XcdBarrier& b) {
;     ...
;     __syncthreads();
; DEV void tr_item(const float* W, int ldw, int col0, int k0, bf16_t* WT, int K, int row0, LAS float* scr, int lane) {
;     ...
;     for (int i = 0; i < 32; ++i) { const int kk = 2 * i + (lane >> 5); scr[kk * 33 + (lane & 31)] = NT_LOAD(&W[(size_t)(k0 + kk) * ldw + col0 + (lane & 31)]); }
;     WAVE_LDS_SYNC();
;     const int c = lane & 7;
; #pragma unroll
;     for (int j = 0; j < 4; ++j) { const int n = (lane >> 3) + 8 * j; const LAS float* s = scr + (8 * c) * 33 + n;
;         u32x4 o; o.x = pk2(s[0 * 33], s[1 * 33]); o.y = pk2(s[2 * 33], s[3 * 33]); o.z = pk2(s[4 * 33], s[5 * 33]); o.w = pk2(s[6 * 33], s[7 * 33]);
;         NT_STORE(o, (u32x4*)(WT + (size_t)(row0 + n) * K + k0 + 8 * c)); }
;     WAVE_LDS_SYNC();
.LBB0_1314:
	s_or_b64 exec, exec, s[34:35]
	s_mov_b64 s[2:3], 0
	s_waitcnt lgkmcnt(0)
	s_barrier
	s_cselect_b32 s38, 1, 0
	v_writelane_b32 v255, s38, 61
	s_nop 0
	v_readlane_b32 s40, v255, 60
	s_cmp_eq_u32 s40, 0
	s_cbranch_scc1 .Lbw7_skip
	s_lshr_b32 s41, s40, 16
	s_and_b32 s40, s40, 0xffff
	s_and_b32 s38, s40, 0x7ff
	s_lshr_b32 s39, s38, 7
	s_and_b32 s38, s38, 0x7f
	s_lshl_b32 s42, s38, 16
	s_lshl_b32 s39, s39, 7
	s_add_i32 s42, s42, s39
	s_lshr_b32 s39, s40, 11
	s_lshl_b32 s39, s39, 23
	s_add_i32 s42, s42, s39
	s_lshl_b32 s39, s41, 27
	s_add_u32 s42, s42, s39
	s_add_u32 s42, s42, 0x2bc8000
	v_readlane_b32 s100, v255, 53
	v_readlane_b32 s101, v255, 54
	s_add_u32 s42, s100, s42
	s_addc_u32 s43, s101, 0
	v_readlane_b32 s39, v251, 29
	s_lshl_b32 s39, s39, 14
	v_and_b32_e32 v127, 31, v200
	v_lshrrev_b32_e32 v128, 5, v200
	v_mul_u32_u24_e32 v128, 33, v128
	v_add_u32_e32 v128, v128, v127
	v_lshl_add_u32 v118, v128, 2, s39
	v_add_u32_e32 v119, 0x400, v118
	v_add_u32_e32 v120, 0x840, v118
	v_add_u32_e32 v121, 0xc40, v118
	v_add_u32_e32 v122, 0x1080, v118
	v_add_u32_e32 v123, 0x1480, v118
	v_add_u32_e32 v124, 0x18c0, v118
	v_add_u32_e32 v125, 0x1cc0, v118
	v_and_b32_e32 v127, 7, v200
	v_lshrrev_b32_e32 v128, 3, v200
	v_mul_u32_u24_e32 v129, 0x108, v127
	v_add_u32_e32 v129, v129, v128
	v_lshl_add_u32 v126, v129, 2, s39
	v_lshlrev_b32_e32 v127, 4, v127
	v_lshl_add_u32 v36, v128, 11, v127
	v_mov_b32_e32 v37, 0
	s_mov_b64 s[100:101], 0x4000
	v_lshl_add_u64 v[20:21], s[42:43], 0, v[36:37]
	v_lshl_add_u64 v[22:23], v[20:21], 0, s[100:101]
	v_lshl_add_u64 v[24:25], v[22:23], 0, s[100:101]
	v_lshl_add_u64 v[26:27], v[24:25], 0, s[100:101]
	s_waitcnt vmcnt(0)
	ds_write2_b32 v118, v38, v39 offset1:66
	ds_write2_b32 v118, v40, v41 offset0:132 offset1:198
	ds_write2_b32 v119, v42, v43 offset0:8 offset1:74
	ds_write2_b32 v119, v44, v45 offset0:140 offset1:206
	ds_write2_b32 v120, v46, v47 offset1:66
	ds_write2_b32 v120, v48, v49 offset0:132 offset1:198
	ds_write2_b32 v121, v50, v51 offset0:8 offset1:74
	ds_write2_b32 v121, v52, v53 offset0:140 offset1:206
	ds_write2_b32 v122, v54, v55 offset1:66
	ds_write2_b32 v122, v56, v57 offset0:132 offset1:198
	ds_write2_b32 v123, v58, v59 offset0:8 offset1:74
	ds_write2_b32 v123, v60, v61 offset0:140 offset1:206
	ds_write2_b32 v124, v62, v63 offset1:66
	ds_write2_b32 v124, v64, v65 offset0:132 offset1:198
	ds_write2_b32 v125, v66, v67 offset0:8 offset1:74
	ds_write2_b32 v125, v68, v69 offset0:140 offset1:206
	ds_read2_b32 v[70:71], v126 offset1:8
	ds_read2_b32 v[72:73], v126 offset0:33 offset1:41
	ds_read2_b32 v[74:75], v126 offset0:66 offset1:74
	ds_read2_b32 v[76:77], v126 offset0:99 offset1:107
	ds_read2_b32 v[78:79], v126 offset0:132 offset1:140
	ds_read2_b32 v[80:81], v126 offset0:165 offset1:173
	ds_read2_b32 v[82:83], v126 offset0:198 offset1:206
	ds_read2_b32 v[84:85], v126 offset0:231 offset1:239
	ds_read2_b32 v[86:87], v126 offset0:16 offset1:24
	ds_read2_b32 v[88:89], v126 offset0:49 offset1:57
	ds_read2_b32 v[90:91], v126 offset0:82 offset1:90
	ds_read2_b32 v[92:93], v126 offset0:115 offset1:123
	s_waitcnt lgkmcnt(4)
	v_cvt_pk_bf16_f32 v102, v70, v72
	v_cvt_pk_bf16_f32 v103, v74, v76
	v_cvt_pk_bf16_f32 v104, v78, v80
	v_cvt_pk_bf16_f32 v105, v82, v84
	v_cvt_pk_bf16_f32 v106, v71, v73
	v_cvt_pk_bf16_f32 v107, v75, v77
	v_cvt_pk_bf16_f32 v108, v79, v81
	v_cvt_pk_bf16_f32 v109, v83, v85
	ds_read2_b32 v[94:95], v126 offset0:148 offset1:156
	ds_read2_b32 v[96:97], v126 offset0:181 offset1:189
	ds_read2_b32 v[98:99], v126 offset0:214 offset1:222
	ds_read2_b32 v[100:101], v126 offset0:247 offset1:255
	global_store_dwordx4 v[20:21], v[102:105], off nt
	global_store_dwordx4 v[22:23], v[106:109], off nt
	s_waitcnt lgkmcnt(0)
	v_cvt_pk_bf16_f32 v110, v86, v88
	v_cvt_pk_bf16_f32 v111, v90, v92
	v_cvt_pk_bf16_f32 v112, v94, v96
	v_cvt_pk_bf16_f32 v113, v98, v100
	v_cvt_pk_bf16_f32 v114, v87, v89
	v_cvt_pk_bf16_f32 v115, v91, v93
	v_cvt_pk_bf16_f32 v116, v95, v97
	v_cvt_pk_bf16_f32 v117, v99, v101
	global_store_dwordx4 v[24:25], v[110:113], off nt
	global_store_dwordx4 v[26:27], v[114:117], off nt
.Lbw7_skip:
	s_waitcnt lgkmcnt(0)
	s_barrier
	v_readlane_b32 s38, v255, 61
	s_cmp_lg_u32 s38, 0

; #define WAVE_LDS_SYNC() do { int _z = 0; (void)emu::wave_xchg(&_z, 4); } while (0)
; #define LAS __attribute__((address_space(3)))
; #define WAVE_LDS_SYNC() asm volatile("s_waitcnt lgkmcnt(0)" ::: "memory")
; #define NT_LOAD(p) __builtin_nontemporal_load(p)
; #define NT_STORE(v, p) __builtin_nontemporal_store((v), (p))
; DEV unsigned pk2(float lo, float hi) { return f2bf(lo) | (f2bf(hi) << 16); }
; DEV unsigned pk2(float lo, float hi) { const f32x2n_t v = {lo, hi}; return __builtin_bit_cast(unsigned, __builtin_convertvector(v, bf16x2n_t)); }
; #define HROW(F, l, r) ((l) == 0 ? ((r) < LATR ? GIN(I_X) + (size_t)(r) * 1024 : GIN(I_CTX) + (size_t)((r) - LATR) * 1024) : (const float*)((F).ws + WS_H) + (size_t)(r) * 1024)
; DEV void tr_item(const float* W, int ldw, int col0, int k0, bf16_t* WT, int K, int row0, LAS float* scr, int lane) {
;     ...
;     for (int i = 0; i < 32; ++i) { const int kk = 2 * i + (lane >> 5); scr[kk * 33 + (lane & 31)] = NT_LOAD(&W[(size_t)(k0 + kk) * ldw + col0 + (lane & 31)]); }
;     WAVE_LDS_SYNC();
;     const int c = lane & 7;
; #pragma unroll
;     for (int j = 0; j < 4; ++j) { const int n = (lane >> 3) + 8 * j; const LAS float* s = scr + (8 * c) * 33 + n;
;         u32x4 o; o.x = pk2(s[0 * 33], s[1 * 33]); o.y = pk2(s[2 * 33], s[3 * 33]); o.z = pk2(s[4 * 33], s[5 * 33]); o.w = pk2(s[6 * 33], s[7 * 33]);
;         NT_STORE(o, (u32x4*)(WT + (size_t)(row0 + n) * K + k0 + 8 * c)); }
;     WAVE_LDS_SYNC();
; template <int RG> DEV void ln1_group(const Frame& F, int l, int r) {
;     const bf16_t* Y = (const bf16_t*)(F.ws + WS_Y); float* H = (float*)(F.ws + WS_H);
;     const float* lg = GIN(I_LN1G) + l * 1024; const float* lb = GIN(I_LN1B) + l * 1024; const float* wr = (const float*)(F.ws + WS_WR) + (size_t)l * NE * 1024;
;     {
;         int b, s; row_bs(r, b, s); const int mr = s < CTX ? B_ : b; const float* mod = (const float*)(F.ws + WS_MOD) + ((size_t)l * NR + mr) * 6144;
;         f32x4 t[RG][4];
; #pragma unroll
;         for (int j = 0; j < 4; ++j) { const f32x4 g1 = *((const f32x4*)(mod + 2048) + F.lane + 64 * j);
; #pragma unroll
;             for (int q = 0; q < RG; ++q) { const f32x4 hv = *((const f32x4*)HROW(F, l, r + q) + F.lane + 64 * j); const u32x2 yw = *((const u32x2*)(Y + (size_t)(r + q) * 1024) + F.lane + 64 * j); const f32x4 yv = (f32x4){bflo(yw.x), bfhi(yw.x), bflo(yw.y), bfhi(yw.y)}; t[q][j] = ALPHA * hv + g1 * yv; }
.LBB0_1377:
	s_or_b64 exec, exec, s[34:35]
	v_readlane_b32 s0, v252, 2
	s_mul_hi_u32 s0, s70, s0
	v_readlane_b32 s3, v252, 3
	s_mul_i32 s0, s0, s3
	s_sub_i32 s0, s70, s0
	s_sub_i32 s2, s0, s3
	s_cmp_ge_u32 s0, s3
	s_cselect_b32 s0, s2, s0
	s_sub_i32 s2, s0, s3
	s_cmp_ge_u32 s0, s3
	v_readlane_b32 s33, v251, 29
	v_readlane_b32 s4, v251, 0
	s_cselect_b32 s0, s2, s0
	s_waitcnt lgkmcnt(0)
	s_barrier
	s_cselect_b32 s38, 1, 0
	v_writelane_b32 v255, s38, 61
	s_nop 0
	v_readlane_b32 s40, v255, 60
	s_cmp_eq_u32 s40, 0
	s_cbranch_scc1 .Lbw8_skip
	s_lshr_b32 s41, s40, 16
	s_and_b32 s40, s40, 0xffff
	s_and_b32 s38, s40, 0x7ff
	s_lshr_b32 s39, s38, 7
	s_and_b32 s38, s38, 0x7f
	s_lshl_b32 s42, s38, 16
	s_lshl_b32 s39, s39, 7
	s_add_i32 s42, s42, s39
	s_lshr_b32 s39, s40, 11
	s_lshl_b32 s39, s39, 23
	s_add_i32 s42, s42, s39
	s_lshl_b32 s39, s41, 27
	s_add_u32 s42, s42, s39
	s_add_u32 s42, s42, 0x2bc8000
	v_readlane_b32 s100, v255, 53
	v_readlane_b32 s101, v255, 54
	s_add_u32 s42, s100, s42
	s_addc_u32 s43, s101, 0
	v_readlane_b32 s39, v251, 29
	s_lshl_b32 s39, s39, 14
	v_and_b32_e32 v127, 31, v200
	v_lshrrev_b32_e32 v128, 5, v200
	v_mul_u32_u24_e32 v128, 33, v128
	v_add_u32_e32 v128, v128, v127
	v_lshl_add_u32 v118, v128, 2, s39
	v_add_u32_e32 v119, 0x400, v118
	v_add_u32_e32 v120, 0x840, v118
	v_add_u32_e32 v121, 0xc40, v118
	v_add_u32_e32 v122, 0x1080, v118
	v_add_u32_e32 v123, 0x1480, v118
	v_add_u32_e32 v124, 0x18c0, v118
	v_add_u32_e32 v125, 0x1cc0, v118
	v_and_b32_e32 v127, 7, v200
	v_lshrrev_b32_e32 v128, 3, v200
	v_mul_u32_u24_e32 v129, 0x108, v127
	v_add_u32_e32 v129, v129, v128
	v_lshl_add_u32 v126, v129, 2, s39
	v_lshlrev_b32_e32 v127, 4, v127
	v_lshl_add_u32 v36, v128, 11, v127
	v_mov_b32_e32 v37, 0
	s_mov_b64 s[100:101], 0x4000
	v_lshl_add_u64 v[20:21], s[42:43], 0, v[36:37]
	v_lshl_add_u64 v[22:23], v[20:21], 0, s[100:101]
	v_lshl_add_u64 v[24:25], v[22:23], 0, s[100:101]
	v_lshl_add_u64 v[26:27], v[24:25], 0, s[100:101]
	s_waitcnt vmcnt(0)
	ds_write2_b32 v118, v38, v39 offset1:66
	ds_write2_b32 v118, v40, v41 offset0:132 offset1:198
	ds_write2_b32 v119, v42, v43 offset0:8 offset1:74
	ds_write2_b32 v119, v44, v45 offset0:140 offset1:206
	ds_write2_b32 v120, v46, v47 offset1:66
	ds_write2_b32 v120, v48, v49 offset0:132 offset1:198
	ds_write2_b32 v121, v50, v51 offset0:8 offset1:74
	ds_write2_b32 v121, v52, v53 offset0:140 offset1:206
	ds_write2_b32 v122, v54, v55 offset1:66
	ds_write2_b32 v122, v56, v57 offset0:132 offset1:198
	ds_write2_b32 v123, v58, v59 offset0:8 offset1:74
	ds_write2_b32 v123, v60, v61 offset0:140 offset1:206
	ds_write2_b32 v124, v62, v63 offset1:66
	ds_write2_b32 v124, v64, v65 offset0:132 offset1:198
	ds_write2_b32 v125, v66, v67 offset0:8 offset1:74
	ds_write2_b32 v125, v68, v69 offset0:140 offset1:206
	ds_read2_b32 v[70:71], v126 offset1:8
	ds_read2_b32 v[72:73], v126 offset0:33 offset1:41
	ds_read2_b32 v[74:75], v126 offset0:66 offset1:74
	ds_read2_b32 v[76:77], v126 offset0:99 offset1:107
	ds_read2_b32 v[78:79], v126 offset0:132 offset1:140
	ds_read2_b32 v[80:81], v126 offset0:165 offset1:173
	ds_read2_b32 v[82:83], v126 offset0:198 offset1:206
	ds_read2_b32 v[84:85], v126 offset0:231 offset1:239
	ds_read2_b32 v[86:87], v126 offset0:16 offset1:24
	ds_read2_b32 v[88:89], v126 offset0:49 offset1:57
	ds_read2_b32 v[90:91], v126 offset0:82 offset1:90
	ds_read2_b32 v[92:93], v126 offset0:115 offset1:123
	s_waitcnt lgkmcnt(4)
	v_cvt_pk_bf16_f32 v102, v70, v72
	v_cvt_pk_bf16_f32 v103, v74, v76
	v_cvt_pk_bf16_f32 v104, v78, v80
	v_cvt_pk_bf16_f32 v105, v82, v84
	v_cvt_pk_bf16_f32 v106, v71, v73
	v_cvt_pk_bf16_f32 v107, v75, v77
	v_cvt_pk_bf16_f32 v108, v79, v81
	v_cvt_pk_bf16_f32 v109, v83, v85
	ds_read2_b32 v[94:95], v126 offset0:148 offset1:156
	ds_read2_b32 v[96:97], v126 offset0:181 offset1:189
	ds_read2_b32 v[98:99], v126 offset0:214 offset1:222
	ds_read2_b32 v[100:101], v126 offset0:247 offset1:255
	global_store_dwordx4 v[20:21], v[102:105], off nt
	global_store_dwordx4 v[22:23], v[106:109], off nt
	s_waitcnt lgkmcnt(0)
	v_cvt_pk_bf16_f32 v110, v86, v88
	v_cvt_pk_bf16_f32 v111, v90, v92
	v_cvt_pk_bf16_f32 v112, v94, v96
	v_cvt_pk_bf16_f32 v113, v98, v100
	v_cvt_pk_bf16_f32 v114, v87, v89
	v_cvt_pk_bf16_f32 v115, v91, v93
	v_cvt_pk_bf16_f32 v116, v95, v97
	v_cvt_pk_bf16_f32 v117, v99, v101
	global_store_dwordx4 v[24:25], v[110:113], off nt
	global_store_dwordx4 v[26:27], v[114:117], off nt
.Lbw8_skip:
	s_waitcnt lgkmcnt(0)
	s_barrier
	v_readlane_b32 s38, v255, 61
	s_cmp_lg_u32 s38, 0
	v_mov_b32_e32 v78, v200
	v_readlane_b32 s5, v251, 1
	s_sub_i32 s71, s70, s0
	s_lshl_b32 s0, s33, 2
	v_readlane_b32 s2, v252, 4
	s_add_i32 s8, s0, s2
	v_ashrrev_i32_e32 v79, 31, v78
	v_readlane_b32 s4, v253, 62
	v_readlane_b32 s6, v251, 2
	v_readlane_b32 s7, v251, 3
	s_cmp_ge_i32 s8, s71
	v_cmp_gt_i32_e64 s[2:3], 16, v78
	s_mul_hi_u32 s57, s4, 5
	s_mul_i32 s48, s4, 5
	v_lshrrev_b32_e32 v128, 28, v79
	v_readlane_b32 s5, v253, 63
	s_cbranch_scc1 .LBB0_1458
	v_readlane_b32 s14, v253, 62
	s_add_u32 s10, s6, 0x32c98000
	v_readlane_b32 s15, v253, 63
	s_addc_u32 s11, s7, 0
	s_lshl_b32 s0, s14, 10
	s_lshl_b64 s[4:5], s[14:15], 16
	s_add_u32 s4, s6, s4
	s_addc_u32 s5, s7, s5
	s_add_u32 s44, s6, 0x10000
	v_lshl_add_u64 v[2:3], v[78:79], 3, s[6:7]
	s_mov_b64 s[16:17], 0x3c6a8800
	s_addc_u32 s45, s7, 0
	v_lshl_add_u64 v[80:81], v[2:3], 0, s[16:17]
	v_lshlrev_b64 v[82:83], 4, v[78:79]
	s_mov_b64 s[16:17], 0x37098000
	s_cmp_lg_u32 s14, 0
	v_lshl_add_u64 v[86:87], v[2:3], 0, s[16:17]
	v_lshl_add_u64 v[2:3], s[4:5], 0, v[82:83]
	s_mov_b64 s[4:5], 0x40cf0c00
	s_cselect_b64 s[12:13], -1, 0
	s_cmp_eq_u32 s14, 0
	v_lshl_add_u64 v[88:89], v[2:3], 0, s[4:5]
	v_lshl_add_u64 v[2:3], v[78:79], 2, s[6:7]
	s_mov_b64 s[4:5], 0x40aa8800
	s_cselect_b64 s[14:15], -1, 0
	v_lshl_add_u64 v[90:91], v[2:3], 0, s[4:5]
	s_lshl_b64 s[4:5], s[0:1], 2
	s_add_u32 s16, s76, s4
	s_addc_u32 s17, s77, s5
	v_add_u32_e32 v0, v78, v128
	s_add_u32 s4, s78, s4
	v_and_b32_e32 v0, -16, v0
	s_addc_u32 s5, s79, s5
	v_lshl_add_u64 v[84:85], s[10:11], 0, v[82:83]
	v_sub_u32_e32 v129, v78, v0
	v_lshl_add_u64 v[92:93], s[16:17], 0, v[82:83]
	v_lshl_add_u64 v[94:95], s[4:5], 0, v[82:83]
	s_branch .LBB0_1380

; #define WAVE_LDS_SYNC() do { int _z = 0; (void)emu::wave_xchg(&_z, 4); } while (0)
; #define LAS __attribute__((address_space(3)))
; #define WAVE_LDS_SYNC() asm volatile("s_waitcnt lgkmcnt(0)" ::: "memory")
; #define NT_LOAD(p) __builtin_nontemporal_load(p)
; #define NT_STORE(v, p) __builtin_nontemporal_store((v), (p))
; DEV unsigned pk2(float lo, float hi) { return f2bf(lo) | (f2bf(hi) << 16); }
; DEV unsigned pk2(float lo, float hi) { const f32x2n_t v = {lo, hi}; return __builtin_bit_cast(unsigned, __builtin_convertvector(v, bf16x2n_t)); }
; DEV void tr_item(const float* W, int ldw, int col0, int k0, bf16_t* WT, int K, int row0, LAS float* scr, int lane) {
;     ...
;     for (int i = 0; i < 32; ++i) { const int kk = 2 * i + (lane >> 5); scr[kk * 33 + (lane & 31)] = NT_LOAD(&W[(size_t)(k0 + kk) * ldw + col0 + (lane & 31)]); }
;     WAVE_LDS_SYNC();
;     const int c = lane & 7;
; #pragma unroll
;     for (int j = 0; j < 4; ++j) { const int n = (lane >> 3) + 8 * j; const LAS float* s = scr + (8 * c) * 33 + n;
;         u32x4 o; o.x = pk2(s[0 * 33], s[1 * 33]); o.y = pk2(s[2 * 33], s[3 * 33]); o.z = pk2(s[4 * 33], s[5 * 33]); o.w = pk2(s[6 * 33], s[7 * 33]);
;         NT_STORE(o, (u32x4*)(WT + (size_t)(row0 + n) * K + k0 + 8 * c)); }
;     WAVE_LDS_SYNC();
; DEV void phase_topk(const Frame& F0, int l) {
;     const Frame F = refresh(F0);
;     const int nitems = (l == DEPTH - 1) ? B_ * NE : 2 * B_ * NE;
;     LAS unsigned* hist = (LAS unsigned*)(F.lds);
;     LAS unsigned* selw = (LAS unsigned*)(F.lds + 1024);
;     LAS unsigned* cnt = (LAS unsigned*)(F.lds + 2048);
;     LAS int* selrow = (LAS int*)(F.lds + 8192);
;     const float* AFF = (const float*)(F.ws + WS_AFF); int* SLOT = (int*)(F.ws + WS_SLOT); float* EG = (float*)(F.ws + WS_EGATE);
;     for (int it = F.bid; it < nitems; it += F.G) {
;         const int e = it % NE, set = it / NE, kind = set / B_, b = set % B_;
;         const int n = kind ? CTX : SEQ, cap = kind ? CAPC : CAPL; const int row0 = kind ? LATR + b * CTX : b * SEQ;
;         const int sbase = kind ? B_ * CAPL + b * CAPC : b * CAPL;
;         const int per = n >= NTHREADS ? n / NTHREADS : 1; const bool act = F.tid * per < n;
.LBB0_1531:
	s_or_b64 exec, exec, s[34:35]
	v_readlane_b32 s2, v253, 51
	v_readlane_b32 s3, v253, 52
	v_readlane_b32 s4, v251, 0
	s_and_b64 s[2:3], s[2:3], exec
	v_writelane_b32 v254, s58, 8
	v_readlane_b32 s5, v251, 1
	v_readlane_b32 s6, v251, 2
	v_readlane_b32 s7, v251, 3
	s_cselect_b32 s0, 64, 0x80
	v_writelane_b32 v254, s59, 9
	v_readlane_b32 s18, v251, 29
	v_mov_b32_e32 v0, v200
	s_mov_b64 s[4:5], s[6:7]
	s_cmp_ge_i32 s95, s0
	v_writelane_b32 v254, s57, 2
	v_writelane_b32 v253, s48, 49
	s_waitcnt lgkmcnt(0)
	s_barrier
	s_cselect_b32 s38, 1, 0
	v_writelane_b32 v255, s38, 61
	s_nop 0
	v_readlane_b32 s40, v255, 60
	s_cmp_eq_u32 s40, 0
	s_cbranch_scc1 .Lbw9_skip
	s_lshr_b32 s41, s40, 16
	s_and_b32 s40, s40, 0xffff
	s_and_b32 s38, s40, 0x7ff
	s_lshr_b32 s39, s38, 7
	s_and_b32 s38, s38, 0x7f
	s_lshl_b32 s42, s38, 16
	s_lshl_b32 s39, s39, 7
	s_add_i32 s42, s42, s39
	s_lshr_b32 s39, s40, 11
	s_lshl_b32 s39, s39, 23
	s_add_i32 s42, s42, s39
	s_lshl_b32 s39, s41, 27
	s_add_u32 s42, s42, s39
	s_add_u32 s42, s42, 0x2bc8000
	v_readlane_b32 s100, v255, 53
	v_readlane_b32 s101, v255, 54
	s_add_u32 s42, s100, s42
	s_addc_u32 s43, s101, 0
	v_readlane_b32 s39, v251, 29
	s_lshl_b32 s39, s39, 14
	v_and_b32_e32 v127, 31, v200
	v_lshrrev_b32_e32 v128, 5, v200
	v_mul_u32_u24_e32 v128, 33, v128
	v_add_u32_e32 v128, v128, v127
	v_lshl_add_u32 v118, v128, 2, s39
	v_add_u32_e32 v119, 0x400, v118
	v_add_u32_e32 v120, 0x840, v118
	v_add_u32_e32 v121, 0xc40, v118
	v_add_u32_e32 v122, 0x1080, v118
	v_add_u32_e32 v123, 0x1480, v118
	v_add_u32_e32 v124, 0x18c0, v118
	v_add_u32_e32 v125, 0x1cc0, v118
	v_and_b32_e32 v127, 7, v200
	v_lshrrev_b32_e32 v128, 3, v200
	v_mul_u32_u24_e32 v129, 0x108, v127
	v_add_u32_e32 v129, v129, v128
	v_lshl_add_u32 v126, v129, 2, s39
	v_lshlrev_b32_e32 v127, 4, v127
	v_lshl_add_u32 v36, v128, 11, v127
	v_mov_b32_e32 v37, 0
	s_mov_b64 s[100:101], 0x4000
	v_lshl_add_u64 v[20:21], s[42:43], 0, v[36:37]
	v_lshl_add_u64 v[22:23], v[20:21], 0, s[100:101]
	v_lshl_add_u64 v[24:25], v[22:23], 0, s[100:101]
	v_lshl_add_u64 v[26:27], v[24:25], 0, s[100:101]
	s_waitcnt vmcnt(0)
	ds_write2_b32 v118, v38, v39 offset1:66
	ds_write2_b32 v118, v40, v41 offset0:132 offset1:198
	ds_write2_b32 v119, v42, v43 offset0:8 offset1:74
	ds_write2_b32 v119, v44, v45 offset0:140 offset1:206
	ds_write2_b32 v120, v46, v47 offset1:66
	ds_write2_b32 v120, v48, v49 offset0:132 offset1:198
	ds_write2_b32 v121, v50, v51 offset0:8 offset1:74
	ds_write2_b32 v121, v52, v53 offset0:140 offset1:206
	ds_write2_b32 v122, v54, v55 offset1:66
	ds_write2_b32 v122, v56, v57 offset0:132 offset1:198
	ds_write2_b32 v123, v58, v59 offset0:8 offset1:74
	ds_write2_b32 v123, v60, v61 offset0:140 offset1:206
	ds_write2_b32 v124, v62, v63 offset1:66
	ds_write2_b32 v124, v64, v65 offset0:132 offset1:198
	ds_write2_b32 v125, v66, v67 offset0:8 offset1:74
	ds_write2_b32 v125, v68, v69 offset0:140 offset1:206
	ds_read2_b32 v[70:71], v126 offset1:8
	ds_read2_b32 v[72:73], v126 offset0:33 offset1:41
	ds_read2_b32 v[74:75], v126 offset0:66 offset1:74
	ds_read2_b32 v[76:77], v126 offset0:99 offset1:107
	ds_read2_b32 v[78:79], v126 offset0:132 offset1:140
	ds_read2_b32 v[80:81], v126 offset0:165 offset1:173
	ds_read2_b32 v[82:83], v126 offset0:198 offset1:206
	ds_read2_b32 v[84:85], v126 offset0:231 offset1:239
	ds_read2_b32 v[86:87], v126 offset0:16 offset1:24
	ds_read2_b32 v[88:89], v126 offset0:49 offset1:57
	ds_read2_b32 v[90:91], v126 offset0:82 offset1:90
	ds_read2_b32 v[92:93], v126 offset0:115 offset1:123
	s_waitcnt lgkmcnt(4)
	v_cvt_pk_bf16_f32 v102, v70, v72
	v_cvt_pk_bf16_f32 v103, v74, v76
	v_cvt_pk_bf16_f32 v104, v78, v80
	v_cvt_pk_bf16_f32 v105, v82, v84
	v_cvt_pk_bf16_f32 v106, v71, v73
	v_cvt_pk_bf16_f32 v107, v75, v77
	v_cvt_pk_bf16_f32 v108, v79, v81
	v_cvt_pk_bf16_f32 v109, v83, v85
	ds_read2_b32 v[94:95], v126 offset0:148 offset1:156
	ds_read2_b32 v[96:97], v126 offset0:181 offset1:189
	ds_read2_b32 v[98:99], v126 offset0:214 offset1:222
	ds_read2_b32 v[100:101], v126 offset0:247 offset1:255
	global_store_dwordx4 v[20:21], v[102:105], off nt
	global_store_dwordx4 v[22:23], v[106:109], off nt
	s_waitcnt lgkmcnt(0)
	v_cvt_pk_bf16_f32 v110, v86, v88
	v_cvt_pk_bf16_f32 v111, v90, v92
	v_cvt_pk_bf16_f32 v112, v94, v96
	v_cvt_pk_bf16_f32 v113, v98, v100
	v_cvt_pk_bf16_f32 v114, v87, v89
	v_cvt_pk_bf16_f32 v115, v91, v93
	v_cvt_pk_bf16_f32 v116, v95, v97
	v_cvt_pk_bf16_f32 v117, v99, v101
	global_store_dwordx4 v[24:25], v[110:113], off nt
	global_store_dwordx4 v[26:27], v[114:117], off nt
; DEV void phase_topk(const Frame& F0, int l) {
;     ...
;         const int per = n >= NTHREADS ? n / NTHREADS : 1; const bool act = F.tid * per < n;
;         unsigned key[8];
; #pragma unroll
;         for (int k = 0; k < 8; ++k) key[k] = (act && k < per) ? __builtin_bit_cast(unsigned, AFF[(size_t)(row0 + F.tid * per + k) * 16 + e]) : 0u;
;         unsigned prefix = 0u, remaining = (unsigned)cap;
;         for (int pass = 0; pass < 4; ++pass) {
;             const int shift = 24 - 8 * pass; const unsigned mask = pass == 0 ? 0u : (0xFFFFFFFFu << (shift + 8));
;             if (F.tid < 256) hist[F.tid] = 0u;
;             __syncthreads();
; #pragma unroll
;             for (int k = 0; k < 8; ++k) if (act && k < per && ((key[k] & mask) == (prefix & mask))) lds_atomic_add(&hist[(key[k] >> shift) & 255u], 1u);
;             __syncthreads();
;             if (F.wave == 0) {
;                 const unsigned h0 = hist[4 * F.lane], h1 = hist[4 * F.lane + 1], h2 = hist[4 * F.lane + 2], h3 = hist[4 * F.lane + 3];
;                 unsigned suf = h0 + h1 + h2 + h3;
; #pragma unroll
;                 for (int o = 1; o < 64; o <<= 1) { const unsigned tv = shfl_t(suf, F.lane + o); if (F.lane + o < 64) suf += tv; }
;                 unsigned cum = suf - (h0 + h1 + h2 + h3);
;                 int dsel = -1; unsigned above = 0u;
;                 if (cum < remaining) {
;                     if (cum + h3 >= remaining) { dsel = 4 * F.lane + 3; above = cum; }
;                     else if (cum + h3 + h2 >= remaining) { dsel = 4 * F.lane + 2; above = cum + h3; }
;                     else if (cum + h3 + h2 + h1 >= remaining) { dsel = 4 * F.lane + 1; above = cum + h3 + h2; }
;                     else if (cum + h3 + h2 + h1 + h0 >= remaining) { dsel = 4 * F.lane; above = cum + h3 + h2 + h1; }
;                 }
;                 if (dsel >= 0) { selw[0] = prefix | ((unsigned)dsel << shift); selw[1] = remaining - above; }
;             }
;             __syncthreads();
;             prefix = selw[0]; remaining = selw[1];
;             __syncthreads();
;         }
;         const unsigned T = prefix, need_eq = remaining;
;         unsigned ngt = 0u, neq = 0u;
; #pragma unroll
;         for (int k = 0; k < 8; ++k) if (act && k < per) { ngt += key[k] > T ? 1u : 0u; neq += key[k] == T ? 1u : 0u; }
;         unsigned pk = (ngt << 16) | neq;
; #pragma unroll
.Lbw9_skip:
	s_waitcnt lgkmcnt(0)
	s_barrier
	v_readlane_b32 s38, v255, 61
	s_cmp_lg_u32 s38, 0
	s_cbranch_scc1 .LBB0_1705
	v_add_u32_e32 v2, 1, v0
	v_and_b32_e32 v3, 64, v200
	v_and_or_b32 v2, v2, 63, v3
	v_lshlrev_b32_e32 v20, 2, v2
	v_add_u32_e32 v2, 2, v0
	v_and_or_b32 v2, v2, 63, v3
	v_lshlrev_b32_e32 v21, 2, v2
	v_add_u32_e32 v2, 4, v0
	v_writelane_b32 v254, s71, 10
	v_writelane_b32 v253, s70, 53
	v_writelane_b32 v251, s64, 47
	v_and_or_b32 v2, v2, 63, v3
	v_lshlrev_b32_e32 v22, 2, v2
	v_writelane_b32 v251, s65, 48
	v_add_u32_e32 v2, 8, v0
	v_writelane_b32 v251, s66, 49
	v_and_or_b32 v2, v2, 63, v3
	v_writelane_b32 v251, s67, 50
	v_lshlrev_b32_e32 v23, 2, v2
	v_add_u32_e32 v2, 16, v0
	v_writelane_b32 v251, s68, 51
	v_and_or_b32 v2, v2, 63, v3
	v_writelane_b32 v251, s69, 52
	s_lshl_b32 s19, s18, 6
	v_lshlrev_b32_e32 v24, 2, v2
	v_and_or_b32 v2, v0, 63, v3
	v_writelane_b32 v251, s70, 53
	s_add_u32 s2, s4, 0x40aa8800
	v_lshlrev_b32_e32 v2, 2, v2
	v_writelane_b32 v251, s71, 54
	v_writelane_b32 v254, s2, 6
	s_addc_u32 s2, s5, 0
	v_xor_b32_e32 v25, 0x80, v2
	v_add_u32_e32 v2, -1, v0
	v_writelane_b32 v251, s72, 55
	v_writelane_b32 v254, s2, 13
	s_add_u32 s2, s4, 0x40bb8800
	v_and_or_b32 v2, v2, 63, v3
	v_writelane_b32 v251, s73, 56
	v_writelane_b32 v254, s2, 15
	s_addc_u32 s2, s5, 0
	v_lshlrev_b32_e32 v26, 2, v2
	v_add_u32_e32 v2, 62, v0
	v_writelane_b32 v251, s74, 57
	s_add_u32 s92, s4, 0x40cc8800
	v_and_or_b32 v2, v2, 63, v3
	v_writelane_b32 v251, s75, 58
	v_writelane_b32 v254, s2, 17
	s_addc_u32 s93, s5, 0
	v_cmp_eq_u32_e64 s[6:7], 63, v0
	v_lshlrev_b32_e32 v27, 2, v2
	v_add_u32_e32 v2, 60, v0
	v_writelane_b32 v251, s76, 59
	s_cmp_eq_u32 s18, 0
	v_writelane_b32 v254, s6, 19
	v_and_or_b32 v2, v2, 63, v3
	v_writelane_b32 v251, s77, 60
	s_cselect_b64 s[90:91], -1, 0
	v_writelane_b32 v254, s7, 20
	s_lshl_b32 s6, s18, 2
	v_lshlrev_b32_e32 v28, 2, v2
	v_add_u32_e32 v2, 56, v0
	v_writelane_b32 v251, s78, 61
	s_add_i32 s6, s6, 0
	v_and_or_b32 v2, v2, 63, v3
	v_writelane_b32 v251, s79, 62
	v_add_u32_e32 v6, s19, v0
	s_add_u32 s78, s4, 0x40d30c00
	v_lshlrev_b32_e32 v29, 2, v2
	v_add_u32_e32 v2, 48, v0
	s_addc_u32 s79, s5, 0
	v_add_u32_e32 v8, 0x880, v6
	v_and_or_b32 v2, v2, 63, v3
	s_movk_i32 s4, 0x7f
	v_lshlrev_b32_e32 v30, 2, v2
	s_cmp_gt_i32 s18, 0
	v_max_i32_e32 v2, 0x700, v8
	v_writelane_b32 v254, s6, 23
	v_cmp_lt_i32_e32 vcc, s4, v6
	v_cmp_lt_i32_e64 s[4:5], 0, v0
	s_cselect_b64 s[74:75], -1, 0
	s_cmp_gt_i32 s18, 1
	v_sub_u32_e32 v2, v2, v6
	v_writelane_b32 v254, s4, 21
	s_cselect_b64 s[96:97], -1, 0
	s_cmp_gt_i32 s18, 2
	v_add_u32_e32 v2, 0xfffff97f, v2
	v_writelane_b32 v254, s5, 22
	s_cselect_b64 s[88:89], -1, 0
	s_cmp_gt_i32 s18, 3
	v_lshrrev_b32_e32 v3, 9, v2
	s_movk_i32 s4, 0x1ff
	s_cselect_b64 s[70:71], -1, 0
	s_cmp_gt_i32 s18, 4
	v_add_u32_e32 v3, 1, v3
	v_cmp_lt_u32_e64 s[4:5], s4, v2
	s_cselect_b64 s[30:31], -1, 0
	s_cmp_gt_i32 s18, 5
	v_writelane_b32 v254, s4, 25
	v_and_b32_e32 v32, 0xfffffe, v3
	s_cselect_b64 s[80:81], -1, 0
	s_cmp_gt_i32 s18, 6
	v_writelane_b32 v254, s5, 26
	v_cmp_ne_u32_e64 s[4:5], v3, v32
	s_cselect_b64 s[72:73], -1, 0
	s_cmp_gt_i32 s18, 7
	v_writelane_b32 v254, s4, 11
	s_cselect_b64 s[76:77], -1, 0
	v_lshlrev_b32_e32 v15, 2, v0
	v_writelane_b32 v254, s5, 12
	s_lshl_b32 s4, s18, 8
	s_add_i32 s4, s4, 0
	v_lshl_add_u32 v16, v0, 4, 0
	v_cmp_gt_i32_e64 s[6:7], 63, v0
	v_cmp_gt_i32_e64 s[8:9], 62, v0
	v_cmp_gt_i32_e64 s[10:11], 60, v0
	v_cmp_gt_i32_e64 s[12:13], 56, v0
	v_cmp_gt_i32_e64 s[14:15], 48, v0
	v_cmp_gt_i32_e64 s[16:17], 32, v0
	v_cmp_gt_i32_e64 s[20:21], 2, v0
	v_cmp_gt_i32_e64 s[22:23], 4, v0
	v_cmp_gt_i32_e64 s[24:25], 8, v0
	v_cmp_gt_i32_e64 s[26:27], 16, v0
	v_not_b32_e32 v0, v0
	s_addk_i32 s4, 0x2000
	v_cmp_gt_i32_e64 s[2:3], s63, v6
	v_lshl_add_u32 v14, v6, 2, 0
	v_or_b32_e32 v17, 1, v15
	v_or_b32_e32 v18, 2, v15
	v_or_b32_e32 v19, 3, v15
	s_mov_b32 s33, s95
	v_subrev_u32_e32 v31, s19, v0
	v_add_u32_e32 v7, 0x200, v6
	v_lshl_add_u32 v33, v32, 9, v8
	v_add_u32_e32 v9, 0xa80, v6
	v_add_u32_e32 v34, s4, v15
	s_xor_b64 s[84:85], vcc, -1
	s_branch .LBB0_1534

; #define WAIT_VM(n) do {} while (0)
; #define WAIT_ALL() do {} while (0)
; #define LAUNDER_S(x) do {} while (0)
; #define WAIT_VM(n) asm volatile("s_waitcnt vmcnt(" #n ")" ::: "memory")
; #define WAIT_ALL() asm volatile("s_waitcnt vmcnt(0) lgkmcnt(0)" ::: "memory")
; #define LAUNDER_S(x) asm volatile("" : "+s"(x))
; DEV int lane_id() { return (int)__builtin_amdgcn_mbcnt_hi(~0u, __builtin_amdgcn_mbcnt_lo(~0u, 0u)); }
; DEV unsigned xb_add(unsigned* p, unsigned v) { return __hip_atomic_fetch_add(p, v, __ATOMIC_RELAXED, __HIP_MEMORY_SCOPE_AGENT); }
; DEV void xcd_barrier(const XcdBarrier& b) {
;     WAIT_VM(0);
;     __syncthreads();
;     int bw = b.wave; LAUNDER_S(bw);
;     if (bw == 0 && lane_id() == 0) {
;         unsigned* bar = b.bar; LAUNDER_S(bar);
;         unsigned bx = b.x; LAUNDER_S(bx);
;         WAIT_ALL();
;         unsigned nloc = b.st[0], nx = b.st[1];
;         if (nloc == 0u) { xcd_barrier_complete(bar, bx, nloc, nx); b.st[0] = nloc; b.st[1] = nx; }
;         const unsigned old = xb_add(&bar[XB_XSUB(bx)], 1u);
.Lbw10_none:
	v_writelane_b32 v255, s41, 60
	s_nop 0
	v_readlane_b32 s38, v255, 61
	s_cmp_lg_u32 s38, 0
	s_barrier
	s_nop 0
	v_or_b32_e32 v0, s0, v200
	v_cmp_eq_u32_e32 vcc, 0, v0
	s_and_saveexec_b64 s[34:35], vcc
	s_mov_b32 s63, 0x15000
	s_mov_b64 s[52:53], 0x1000
	s_cbranch_execz .LBB0_1749
	v_readlane_b32 s4, v251, 0
	v_readlane_b32 s6, v251, 2
	v_readlane_b32 s7, v251, 3
	s_mov_b64 s[36:37], s[6:7]
	v_readlane_b32 s0, v251, 28
	v_readlane_b32 s2, v253, 7
	s_waitcnt vmcnt(0) lgkmcnt(0)
	v_readlane_b32 s5, v251, 1
	s_nop 0
	v_mov_b32_e32 v0, s2
	ds_read_b32 v2, v0
	v_readlane_b32 s2, v253, 8
	s_waitcnt lgkmcnt(0)
	v_cmp_ne_u32_e32 vcc, 0, v2
	v_mov_b32_e32 v0, s2
	ds_read_b32 v0, v0
	s_cbranch_vccnz .LBB0_1720
	s_add_u32 s2, s36, 0x1000
	s_addc_u32 s3, s37, 0
	s_add_u32 s4, s36, 0x1100
	s_addc_u32 s5, s37, 0
	s_add_u32 s6, s36, 0x1200
	s_addc_u32 s7, s37, 0
	s_add_u32 s8, s36, 0x1300
	s_addc_u32 s9, s37, 0
	s_mov_b32 s28, 1
	s_mov_b64 s[10:11], 0
	s_branch .LBB0_1710

; #define WAVE_LDS_SYNC() do { int _z = 0; (void)emu::wave_xchg(&_z, 4); } while (0)
; #define LAS __attribute__((address_space(3)))
; #define WAVE_LDS_SYNC() asm volatile("s_waitcnt lgkmcnt(0)" ::: "memory")
; #define NT_LOAD(p) __builtin_nontemporal_load(p)
; #define NT_STORE(v, p) __builtin_nontemporal_store((v), (p))
; DEV unsigned pk2(float lo, float hi) { return f2bf(lo) | (f2bf(hi) << 16); }
; DEV unsigned pk2(float lo, float hi) { const f32x2n_t v = {lo, hi}; return __builtin_bit_cast(unsigned, __builtin_convertvector(v, bf16x2n_t)); }
; DEV void tr_item(const float* W, int ldw, int col0, int k0, bf16_t* WT, int K, int row0, LAS float* scr, int lane) {
;     ...
;     for (int i = 0; i < 32; ++i) { const int kk = 2 * i + (lane >> 5); scr[kk * 33 + (lane & 31)] = NT_LOAD(&W[(size_t)(k0 + kk) * ldw + col0 + (lane & 31)]); }
;     WAVE_LDS_SYNC();
;     const int c = lane & 7;
; #pragma unroll
;     for (int j = 0; j < 4; ++j) { const int n = (lane >> 3) + 8 * j; const LAS float* s = scr + (8 * c) * 33 + n;
;         u32x4 o; o.x = pk2(s[0 * 33], s[1 * 33]); o.y = pk2(s[2 * 33], s[3 * 33]); o.z = pk2(s[4 * 33], s[5 * 33]); o.w = pk2(s[6 * 33], s[7 * 33]);
;         NT_STORE(o, (u32x4*)(WT + (size_t)(row0 + n) * K + k0 + 8 * c)); }
;     WAVE_LDS_SYNC();
; DEV void gemm_g4(const Frame& F0, int l, int vcu) {
;     const Frame F = refresh(F0);
;     pg8::GatherOrder S; S.init((const void*)(F.ws + WS_XIN), (const bf16_t*)(F.ws + WS_WGU) + (size_t)l * NE * 2 * FF * 1024, 1024, 2 * FF, F.G, vcu, (l == DEPTH - 1) ? B_ * CAPL : EROWS); S.gidx = (const int*)(F.ws + WS_EIDX);
.LBB0_1749:
	s_or_b64 exec, exec, s[34:35]
	v_readlane_b32 s4, v251, 0
	v_readlane_b32 s5, v251, 1
	v_readlane_b32 s4, v253, 51
	v_readlane_b32 s5, v253, 52
	s_and_b64 s[4:5], s[4:5], exec
	s_cselect_b32 s33, 8, 9
	s_lshl_b32 s0, s33, 8
	v_readlane_b32 s3, v251, 29
	v_mov_b32_e32 v0, v200
	v_readlane_b32 s6, v251, 2
	v_readlane_b32 s7, v251, 3
	s_cmp_ge_i32 s95, s0
	s_mov_b64 s[66:67], s[54:55]
	s_waitcnt lgkmcnt(0)
	s_barrier
	s_cselect_b32 s38, 1, 0
	v_writelane_b32 v255, s38, 61
	s_nop 0
	v_readlane_b32 s40, v255, 60
	s_cmp_eq_u32 s40, 0
	s_cbranch_scc1 .Lbw10_skip
	s_lshr_b32 s41, s40, 16
	s_and_b32 s40, s40, 0xffff
	s_and_b32 s38, s40, 0x7ff
	s_lshr_b32 s39, s38, 7
	s_and_b32 s38, s38, 0x7f
	s_lshl_b32 s42, s38, 16
	s_lshl_b32 s39, s39, 7
	s_add_i32 s42, s42, s39
	s_lshr_b32 s39, s40, 11
	s_lshl_b32 s39, s39, 23
	s_add_i32 s42, s42, s39
	s_lshl_b32 s39, s41, 27
	s_add_u32 s42, s42, s39
	s_add_u32 s42, s42, 0x2bc8000
	v_readlane_b32 s100, v255, 53
	v_readlane_b32 s101, v255, 54
	s_add_u32 s42, s100, s42
	s_addc_u32 s43, s101, 0
	v_readlane_b32 s39, v251, 29
	s_lshl_b32 s39, s39, 14
	v_and_b32_e32 v127, 31, v200
	v_lshrrev_b32_e32 v128, 5, v200
	v_mul_u32_u24_e32 v128, 33, v128
	v_add_u32_e32 v128, v128, v127
	v_lshl_add_u32 v118, v128, 2, s39
	v_add_u32_e32 v119, 0x400, v118
	v_add_u32_e32 v120, 0x840, v118
	v_add_u32_e32 v121, 0xc40, v118
	v_add_u32_e32 v122, 0x1080, v118
	v_add_u32_e32 v123, 0x1480, v118
	v_add_u32_e32 v124, 0x18c0, v118
	v_add_u32_e32 v125, 0x1cc0, v118
	v_and_b32_e32 v127, 7, v200
	v_lshrrev_b32_e32 v128, 3, v200
	v_mul_u32_u24_e32 v129, 0x108, v127
	v_add_u32_e32 v129, v129, v128
	v_lshl_add_u32 v126, v129, 2, s39
	v_lshlrev_b32_e32 v127, 4, v127
	v_lshl_add_u32 v36, v128, 11, v127
	v_mov_b32_e32 v37, 0
	s_mov_b64 s[100:101], 0x4000
	v_lshl_add_u64 v[20:21], s[42:43], 0, v[36:37]
	v_lshl_add_u64 v[22:23], v[20:21], 0, s[100:101]
	v_lshl_add_u64 v[24:25], v[22:23], 0, s[100:101]
	v_lshl_add_u64 v[26:27], v[24:25], 0, s[100:101]
	s_waitcnt vmcnt(0)
	ds_write2_b32 v118, v38, v39 offset1:66
	ds_write2_b32 v118, v40, v41 offset0:132 offset1:198
	ds_write2_b32 v119, v42, v43 offset0:8 offset1:74
	ds_write2_b32 v119, v44, v45 offset0:140 offset1:206
	ds_write2_b32 v120, v46, v47 offset1:66
	ds_write2_b32 v120, v48, v49 offset0:132 offset1:198
	ds_write2_b32 v121, v50, v51 offset0:8 offset1:74
	ds_write2_b32 v121, v52, v53 offset0:140 offset1:206
	ds_write2_b32 v122, v54, v55 offset1:66
	ds_write2_b32 v122, v56, v57 offset0:132 offset1:198
	ds_write2_b32 v123, v58, v59 offset0:8 offset1:74
	ds_write2_b32 v123, v60, v61 offset0:140 offset1:206
	ds_write2_b32 v124, v62, v63 offset1:66
	ds_write2_b32 v124, v64, v65 offset0:132 offset1:198
	ds_write2_b32 v125, v66, v67 offset0:8 offset1:74
	ds_write2_b32 v125, v68, v69 offset0:140 offset1:206
	ds_read2_b32 v[70:71], v126 offset1:8
	ds_read2_b32 v[72:73], v126 offset0:33 offset1:41
	ds_read2_b32 v[74:75], v126 offset0:66 offset1:74
	ds_read2_b32 v[76:77], v126 offset0:99 offset1:107
	ds_read2_b32 v[78:79], v126 offset0:132 offset1:140
	ds_read2_b32 v[80:81], v126 offset0:165 offset1:173
	ds_read2_b32 v[82:83], v126 offset0:198 offset1:206
	ds_read2_b32 v[84:85], v126 offset0:231 offset1:239
	ds_read2_b32 v[86:87], v126 offset0:16 offset1:24
	ds_read2_b32 v[88:89], v126 offset0:49 offset1:57
	ds_read2_b32 v[90:91], v126 offset0:82 offset1:90
	ds_read2_b32 v[92:93], v126 offset0:115 offset1:123
	s_waitcnt lgkmcnt(4)
	v_cvt_pk_bf16_f32 v102, v70, v72
	v_cvt_pk_bf16_f32 v103, v74, v76
	v_cvt_pk_bf16_f32 v104, v78, v80
	v_cvt_pk_bf16_f32 v105, v82, v84
	v_cvt_pk_bf16_f32 v106, v71, v73
	v_cvt_pk_bf16_f32 v107, v75, v77
	v_cvt_pk_bf16_f32 v108, v79, v81
	v_cvt_pk_bf16_f32 v109, v83, v85
	ds_read2_b32 v[94:95], v126 offset0:148 offset1:156
	ds_read2_b32 v[96:97], v126 offset0:181 offset1:189
	ds_read2_b32 v[98:99], v126 offset0:214 offset1:222
	ds_read2_b32 v[100:101], v126 offset0:247 offset1:255
	global_store_dwordx4 v[20:21], v[102:105], off nt
	global_store_dwordx4 v[22:23], v[106:109], off nt
	s_waitcnt lgkmcnt(0)
	v_cvt_pk_bf16_f32 v110, v86, v88
	v_cvt_pk_bf16_f32 v111, v90, v92
	v_cvt_pk_bf16_f32 v112, v94, v96
	v_cvt_pk_bf16_f32 v113, v98, v100
	v_cvt_pk_bf16_f32 v114, v87, v89
	v_cvt_pk_bf16_f32 v115, v91, v93
	v_cvt_pk_bf16_f32 v116, v95, v97
	v_cvt_pk_bf16_f32 v117, v99, v101
	global_store_dwordx4 v[24:25], v[110:113], off nt
	global_store_dwordx4 v[26:27], v[114:117], off nt
; #define S_BARRIER() emu::block_barrier()
; #define WAIT_VM(n) do {} while (0)
; #define S_BARRIER() __builtin_amdgcn_s_barrier()
; #define WAIT_VM(n) asm volatile("s_waitcnt vmcnt(" #n ")" ::: "memory")
; #define PG8_STAGE(bufoff, gbase, voff) do { _Pragma("unroll") for (int _i = 0; _i < 2; ++_i) \
;         glds16(((const char*)(gbase) + (voff)[_i]), (lds + (bufoff) + ldsw + _i * 8192)); } while (0)
; template <class Epi, class Sched>
; DEV void gemm_phase(LAS unsigned char* lds, const int K, const Sched& S, const Epi& E, const int wid, const int lane) {
;     ...
; #pragma unroll
;     for (int i = 0; i < 2; ++i) { int R, C; stage_rc(tid * 16 + i * 8192, R, C); const int Rb = Epi::PERM ? ((R & ~31) + perm32(R & 31)) : R; Ri[i] = R; Ci[i] = C;
;         voffA[i] = (unsigned)(R * K + C) * 2u; voffB[i] = (unsigned)(Rb * K + C) * 2u; }
;     unsigned goffC[2][2] = {{0u, 0u}, {0u, 0u}}, goffN[2][2] = {{0u, 0u}, {0u, 0u}};
;     constexpr int GIDX_OFF = STAGE_BYTES;
;     const size_t kstep = (size_t)(BK * 2);
;     const size_t hstep = (size_t)HALF * K * 2;
;     const unsigned ldsw = (unsigned)wid * 1024u;
;     const int aoff = lds_byte(wr * 64 + fr, fq * 8), boff = lds_byte(wc * 32 + fr, fq * 8);
;     ...
;     Unit cur, nxt; int ui = 0;
;     if (!S.next(0, cur)) return;
;     f32x4 acc[2][2][4][2];
; #pragma unroll
;     for (int a = 0; a < 2; ++a)
; #pragma unroll
;         for (int b = 0; b < 2; ++b)
; #pragma unroll
;             for (int m = 0; m < 4; ++m)
; #pragma unroll
;                 for (int n = 0; n < 2; ++n) acc[a][b][m][n] = (f32x4){0.f, 0.f, 0.f, 0.f};
;     bf16x8 At[4][2], B0[2][2], B1[2][2];
;     const char* cA = cur.A; const char* cB = cur.B;
;     if constexpr (Sched::GATHER_A) {
; #pragma unroll
;         for (int hh = 0; hh < 2; ++hh)
; #pragma unroll
;             for (int i = 0; i < 2; ++i) { goffC[hh][i] = (unsigned)S.gidx[S.idx_base(cur) + hh * HALF + Ri[i]] * (unsigned)(K * 2) + (unsigned)(Ci[i] * 2); goffN[hh][i] = goffC[hh][i]; }
;     }
;     PG8_STAGE(PG8_SB(0, 0), cB, voffB); PG8_STAGE(PG8_SB(0, 1), cB + hstep, voffB); PG8_STAGEA(PG8_SA(0, 0), cA, 0, false); PG8_STAGEA(PG8_SA(0, 1), cA, 1, false);
;     if (wr == 1) S_BARRIER();
;     WAIT_VM(2); S_BARRIER();
;     PG8_STAGE(PG8_SB(1, 0), cB + kstep, voffB); PG8_STAGEA(PG8_SA(1, 0), cA + kstep, 0, false); PG8_STAGE(PG8_SB(1, 1), cB + hstep + kstep, voffB);
;     WAIT_VM(6); S_BARRIER();
.Lbw10_skip:
	s_waitcnt lgkmcnt(0)
	s_barrier
	v_readlane_b32 s38, v255, 61
	s_cmp_lg_u32 s38, 0
	s_cbranch_scc1 .LBB0_1769
	v_readlane_b32 s4, v253, 62
	s_add_u32 s8, s6, 0x37098000
	v_readlane_b32 s5, v253, 63
	s_addc_u32 s9, s7, 0
	s_lshl_b64 s[4:5], s[4:5], 27
	s_add_u32 s2, s6, s4
	s_addc_u32 s4, s7, s5
	s_add_u32 s38, s2, 0x2bc8000
	s_addc_u32 s39, s4, 0
	s_add_u32 s40, s6, 0x40d30c00
	s_addc_u32 s41, s7, 0
	s_lshl_b32 s42, s3, 10
	v_lshlrev_b32_e32 v130, 4, v0
	v_add_u32_e32 v3, s42, v130
	v_ashrrev_i32_e32 v2, 31, v3
	v_lshrrev_b32_e32 v2, 22, v2
	v_add_u32_e32 v2, v3, v2
	v_ashrrev_i32_e32 v4, 10, v2
	v_mul_i32_i24_e32 v2, 0x400, v4
	v_sub_u32_e32 v2, v3, v2
	v_lshrrev_b32_e32 v5, 4, v2
	v_bitop3_b32 v5, v5, v2, 32 bitop3:0x6c
	v_ashrrev_i32_e32 v6, 31, v5
	v_lshrrev_b32_e32 v6, 26, v6
	v_add_u32_e32 v6, v5, v6
	v_ashrrev_i32_e32 v7, 6, v6
	v_and_b32_e32 v6, 0xc0, v6
	v_sub_u32_e32 v5, v5, v6
	v_lshlrev_b32_e32 v2, 3, v4
	v_lshlrev_b32_e32 v4, 5, v4
	v_ashrrev_i16_sdwa v5, v202, sext(v5) dst_sel:DWORD dst_unused:UNUSED_PAD src0_sel:DWORD src1_sel:BYTE_0
	v_and_b32_e32 v4, 32, v4
	v_bfe_i32 v5, v5, 0, 16
	v_add_u32_e32 v3, 0x2000, v3
	v_add_lshl_u32 v147, v4, v5, 1
	v_ashrrev_i32_e32 v4, 31, v3
	v_lshrrev_b32_e32 v4, 22, v4
	v_add_u32_e32 v4, v3, v4
	v_ashrrev_i32_e32 v5, 10, v4
	v_mul_i32_i24_e32 v4, 0x400, v5
	v_sub_u32_e32 v3, v3, v4
	v_lshrrev_b32_e32 v4, 4, v3
	v_bitop3_b32 v3, v4, v3, 32 bitop3:0x6c
	v_ashrrev_i32_e32 v6, 31, v3
	v_lshrrev_b32_e32 v6, 26, v6
	v_add_u32_e32 v6, v3, v6
	v_ashrrev_i32_e32 v8, 6, v6
	v_and_b32_e32 v6, 0xffc0, v6
	v_sub_u32_e32 v3, v3, v6
	v_lshrrev_b16_e32 v6, 7, v3
	v_and_b32_e32 v6, 1, v6
	v_lshlrev_b32_e32 v4, 3, v5
	v_add_u16_e32 v3, v3, v6
	v_and_b32_e32 v4, -16, v4
	v_lshlrev_b32_e32 v5, 5, v5
	v_ashrrev_i16_sdwa v3, v202, sext(v3) dst_sel:DWORD dst_unused:UNUSED_PAD src0_sel:DWORD src1_sel:BYTE_0
	v_add_u32_e32 v4, v8, v4
	v_and_b32_e32 v5, 32, v5
	v_bfe_i32 v3, v3, 0, 16
	v_add_lshl_u32 v148, v5, v3, 1
	v_and_b32_e32 v3, 3, v8
	s_mov_b32 s2, 0x1fffe0
	v_lshrrev_b32_e32 v5, 2, v4
	v_lshlrev_b32_e32 v6, 1, v4
	v_and_b32_e32 v2, -16, v2
	v_and_or_b32 v3, v4, s2, v3
	v_and_b32_e32 v5, 4, v5
	v_and_b32_e32 v6, 24, v6
	s_lshl_b32 s43, s33, 5
	v_readlane_b32 s4, v252, 24
	s_ashr_i32 s14, s3, 2
	v_add_u32_e32 v2, v7, v2
	v_or3_b32 v3, v3, v5, v6
	s_or_b32 s44, s43, 1
	v_readlane_b32 s5, v252, 25
	v_lshl_add_u32 v132, v3, 11, v148
	v_and_b32_e32 v3, 3, v7
	v_lshrrev_b32_e32 v5, 2, v2
	v_lshlrev_b32_e32 v6, 1, v2
	s_and_b64 s[4:5], s[4:5], exec
	v_and_or_b32 v3, v2, s2, v3
	v_and_b32_e32 v5, 4, v5
	v_and_b32_e32 v6, 24, v6
	s_cselect_b32 s2, s44, s43
	s_lshl_b32 s45, s33, 4
	v_or3_b32 v3, v3, v5, v6
	s_abs_i32 s47, s45
	v_lshl_add_u32 v134, v3, 11, v147
	v_cvt_f32_u32_e32 v3, s47
	v_readlane_b32 s4, v252, 23
	s_sub_i32 s10, 0, s47
	s_mul_i32 s2, s2, s4
	v_rcp_iflag_f32_e32 v3, v3
	v_readlane_b32 s4, v252, 21
	s_add_i32 s2, s2, s4
	s_abs_i32 s5, s2
	v_mul_f32_e32 v3, 0x4f7ffffe, v3
	v_cvt_u32_f32_e32 v3, v3
	s_ashr_i32 s4, s2, 31
	s_bfe_i32 s46, s33, 0x1001b
	s_xor_b32 s4, s4, s46
	v_readfirstlane_b32 s48, v3
	s_mul_i32 s10, s10, s48
	s_mul_hi_u32 s10, s48, s10
	s_add_i32 s48, s48, s10
	s_mul_hi_u32 s10, s5, s48
	s_mul_i32 s11, s10, s47
	s_sub_i32 s5, s5, s11
	s_add_i32 s11, s10, 1
	s_sub_i32 s12, s5, s47
	s_cmp_ge_u32 s5, s47
	s_cselect_b32 s10, s11, s10
	s_cselect_b32 s5, s12, s5
	s_add_i32 s11, s10, 1
	s_cmp_ge_u32 s5, s47
	s_cselect_b32 s5, s11, s10
	s_xor_b32 s5, s5, s4
	s_sub_i32 s28, s5, s4
	s_mul_i32 s4, s28, s45
	s_sub_i32 s10, s2, s4
	s_sext_i32_i16 s2, s33
	v_cvt_f32_i32_e32 v5, s2
	v_cvt_f32_i32_e32 v3, s10
	s_xor_b32 s4, s10, s2
	s_ashr_i32 s4, s4, 30
	v_rcp_iflag_f32_e32 v6, v5
	s_or_b32 s11, s4, 1
	s_mul_i32 s15, s28, 0x2400
	v_mov_b32_e32 v135, v1
	v_mul_f32_e32 v6, v3, v6
	v_trunc_f32_e32 v6, v6
	v_fma_f32 v3, -v6, v5, v3
	v_cvt_i32_f32_e32 v6, v6
	v_cmp_ge_f32_e64 s[4:5], |v3|, |v5|
	s_and_b64 s[4:5], s[4:5], exec
	s_cselect_b32 s2, s11, 0
	v_readfirstlane_b32 s4, v6
	s_add_i32 s2, s4, s2
	s_mul_i32 s4, s2, s33
	s_ashr_i32 s29, s28, 31
	s_sub_i32 s12, s10, s4
	s_lshl_b64 s[4:5], s[28:29], 23
	s_add_u32 s10, s38, s4
	s_addc_u32 s11, s39, s5
	s_bfe_i64 s[4:5], s[2:3], 0x100000
	s_lshl_b64 s[4:5], s[4:5], 19
	s_add_u32 s4, s10, s4
	s_addc_u32 s5, s11, s5
	s_bfe_i64 s[10:11], s[12:13], 0x100000
	s_mul_hi_i32 s13, s28, 0x2400
	s_add_u32 s15, s40, s15
	s_addc_u32 s13, s41, s13
	s_lshl_b64 s[10:11], s[10:11], 10
	s_add_u32 s10, s15, s10
	s_addc_u32 s11, s13, s11
	v_ashrrev_i32_e32 v3, 31, v2
	v_lshl_add_u64 v[6:7], v[2:3], 2, s[10:11]
	global_load_dword v3, v[6:7], off
	v_ashrrev_i32_e32 v5, 31, v4
	v_lshl_add_u64 v[8:9], v[4:5], 2, s[10:11]
	s_add_i32 s29, s42, 0
	s_add_i32 m0, s29, 0x10000
	v_mov_b32_e32 v133, v1
	global_load_lds_dwordx4 v134, s[4:5]
	s_add_i32 m0, s29, 0x12000
	s_add_u32 s10, s4, 0x40000
	global_load_lds_dwordx4 v132, s[4:5]
	s_addc_u32 s11, s5, 0
	s_add_i32 m0, s29, 0x14000
	s_add_i32 s49, s29, 0x2000
	global_load_lds_dwordx4 v134, s[10:11]
	s_add_i32 m0, s29, 0x16000
	s_add_i32 s50, s29, 0x4000
	global_load_lds_dwordx4 v132, s[10:11]
	s_mov_b32 m0, s29
	s_add_i32 s51, s29, 0x6000
	s_cmp_eq_u32 s14, 1
	s_cselect_b64 s[10:11], -1, 0
	s_cmp_lg_u32 s14, 1
	s_waitcnt vmcnt(0)
	v_lshl_add_u32 v136, v3, 11, v147
	global_load_dword v3, v[8:9], off
	s_waitcnt vmcnt(0)
	v_lshl_add_u32 v138, v3, 11, v148
	global_load_dword v3, v[6:7], off offset:512
	v_lshl_add_u64 v[6:7], s[4:5], 0, v[134:135]
	global_load_lds_dwordx4 v136, s[8:9]
	s_mov_b32 m0, s49
	s_waitcnt vmcnt(0)
	v_lshl_add_u32 v140, v3, 11, v147
	global_load_dword v3, v[8:9], off offset:512
	v_lshl_add_u64 v[8:9], s[4:5], 0, v[132:133]
	global_load_lds_dwordx4 v138, s[8:9]
	s_mov_b32 m0, s50
	s_waitcnt vmcnt(0)
	v_lshl_add_u32 v142, v3, 11, v148
	global_load_lds_dwordx4 v140, s[8:9]
	s_mov_b32 m0, s51
	s_nop 0
	global_load_lds_dwordx4 v142, s[8:9]
	s_cbranch_scc1 .LBB0_1752
	s_barrier

; #define WAVE_LDS_SYNC() do { int _z = 0; (void)emu::wave_xchg(&_z, 4); } while (0)
; #define LAS __attribute__((address_space(3)))
; #define WAVE_LDS_SYNC() asm volatile("s_waitcnt lgkmcnt(0)" ::: "memory")
; #define NT_LOAD(p) __builtin_nontemporal_load(p)
; #define NT_STORE(v, p) __builtin_nontemporal_store((v), (p))
; DEV unsigned pk2(float lo, float hi) { return f2bf(lo) | (f2bf(hi) << 16); }
; DEV unsigned pk2(float lo, float hi) { const f32x2n_t v = {lo, hi}; return __builtin_bit_cast(unsigned, __builtin_convertvector(v, bf16x2n_t)); }
; DEV void tr_item(const float* W, int ldw, int col0, int k0, bf16_t* WT, int K, int row0, LAS float* scr, int lane) {
;     ...
;     for (int i = 0; i < 32; ++i) { const int kk = 2 * i + (lane >> 5); scr[kk * 33 + (lane & 31)] = NT_LOAD(&W[(size_t)(k0 + kk) * ldw + col0 + (lane & 31)]); }
;     WAVE_LDS_SYNC();
;     const int c = lane & 7;
; #pragma unroll
;     for (int j = 0; j < 4; ++j) { const int n = (lane >> 3) + 8 * j; const LAS float* s = scr + (8 * c) * 33 + n;
;         u32x4 o; o.x = pk2(s[0 * 33], s[1 * 33]); o.y = pk2(s[2 * 33], s[3 * 33]); o.z = pk2(s[4 * 33], s[5 * 33]); o.w = pk2(s[6 * 33], s[7 * 33]);
;         NT_STORE(o, (u32x4*)(WT + (size_t)(row0 + n) * K + k0 + 8 * c)); }
;     WAVE_LDS_SYNC();
.LBB0_1813:
	s_or_b64 exec, exec, s[34:35]
	v_readlane_b32 s4, v251, 0
	v_readlane_b32 s6, v251, 2
	v_readlane_b32 s7, v251, 3
	s_lshl_b32 s0, s33, 6
	v_readlane_b32 s10, v251, 29
	v_mov_b32_e32 v16, v200
	s_mov_b64 s[2:3], s[6:7]
	s_cmp_ge_i32 s95, s0
	s_waitcnt lgkmcnt(0)
	s_barrier
	s_cselect_b32 s38, 1, 0
	v_writelane_b32 v255, s38, 61
	s_nop 0
	v_readlane_b32 s40, v255, 60
	s_cmp_eq_u32 s40, 0
	s_cbranch_scc1 .Lbw11_skip
	s_lshr_b32 s41, s40, 16
	s_and_b32 s40, s40, 0xffff
	s_and_b32 s38, s40, 0x7ff
	s_lshr_b32 s39, s38, 7
	s_and_b32 s38, s38, 0x7f
	s_lshl_b32 s42, s38, 16
	s_lshl_b32 s39, s39, 7
	s_add_i32 s42, s42, s39
	s_lshr_b32 s39, s40, 11
	s_lshl_b32 s39, s39, 23
	s_add_i32 s42, s42, s39
	s_lshl_b32 s39, s41, 27
	s_add_u32 s42, s42, s39
	s_add_u32 s42, s42, 0x2bc8000
	v_readlane_b32 s100, v255, 53
	v_readlane_b32 s101, v255, 54
	s_add_u32 s42, s100, s42
	s_addc_u32 s43, s101, 0
	v_readlane_b32 s39, v251, 29
	s_lshl_b32 s39, s39, 14
	v_and_b32_e32 v127, 31, v200
	v_lshrrev_b32_e32 v128, 5, v200
	v_mul_u32_u24_e32 v128, 33, v128
	v_add_u32_e32 v128, v128, v127
	v_lshl_add_u32 v118, v128, 2, s39
	v_add_u32_e32 v119, 0x400, v118
	v_add_u32_e32 v120, 0x840, v118
	v_add_u32_e32 v121, 0xc40, v118
	v_add_u32_e32 v122, 0x1080, v118
	v_add_u32_e32 v123, 0x1480, v118
	v_add_u32_e32 v124, 0x18c0, v118
	v_add_u32_e32 v125, 0x1cc0, v118
	v_and_b32_e32 v127, 7, v200
	v_lshrrev_b32_e32 v128, 3, v200
	v_mul_u32_u24_e32 v129, 0x108, v127
	v_add_u32_e32 v129, v129, v128
	v_lshl_add_u32 v126, v129, 2, s39
	v_lshlrev_b32_e32 v127, 4, v127
	v_lshl_add_u32 v36, v128, 11, v127
	v_mov_b32_e32 v37, 0
	s_mov_b64 s[100:101], 0x4000
	v_lshl_add_u64 v[20:21], s[42:43], 0, v[36:37]
	v_lshl_add_u64 v[22:23], v[20:21], 0, s[100:101]
	v_lshl_add_u64 v[24:25], v[22:23], 0, s[100:101]
	v_lshl_add_u64 v[26:27], v[24:25], 0, s[100:101]
	s_waitcnt vmcnt(0)
	ds_write2_b32 v118, v38, v39 offset1:66
	ds_write2_b32 v118, v40, v41 offset0:132 offset1:198
	ds_write2_b32 v119, v42, v43 offset0:8 offset1:74
	ds_write2_b32 v119, v44, v45 offset0:140 offset1:206
	ds_write2_b32 v120, v46, v47 offset1:66
	ds_write2_b32 v120, v48, v49 offset0:132 offset1:198
	ds_write2_b32 v121, v50, v51 offset0:8 offset1:74
	ds_write2_b32 v121, v52, v53 offset0:140 offset1:206
	ds_write2_b32 v122, v54, v55 offset1:66
	ds_write2_b32 v122, v56, v57 offset0:132 offset1:198
	ds_write2_b32 v123, v58, v59 offset0:8 offset1:74
	ds_write2_b32 v123, v60, v61 offset0:140 offset1:206
	ds_write2_b32 v124, v62, v63 offset1:66
	ds_write2_b32 v124, v64, v65 offset0:132 offset1:198
	ds_write2_b32 v125, v66, v67 offset0:8 offset1:74
	ds_write2_b32 v125, v68, v69 offset0:140 offset1:206
	ds_read2_b32 v[70:71], v126 offset1:8
	ds_read2_b32 v[72:73], v126 offset0:33 offset1:41
	ds_read2_b32 v[74:75], v126 offset0:66 offset1:74
	ds_read2_b32 v[76:77], v126 offset0:99 offset1:107
	ds_read2_b32 v[78:79], v126 offset0:132 offset1:140
	ds_read2_b32 v[80:81], v126 offset0:165 offset1:173
	ds_read2_b32 v[82:83], v126 offset0:198 offset1:206
	ds_read2_b32 v[84:85], v126 offset0:231 offset1:239
	ds_read2_b32 v[86:87], v126 offset0:16 offset1:24
	ds_read2_b32 v[88:89], v126 offset0:49 offset1:57
	ds_read2_b32 v[90:91], v126 offset0:82 offset1:90
	ds_read2_b32 v[92:93], v126 offset0:115 offset1:123
	s_waitcnt lgkmcnt(4)
	v_cvt_pk_bf16_f32 v102, v70, v72
	v_cvt_pk_bf16_f32 v103, v74, v76
	v_cvt_pk_bf16_f32 v104, v78, v80
	v_cvt_pk_bf16_f32 v105, v82, v84
	v_cvt_pk_bf16_f32 v106, v71, v73
	v_cvt_pk_bf16_f32 v107, v75, v77
	v_cvt_pk_bf16_f32 v108, v79, v81
	v_cvt_pk_bf16_f32 v109, v83, v85
	ds_read2_b32 v[94:95], v126 offset0:148 offset1:156
	ds_read2_b32 v[96:97], v126 offset0:181 offset1:189
	ds_read2_b32 v[98:99], v126 offset0:214 offset1:222
	ds_read2_b32 v[100:101], v126 offset0:247 offset1:255
	global_store_dwordx4 v[20:21], v[102:105], off nt
	global_store_dwordx4 v[22:23], v[106:109], off nt
	s_waitcnt lgkmcnt(0)
	v_cvt_pk_bf16_f32 v110, v86, v88
	v_cvt_pk_bf16_f32 v111, v90, v92
	v_cvt_pk_bf16_f32 v112, v94, v96
	v_cvt_pk_bf16_f32 v113, v98, v100
	v_cvt_pk_bf16_f32 v114, v87, v89
	v_cvt_pk_bf16_f32 v115, v91, v93
	v_cvt_pk_bf16_f32 v116, v95, v97
	v_cvt_pk_bf16_f32 v117, v99, v101
	global_store_dwordx4 v[24:25], v[110:113], off nt
	global_store_dwordx4 v[26:27], v[114:117], off nt
; #define WAIT_VM(n) do {} while (0)
; template <class Epi, class Sched>
; DEV void gemm_phase(LAS unsigned char* lds, const int K, const Sched& S, const Epi& E, const int wid, const int lane) {
;     ...
; #pragma unroll
;     for (int i = 0; i < 2; ++i) { int R, C; stage_rc(tid * 16 + i * 8192, R, C); const int Rb = Epi::PERM ? ((R & ~31) + perm32(R & 31)) : R; Ri[i] = R; Ci[i] = C;
;         voffA[i] = (unsigned)(R * K + C) * 2u; voffB[i] = (unsigned)(Rb * K + C) * 2u; }
;     unsigned goffC[2][2] = {{0u, 0u}, {0u, 0u}}, goffN[2][2] = {{0u, 0u}, {0u, 0u}};
;     constexpr int GIDX_OFF = STAGE_BYTES;
;     const size_t kstep = (size_t)(BK * 2);
;     const size_t hstep = (size_t)HALF * K * 2;
;     const unsigned ldsw = (unsigned)wid * 1024u;
;     const int aoff = lds_byte(wr * 64 + fr, fq * 8), boff = lds_byte(wc * 32 + fr, fq * 8);
;     ...
;     Unit cur, nxt; int ui = 0;
;     if (!S.next(0, cur)) return;
;     f32x4 acc[2][2][4][2];
; #pragma unroll
;     for (int a = 0; a < 2; ++a)
; #pragma unroll
;         for (int b = 0; b < 2; ++b)
; #pragma unroll
;             for (int m = 0; m < 4; ++m)
; #pragma unroll
;                 for (int n = 0; n < 2; ++n) acc[a][b][m][n] = (f32x4){0.f, 0.f, 0.f, 0.f};
;     bf16x8 At[4][2], B0[2][2], B1[2][2];
;     const char* cA = cur.A; const char* cB = cur.B;
;     if constexpr (Sched::GATHER_A) {
; #pragma unroll
;         for (int hh = 0; hh < 2; ++hh)
; #pragma unroll
;             for (int i = 0; i < 2; ++i) { goffC[hh][i] = (unsigned)S.gidx[S.idx_base(cur) + hh * HALF + Ri[i]] * (unsigned)(K * 2) + (unsigned)(Ci[i] * 2); goffN[hh][i] = goffC[hh][i]; }
;     }
;     PG8_STAGE(PG8_SB(0, 0), cB, voffB); PG8_STAGE(PG8_SB(0, 1), cB + hstep, voffB); PG8_STAGEA(PG8_SA(0, 0), cA, 0, false); PG8_STAGEA(PG8_SA(0, 1), cA, 1, false);
;     if (wr == 1) S_BARRIER();
;     WAIT_VM(2); S_BARRIER();
;     PG8_STAGE(PG8_SB(1, 0), cB + kstep, voffB); PG8_STAGEA(PG8_SA(1, 0), cA + kstep, 0, false); PG8_STAGE(PG8_SB(1, 1), cB + hstep + kstep, voffB);
;     WAIT_VM(6); S_BARRIER();
; DEV void gemm_g5(const Frame& F0, int l, int vcu) {
;     const Frame F = refresh(F0);
;     pg8::GroupedOrder S; S.init((const void*)(F.ws + WS_HID), (const bf16_t*)(F.ws + WS_WD) + (size_t)l * NE * 1024 * FF, FF, 1024, F.G, vcu, (l == DEPTH - 1) ? B_ * CAPL : EROWS);
;     EpiYse E; E.O = (bf16_t*)(F.ws + WS_YSE); E.rowscale = (const float*)(F.ws + WS_EGATE);
.Lbw11_skip:
	s_waitcnt lgkmcnt(0)
	s_barrier
	v_readlane_b32 s38, v255, 61
	s_cmp_lg_u32 s38, 0
	v_readlane_b32 s5, v251, 1
	s_cbranch_scc1 .LBB0_1829
	v_readlane_b32 s4, v253, 62
	s_add_u32 s30, s2, 0x45dd4c00
	v_readlane_b32 s5, v253, 63
	s_addc_u32 s31, s3, 0
	s_lshl_b64 s[4:5], s[4:5], 26
	s_add_u32 s4, s2, s4
	s_addc_u32 s5, s3, s5
	s_add_u32 s34, s4, 0x22bc8000
	s_addc_u32 s35, s5, 0
	s_lshl_b32 s36, s10, 10
	v_lshl_add_u32 v0, v16, 4, s36
	v_add_u32_e32 v2, 0x2000, v0
	v_ashrrev_i32_e32 v3, 31, v2
	v_lshrrev_b32_e32 v3, 22, v3
	v_add_u32_e32 v3, v2, v3
	v_ashrrev_i32_e32 v10, 10, v3
	v_mul_i32_i24_e32 v3, 0x400, v10
	v_sub_u32_e32 v2, v2, v3
	v_lshrrev_b32_e32 v3, 4, v2
	v_bitop3_b32 v2, v3, v2, 32 bitop3:0x6c
	v_ashrrev_i32_e32 v3, 31, v2
	v_lshrrev_b32_e32 v3, 26, v3
	v_add_u32_e32 v3, v2, v3
	v_ashrrev_i32_e32 v11, 6, v3
	v_lshlrev_b32_e32 v4, 3, v10
	v_and_b32_e32 v3, 0xffc0, v3
	v_and_b32_e32 v4, -16, v4
	v_sub_u32_e32 v2, v2, v3
	v_add_u32_e32 v4, v11, v4
	v_lshrrev_b16_e32 v3, 7, v2
	v_and_b32_e32 v5, 3, v11
	s_mov_b32 s4, 0xfffe0
	v_lshrrev_b32_e32 v6, 2, v4
	v_lshlrev_b32_e32 v7, 1, v4
	v_and_b32_e32 v3, 1, v3
	v_and_or_b32 v5, v4, s4, v5
	v_and_b32_e32 v6, 4, v6
	v_and_b32_e32 v7, 24, v7
	v_add_u16_e32 v2, v2, v3
	v_or3_b32 v5, v5, v6, v7
	v_lshlrev_b32_e32 v6, 5, v10
	v_ashrrev_i16_sdwa v2, v202, sext(v2) dst_sel:DWORD dst_unused:UNUSED_PAD src0_sel:DWORD src1_sel:BYTE_0
	v_and_b32_e32 v6, 32, v6
	v_bfe_i32 v13, v2, 0, 16
	v_add_lshl_u32 v2, v6, v13, 1
	v_lshl_add_u32 v130, v5, 12, v2
	v_lshl_add_u32 v132, v4, 12, v2
	v_ashrrev_i32_e32 v2, 31, v0
	v_lshrrev_b32_e32 v2, 22, v2
	v_add_u32_e32 v2, v0, v2
	v_ashrrev_i32_e32 v12, 10, v2
	v_mul_i32_i24_e32 v2, 0x400, v12
	v_sub_u32_e32 v0, v0, v2
	v_lshrrev_b32_e32 v2, 4, v0
	v_bitop3_b32 v0, v2, v0, 32 bitop3:0x6c
	v_ashrrev_i32_e32 v2, 31, v0
	v_lshrrev_b32_e32 v2, 26, v2
	v_add_u32_e32 v2, v0, v2
	v_lshlrev_b32_e32 v3, 3, v12
	v_ashrrev_i32_e32 v14, 6, v2
	v_and_b32_e32 v3, -16, v3
	v_add_u32_e32 v3, v14, v3
	v_and_b32_e32 v4, 3, v14
	v_and_or_b32 v4, v3, s4, v4
	s_lshl_b32 s37, s33, 3
	v_readlane_b32 s4, v252, 24
	s_ashr_i32 s11, s10, 2
	v_lshrrev_b32_e32 v5, 2, v3
	v_lshlrev_b32_e32 v6, 1, v3
	v_and_b32_e32 v2, 0xc0, v2
	s_or_b32 s38, s37, 1
	v_readlane_b32 s5, v252, 25
	v_and_b32_e32 v5, 4, v5
	v_and_b32_e32 v6, 24, v6
	v_sub_u32_e32 v0, v0, v2
	s_and_b64 s[4:5], s[4:5], exec
	v_or3_b32 v4, v4, v5, v6
	v_lshlrev_b32_e32 v5, 5, v12
	v_ashrrev_i16_sdwa v0, v202, sext(v0) dst_sel:DWORD dst_unused:UNUSED_PAD src0_sel:DWORD src1_sel:BYTE_0
	s_cselect_b32 s4, s38, s37
	s_lshl_b32 s39, s33, 2
	v_and_b32_e32 v5, 32, v5
	v_bfe_i32 v15, v0, 0, 16
	s_abs_i32 s40, s39
	v_add_lshl_u32 v2, v5, v15, 1
	v_cvt_f32_u32_e32 v5, s40
	v_lshl_add_u32 v0, v4, 12, v2
	v_lshl_add_u32 v134, v3, 12, v2
	v_readlane_b32 s5, v252, 23
	v_rcp_iflag_f32_e32 v2, v5
	s_sub_i32 s7, 0, s40
	s_mul_i32 s4, s4, s5
	v_readlane_b32 s5, v252, 21
	v_mul_f32_e32 v2, 0x4f7ffffe, v2
	v_cvt_u32_f32_e32 v2, v2
	s_add_i32 s4, s4, s5
	s_abs_i32 s6, s4
	s_ashr_i32 s5, s4, 31
	v_readfirstlane_b32 s42, v2
	s_mul_i32 s7, s7, s42
	s_mul_hi_u32 s7, s42, s7
	s_add_i32 s42, s42, s7
	s_mul_hi_u32 s7, s6, s42
	s_mul_i32 s8, s7, s40
	s_bfe_i32 s41, s33, 0x1001d
	s_sub_i32 s6, s6, s8
	s_xor_b32 s5, s5, s41
	s_add_i32 s8, s7, 1
	s_sub_i32 s9, s6, s40
	s_cmp_ge_u32 s6, s40
	s_cselect_b32 s7, s8, s7
	s_cselect_b32 s6, s9, s6
	s_add_i32 s8, s7, 1
	s_cmp_ge_u32 s6, s40
	s_cselect_b32 s6, s8, s7
	s_xor_b32 s6, s6, s5
	s_sub_i32 s22, s6, s5
	s_sext_i32_i8 s5, s33
	v_cvt_f32_i32_e32 v2, s5
	s_mul_i32 s6, s22, s39
	s_sub_i32 s7, s4, s6
	v_cvt_f32_i32_e32 v3, s7
	v_rcp_iflag_f32_e32 v4, v2
	s_xor_b32 s4, s7, s5
	s_ashr_i32 s4, s4, 30
	s_or_b32 s6, s4, 1
	v_mul_f32_e32 v4, v3, v4
	v_trunc_f32_e32 v4, v4
	v_fma_f32 v3, -v4, v2, v3
	v_cvt_i32_f32_e32 v4, v4
	v_cmp_ge_f32_e64 s[4:5], |v3|, |v2|
	s_and_b64 s[4:5], s[4:5], exec
	s_cselect_b32 s4, s6, 0
	v_readfirstlane_b32 s5, v4
	s_add_i32 s6, s5, s4
	s_mul_i32 s4, s6, s33
	s_sub_i32 s8, s7, s4
	s_bfe_i64 s[4:5], s[8:9], 0x80000
	s_ashr_i32 s23, s22, 31
	s_lshl_b64 s[4:5], s[4:5], 20
	s_add_u32 s4, s30, s4
	s_mul_i32 s9, s22, 0x900000
	s_addc_u32 s5, s31, s5
	s_mul_hi_i32 s7, s22, 0x900000
	s_add_u32 s24, s4, s9
	s_addc_u32 s25, s5, s7
	s_lshl_b64 s[4:5], s[22:23], 22
	s_add_u32 s7, s34, s4
	s_addc_u32 s9, s35, s5
	s_bfe_i64 s[4:5], s[6:7], 0x80000
	s_lshl_b64 s[4:5], s[4:5], 20
	s_add_u32 s26, s7, s4
	s_addc_u32 s27, s9, s5
	s_add_i32 s43, s36, 0
	s_add_i32 m0, s43, 0x10000
	v_add_u32_e32 v136, 0x80000, v134
	global_load_lds_dwordx4 v0, s[26:27]
	s_add_i32 m0, s43, 0x12000
	s_add_u32 s4, s26, 0x80000
	global_load_lds_dwordx4 v130, s[26:27]
	s_addc_u32 s5, s27, 0
	s_add_i32 m0, s43, 0x14000
	s_add_i32 s44, s43, 0x2000
	global_load_lds_dwordx4 v0, s[4:5]
	s_add_i32 m0, s43, 0x16000
	s_add_i32 s45, s43, 0x4000
	global_load_lds_dwordx4 v130, s[4:5]
	s_mov_b32 m0, s43
	s_add_i32 s46, s43, 0x6000
	global_load_lds_dwordx4 v134, s[24:25]
	s_mov_b32 m0, s44
	v_add_u32_e32 v138, 0x80000, v132
	global_load_lds_dwordx4 v132, s[24:25]
	s_mov_b32 m0, s45
	v_mov_b32_e32 v131, v1
	global_load_lds_dwordx4 v136, s[24:25]
	s_mov_b32 m0, s46
	v_mov_b32_e32 v135, v1
	global_load_lds_dwordx4 v138, s[24:25]
	v_mov_b32_e32 v133, v1
	s_cmp_eq_u32 s11, 1
	v_lshl_add_u64 v[8:9], s[26:27], 0, v[0:1]
	v_lshl_add_u64 v[6:7], s[26:27], 0, v[130:131]
	v_lshl_add_u64 v[2:3], s[24:25], 0, v[134:135]
	s_cselect_b64 s[4:5], -1, 0
	s_cmp_lg_u32 s11, 1
	v_lshl_add_u64 v[4:5], s[24:25], 0, v[132:133]
	s_cbranch_scc1 .LBB0_1816
	s_barrier

; #define WAIT_VM(n) do {} while (0)
; #define LAUNDER_S(x) do {} while (0)
; #define WAIT_VM(n) asm volatile("s_waitcnt vmcnt(" #n ")" ::: "memory")
; #define LAUNDER_S(x) asm volatile("" : "+s"(x))
; DEV void xcd_barrier(const XcdBarrier& b) {
;     WAIT_VM(0);
;     __syncthreads();
;     int bw = b.wave; LAUNDER_S(bw);
; DEV void phase_prologue_a(const Frame& F0) {
;     ...
;         constexpr int GU_NB = 2 * FF / 32, GU_ITEMS = 16 * GU_NB;
;         for (int it = F.gw; it < NE * GU_ITEMS; it += F.NGW) { const int e = it / GU_ITEMS, r = it % GU_ITEMS, kb = r / GU_NB, nb = r % GU_NB; const int d0 = 32 * nb, j = d0 >> 8, w = d0 & 255;
;             const float* src = (w < 128 ? GIN(I_WGATE) : GIN(I_WUP)) + ((size_t)l * NE + e) * 1024 * FF;
;             tr_item(src, FF, 128 * j + (w & 127), 64 * kb, (bf16_t*)(F.ws + WS_WGU) + ((size_t)l * NE + e) * 2 * FF * 1024, 1024, d0, scr, F.lane); }
.Lsd_done:
.LBB0_1829:
	s_waitcnt vmcnt(0)
	v_readlane_b32 s0, v251, 29
	s_cselect_b32 s38, 1, 0
	v_writelane_b32 v255, s38, 61
	v_readlane_b32 s38, v255, 59
	s_add_i32 s39, s38, 1
	v_writelane_b32 v255, s39, 59
	s_mov_b32 s41, 0
	v_readlane_b32 s39, v251, 29
	s_cmp_eq_u32 s39, 0
	s_cbranch_scc1 .Lbw12_none
	v_readlane_b32 s40, v255, 51
	s_cmp_lg_u32 s40, 0x100
	s_cbranch_scc1 .Lbw12_none
	v_readlane_b32 s40, v255, 48
	s_mul_i32 s40, s40, 7
	s_mul_i32 s38, s38, 0x700
	s_add_i32 s40, s40, s38
	s_add_i32 s40, s40, s39
	s_add_i32 s40, s40, -1
	s_cmp_lt_u32 s40, 0x11f00
	s_cbranch_scc0 .Lbw12_none
	s_mov_b32 s41, 1
	s_cmp_lt_u32 s40, 0x8000
	s_cbranch_scc1 .Lbw12_have
	s_mov_b32 s41, 2
	s_sub_i32 s40, s40, 0x8000
	s_cmp_lt_u32 s40, 0x5200
	s_cbranch_scc1 .Lbw12_have
	s_mov_b32 s41, 3
	s_sub_i32 s40, s40, 0x5200

; #define WAVE_LDS_SYNC() do { int _z = 0; (void)emu::wave_xchg(&_z, 4); } while (0)
; #define LAS __attribute__((address_space(3)))
; #define WAVE_LDS_SYNC() asm volatile("s_waitcnt lgkmcnt(0)" ::: "memory")
; #define NT_LOAD(p) __builtin_nontemporal_load(p)
; #define NT_STORE(v, p) __builtin_nontemporal_store((v), (p))
; DEV unsigned pk2(float lo, float hi) { return f2bf(lo) | (f2bf(hi) << 16); }
; DEV unsigned pk2(float lo, float hi) { const f32x2n_t v = {lo, hi}; return __builtin_bit_cast(unsigned, __builtin_convertvector(v, bf16x2n_t)); }
; DEV void row_bs(int r, int& b, int& s) { if (r < LATR) { b = r / SEQ; s = CTX + r % SEQ; } else { const int q = r - LATR; b = q / CTX; s = q % CTX; } }
; DEV void tr_item(const float* W, int ldw, int col0, int k0, bf16_t* WT, int K, int row0, LAS float* scr, int lane) {
;     ...
;     for (int i = 0; i < 32; ++i) { const int kk = 2 * i + (lane >> 5); scr[kk * 33 + (lane & 31)] = NT_LOAD(&W[(size_t)(k0 + kk) * ldw + col0 + (lane & 31)]); }
;     WAVE_LDS_SYNC();
;     const int c = lane & 7;
; #pragma unroll
;     for (int j = 0; j < 4; ++j) { const int n = (lane >> 3) + 8 * j; const LAS float* s = scr + (8 * c) * 33 + n;
;         u32x4 o; o.x = pk2(s[0 * 33], s[1 * 33]); o.y = pk2(s[2 * 33], s[3 * 33]); o.z = pk2(s[4 * 33], s[5 * 33]); o.w = pk2(s[6 * 33], s[7 * 33]);
;         NT_STORE(o, (u32x4*)(WT + (size_t)(row0 + n) * K + k0 + 8 * c)); }
;     WAVE_LDS_SYNC();
; template <int RG> DEV void ln2_group(const Frame& F, int l, int r) {
;     float* H = (float*)(F.ws + WS_H); const int* SLOT = (const int*)(F.ws + WS_SLOT); const bf16_t* YSE = (const bf16_t*)(F.ws + WS_YSE);
;     const float* lg = GIN(I_LN2G) + l * 1024; const float* lb = GIN(I_LN2B) + l * 1024;
;     {
;         int b, s; row_bs(r, b, s); const int mr = s < CTX ? B_ : b; const float* mod = (const float*)(F.ws + WS_MOD) + ((size_t)l * NR + mr) * 6144;
;         f32x4 t[RG][4];
;         const int myslot = F.lane < RG * 16 ? SLOT[(size_t)r * 16 + F.lane] : -1;
;         f32x4 hv[RG][4], g2[4];
; #pragma unroll
;         for (int j = 0; j < 4; ++j) { g2[j] = *((const f32x4*)(mod + 5120) + F.lane + 64 * j);
; #pragma unroll
;             for (int q = 0; q < RG; ++q) hv[q][j] = *((const f32x4*)(H + (size_t)(r + q) * 1024) + F.lane + 64 * j); }
.LBB0_1873:
	s_or_b64 exec, exec, s[34:35]
	v_readlane_b32 s33, v251, 29
	s_waitcnt lgkmcnt(0)
	s_barrier
	s_cselect_b32 s38, 1, 0
	v_writelane_b32 v255, s38, 61
	s_nop 0
	v_readlane_b32 s40, v255, 60
	s_cmp_eq_u32 s40, 0
	s_cbranch_scc1 .Lbw12_skip
	s_lshr_b32 s41, s40, 16
	s_and_b32 s40, s40, 0xffff
	s_and_b32 s38, s40, 0x7ff
	s_lshr_b32 s39, s38, 7
	s_and_b32 s38, s38, 0x7f
	s_lshl_b32 s42, s38, 16
	s_lshl_b32 s39, s39, 7
	s_add_i32 s42, s42, s39
	s_lshr_b32 s39, s40, 11
	s_lshl_b32 s39, s39, 23
	s_add_i32 s42, s42, s39
	s_lshl_b32 s39, s41, 27
	s_add_u32 s42, s42, s39
	s_add_u32 s42, s42, 0x2bc8000
	v_readlane_b32 s100, v255, 53
	v_readlane_b32 s101, v255, 54
	s_add_u32 s42, s100, s42
	s_addc_u32 s43, s101, 0
	v_readlane_b32 s39, v251, 29
	s_lshl_b32 s39, s39, 14
	v_and_b32_e32 v127, 31, v200
	v_lshrrev_b32_e32 v128, 5, v200
	v_mul_u32_u24_e32 v128, 33, v128
	v_add_u32_e32 v128, v128, v127
	v_lshl_add_u32 v118, v128, 2, s39
	v_add_u32_e32 v119, 0x400, v118
	v_add_u32_e32 v120, 0x840, v118
	v_add_u32_e32 v121, 0xc40, v118
	v_add_u32_e32 v122, 0x1080, v118
	v_add_u32_e32 v123, 0x1480, v118
	v_add_u32_e32 v124, 0x18c0, v118
	v_add_u32_e32 v125, 0x1cc0, v118
	v_and_b32_e32 v127, 7, v200
	v_lshrrev_b32_e32 v128, 3, v200
	v_mul_u32_u24_e32 v129, 0x108, v127
	v_add_u32_e32 v129, v129, v128
	v_lshl_add_u32 v126, v129, 2, s39
	v_lshlrev_b32_e32 v127, 4, v127
	v_lshl_add_u32 v36, v128, 11, v127
	v_mov_b32_e32 v37, 0
	s_mov_b64 s[100:101], 0x4000
	v_lshl_add_u64 v[20:21], s[42:43], 0, v[36:37]
	v_lshl_add_u64 v[22:23], v[20:21], 0, s[100:101]
	v_lshl_add_u64 v[24:25], v[22:23], 0, s[100:101]
	v_lshl_add_u64 v[26:27], v[24:25], 0, s[100:101]
	s_waitcnt vmcnt(0)
	ds_write2_b32 v118, v38, v39 offset1:66
	ds_write2_b32 v118, v40, v41 offset0:132 offset1:198
	ds_write2_b32 v119, v42, v43 offset0:8 offset1:74
	ds_write2_b32 v119, v44, v45 offset0:140 offset1:206
	ds_write2_b32 v120, v46, v47 offset1:66
	ds_write2_b32 v120, v48, v49 offset0:132 offset1:198
	ds_write2_b32 v121, v50, v51 offset0:8 offset1:74
	ds_write2_b32 v121, v52, v53 offset0:140 offset1:206
	ds_write2_b32 v122, v54, v55 offset1:66
	ds_write2_b32 v122, v56, v57 offset0:132 offset1:198
	ds_write2_b32 v123, v58, v59 offset0:8 offset1:74
	ds_write2_b32 v123, v60, v61 offset0:140 offset1:206
	ds_write2_b32 v124, v62, v63 offset1:66
	ds_write2_b32 v124, v64, v65 offset0:132 offset1:198
	ds_write2_b32 v125, v66, v67 offset0:8 offset1:74
	ds_write2_b32 v125, v68, v69 offset0:140 offset1:206
	ds_read2_b32 v[70:71], v126 offset1:8
	ds_read2_b32 v[72:73], v126 offset0:33 offset1:41
	ds_read2_b32 v[74:75], v126 offset0:66 offset1:74
	ds_read2_b32 v[76:77], v126 offset0:99 offset1:107
	ds_read2_b32 v[78:79], v126 offset0:132 offset1:140
	ds_read2_b32 v[80:81], v126 offset0:165 offset1:173
	ds_read2_b32 v[82:83], v126 offset0:198 offset1:206
	ds_read2_b32 v[84:85], v126 offset0:231 offset1:239
	ds_read2_b32 v[86:87], v126 offset0:16 offset1:24
	ds_read2_b32 v[88:89], v126 offset0:49 offset1:57
	ds_read2_b32 v[90:91], v126 offset0:82 offset1:90
	ds_read2_b32 v[92:93], v126 offset0:115 offset1:123
	s_waitcnt lgkmcnt(4)
	v_cvt_pk_bf16_f32 v102, v70, v72
	v_cvt_pk_bf16_f32 v103, v74, v76
	v_cvt_pk_bf16_f32 v104, v78, v80
	v_cvt_pk_bf16_f32 v105, v82, v84
	v_cvt_pk_bf16_f32 v106, v71, v73
	v_cvt_pk_bf16_f32 v107, v75, v77
	v_cvt_pk_bf16_f32 v108, v79, v81
	v_cvt_pk_bf16_f32 v109, v83, v85
	ds_read2_b32 v[94:95], v126 offset0:148 offset1:156
	ds_read2_b32 v[96:97], v126 offset0:181 offset1:189
	ds_read2_b32 v[98:99], v126 offset0:214 offset1:222
	ds_read2_b32 v[100:101], v126 offset0:247 offset1:255
	global_store_dwordx4 v[20:21], v[102:105], off nt
	global_store_dwordx4 v[22:23], v[106:109], off nt
	s_waitcnt lgkmcnt(0)
	v_cvt_pk_bf16_f32 v110, v86, v88
	v_cvt_pk_bf16_f32 v111, v90, v92
	v_cvt_pk_bf16_f32 v112, v94, v96
	v_cvt_pk_bf16_f32 v113, v98, v100
	v_cvt_pk_bf16_f32 v114, v87, v89
	v_cvt_pk_bf16_f32 v115, v91, v93
	v_cvt_pk_bf16_f32 v116, v95, v97
	v_cvt_pk_bf16_f32 v117, v99, v101
	global_store_dwordx4 v[24:25], v[110:113], off nt
	global_store_dwordx4 v[26:27], v[114:117], off nt
.Lbw12_skip:
	s_waitcnt lgkmcnt(0)
	s_barrier
	v_readlane_b32 s38, v255, 61
	s_cmp_lg_u32 s38, 0
	s_lshl_b32 s0, s33, 2
	v_readlane_b32 s2, v252, 4
	v_mov_b32_e32 v82, v200
	v_readlane_b32 s4, v251, 0
	s_add_i32 s8, s0, s2
	v_readlane_b32 s6, v251, 2
	v_readlane_b32 s7, v251, 3
	s_cmp_ge_i32 s8, s71
	v_ashrrev_i32_e32 v83, 31, v82
	v_readlane_b32 s5, v251, 1
	s_cbranch_scc1 .LBB0_1910
	s_add_u32 s10, s6, 0x32c98000
	s_addc_u32 s11, s7, 0
	s_add_u32 s12, s6, 0x4edd4c00
	v_readlane_b32 s2, v253, 62
	s_addc_u32 s13, s7, 0
	s_lshl_b32 s0, s2, 10
	s_add_u32 s14, s6, 0x39298000
	v_lshl_add_u64 v[2:3], v[82:83], 2, s[6:7]
	s_mov_b64 s[4:5], 0x40bb8800
	s_addc_u32 s15, s7, 0
	v_readlane_b32 s16, v251, 0
	v_lshl_add_u64 v[86:87], v[2:3], 0, s[4:5]
	v_lshlrev_b64 v[2:3], 4, v[82:83]
	s_add_u32 s42, s6, 0x10000
	v_lshl_add_u64 v[4:5], v[82:83], 3, s[6:7]
	s_mov_b64 s[4:5], 0x37098000
	v_readlane_b32 s17, v251, 1
	v_readlane_b32 s18, v251, 2
	v_readlane_b32 s19, v251, 3
	s_addc_u32 s43, s7, 0
	s_add_i32 s44, s48, 5
	v_lshl_add_u64 v[90:91], v[4:5], 0, s[4:5]
	v_lshl_add_u64 v[92:93], s[16:17], 0, v[2:3]
	s_lshl_b64 s[4:5], s[0:1], 2
	v_readlane_b32 s16, v253, 26
	v_readlane_b32 s17, v253, 27
	s_add_u32 s16, s16, s4
	v_readlane_b32 s18, v253, 28
	s_addc_u32 s17, s17, s5
	v_readlane_b32 s3, v253, 63
	v_readlane_b32 s19, v253, 29
	s_add_u32 s18, s18, s4
	v_cmp_gt_i32_e64 s[2:3], 64, v82
	v_mov_b32_e32 v84, v82
	v_mov_b32_e32 v85, v1
	v_lshl_add_u64 v[88:89], s[10:11], 0, v[2:3]
	s_addc_u32 s19, s19, s5
	v_readlane_b32 s20, v253, 30
	v_readlane_b32 s21, v253, 31
	v_readlane_b32 s22, v253, 32
	v_readlane_b32 s23, v253, 33
	v_readlane_b32 s24, v253, 34
	v_readlane_b32 s25, v253, 35
	v_readlane_b32 s26, v253, 36
	v_readlane_b32 s27, v253, 37
	v_readlane_b32 s28, v253, 38
	v_readlane_b32 s29, v253, 39
	v_readlane_b32 s30, v253, 40
	v_readlane_b32 s31, v253, 41
	s_branch .LBB0_1876
